# adds: pipelined rstd sections in UP/Z/UQ/UKV epilogues (all partial-sum loads in flight, cross-lane finish), 4-deep residual epilogues, lean hand-written NSA selected/window tile loops (no packed-f32
# speedup vs baseline: 1.0326x; 1.0326x over previous
;     DI float* ssqh() const { return (float*)(ws + WS_SSQH); }
; DI float rstd_h(const float* ssqh, int row) {
;     const f32x4* p = (const f32x4*)(ssqh + (size_t)row * 16); float s = 0.f;
; #pragma unroll
;     for (int i = 0; i < 4; ++i) { f32x4 v = p[i]; s += (v[0] + v[1]) + (v[2] + v[3]); }
;     return rsqrtf(s * (1.f / 1024.f) + EPS);
; }
;     __device__ __forceinline__ void operator()(f32x4 (&acc)[2][2][4][2], const Unit& u, int wr, int wc, int fr_in, int fq_in) const {
;     ...
;         const int b = STRIDE == 254 ? u.pm / 17 : u.pm / 16, tl0 = STRIDE == 254 ? 254 * (u.pm % 17) - 2 : 256 * (u.pm % 16), wid = wr * 4 + wc;
; #pragma unroll
;         for (int ai = 0; ai < 2; ++ai)
; #pragma unroll
;             for (int m = 0; m < 4; ++m) {
;                 const int tl = tl0 + ai * HALF + wr * 64 + m * 16 + fr; float sc = 0.f;
;                 if (tl >= 0 && tl < 4096) sc = ::rstd_h(ssqh, b * 4096 + tl);
.LBB0_47:
	s_mul_hi_i32 s8, s22, 0x78787879
	s_lshr_b32 s9, s8, 31
	s_ashr_i32 s8, s8, 3
	s_add_i32 s8, s8, s9
	s_mul_i32 s9, s8, 17
	s_sub_i32 s9, s22, s9
	v_mov_b32_e32 v163, v184
	v_mov_b32_e32 v162, v233
	s_mul_i32 s23, s9, 0xfe
	v_readlane_b32 s9, v254, 55
	s_add_i32 s23, s23, -2
	s_lshl_b32 s22, s8, 12
	v_add_u32_e32 v199, s9, v162
	v_add_u32_e32 v205, s23, v199
	v_and_b32_e32 v212, 48, v221
	v_xor_b32_e32 v213, 16, v221
	v_lshlrev_b32_e32 v213, 2, v213
	s_movk_i32 s8, 0xfff
	v_mov_b32_e32 v150, v205
	v_min_u32_e32 v209, s8, v150
	v_or_b32_e32 v209, s22, v209
	v_lshl_add_u32 v209, v209, 6, v212
	global_load_dwordx4 v[134:137], v209, s[48:49]
	v_add_u32_e32 v151, 0x10, v205
	v_min_u32_e32 v209, s8, v151
	v_or_b32_e32 v209, s22, v209
	v_lshl_add_u32 v209, v209, 6, v212
	global_load_dwordx4 v[138:141], v209, s[48:49]
	v_add_u32_e32 v152, 0x20, v205
	v_min_u32_e32 v209, s8, v152
	v_or_b32_e32 v209, s22, v209
	v_lshl_add_u32 v209, v209, 6, v212
	global_load_dwordx4 v[142:145], v209, s[48:49]
	v_add_u32_e32 v153, 0x30, v205
	v_min_u32_e32 v209, s8, v153
	v_or_b32_e32 v209, s22, v209
	v_lshl_add_u32 v209, v209, 6, v212
	global_load_dwordx4 v[146:149], v209, s[48:49]
	v_add_u32_e32 v158, 0x80, v205
	v_min_u32_e32 v209, s8, v158
	v_or_b32_e32 v209, s22, v209
	v_lshl_add_u32 v209, v209, 6, v212
	global_load_dwordx4 v[164:167], v209, s[48:49]
	v_add_u32_e32 v159, 0x90, v205
	v_min_u32_e32 v209, s8, v159
	v_or_b32_e32 v209, s22, v209
	v_lshl_add_u32 v209, v209, 6, v212
	global_load_dwordx4 v[236:239], v209, s[48:49]
	v_add_u32_e32 v160, 0xa0, v205
	v_min_u32_e32 v209, s8, v160
	v_or_b32_e32 v209, s22, v209
	v_lshl_add_u32 v209, v209, 6, v212
	global_load_dwordx4 v[240:243], v209, s[48:49]
	v_add_u32_e32 v161, 0xb0, v205
	v_min_u32_e32 v209, s8, v161
	v_or_b32_e32 v209, s22, v209
	v_lshl_add_u32 v209, v209, 6, v212
	global_load_dwordx4 v[244:247], v209, s[48:49]
	s_waitcnt vmcnt(0)
	v_add_f32_e32 v168, v134, v135
	v_add_f32_e32 v248, v136, v137
	v_add_f32_e32 v169, v138, v139
	v_add_f32_e32 v249, v140, v141
	v_add_f32_e32 v170, v142, v143
	v_add_f32_e32 v250, v144, v145
	v_add_f32_e32 v176, v146, v147
	v_add_f32_e32 v251, v148, v149
	v_add_f32_e32 v177, v164, v165
	v_add_f32_e32 v203, v166, v167
	v_add_f32_e32 v196, v236, v237
	v_add_f32_e32 v207, v238, v239
	v_add_f32_e32 v197, v240, v241
	v_add_f32_e32 v210, v242, v243
	v_add_f32_e32 v201, v244, v245
	v_add_f32_e32 v211, v246, v247
	v_add_f32_e32 v168, v168, v248
	v_add_f32_e32 v169, v169, v249
	v_add_f32_e32 v170, v170, v250
	v_add_f32_e32 v176, v176, v251
	v_add_f32_e32 v177, v177, v203
	v_add_f32_e32 v196, v196, v207
	v_add_f32_e32 v197, v197, v210
	v_add_f32_e32 v201, v201, v211
	ds_bpermute_b32 v248, v213, v168
	ds_bpermute_b32 v249, v213, v169
	ds_bpermute_b32 v250, v213, v170
	ds_bpermute_b32 v251, v213, v176
	ds_bpermute_b32 v203, v213, v177
	ds_bpermute_b32 v207, v213, v196
	ds_bpermute_b32 v210, v213, v197
	ds_bpermute_b32 v211, v213, v201
	s_waitcnt lgkmcnt(0)
; #define PG8_LAS __attribute__((address_space(3)))
;     DI float* ssqh() const { return (float*)(ws + WS_SSQH); }
;     __device__ __forceinline__ void operator()(f32x4 (&acc)[2][2][4][2], const Unit& u, int wr, int wc, int fr_in, int fq_in) const {
;     ...
;                 const int tl = tl0 + ai * HALF + wr * 64 + m * 16 + fr; float sc = 0.f;
;                 if (tl >= 0 && tl < 4096) sc = ::rstd_h(ssqh, b * 4096 + tl);
; #pragma unroll
;                 for (int bj = 0; bj < 2; ++bj)
; #pragma unroll
;                     for (int n = 0; n < 2; ++n) acc[ai][bj][m][n] *= sc;
;             }
;         if (fr >= 14) {
; #pragma unroll
;             for (int ai = 0; ai < 2; ++ai)
; #pragma unroll
;                 for (int bj = 0; bj < 2; ++bj)
; #pragma unroll
;                     for (int n = 0; n < 2; ++n) *(PG8_LAS f32x4*)(xch + ((((wid * 2 + ai) * 4 + fq) * 2 + (fr - 14)) * 4 + bj * 2 + n) * 4) = acc[ai][bj][3][n];
;         }
	v_add_f32_e32 v168, v168, v248
	v_add_f32_e32 v169, v169, v249
	v_add_f32_e32 v170, v170, v250
	v_add_f32_e32 v176, v176, v251
	v_add_f32_e32 v177, v177, v203
	v_add_f32_e32 v196, v196, v207
	v_add_f32_e32 v197, v197, v210
	v_add_f32_e32 v201, v201, v211
	v_mov_b32_e32 v248, v168
	v_mov_b32_e32 v249, v169
	v_mov_b32_e32 v250, v170
	v_mov_b32_e32 v251, v176
	v_mov_b32_e32 v203, v177
	v_mov_b32_e32 v207, v196
	v_mov_b32_e32 v210, v197
	v_mov_b32_e32 v211, v201
	s_nop 1
	v_permlane32_swap_b32_e32 v248, v168
	v_permlane32_swap_b32_e32 v249, v169
	v_permlane32_swap_b32_e32 v250, v170
	v_permlane32_swap_b32_e32 v251, v176
	v_permlane32_swap_b32_e32 v203, v177
	v_permlane32_swap_b32_e32 v207, v196
	v_permlane32_swap_b32_e32 v210, v197
	v_permlane32_swap_b32_e32 v211, v201
	v_add_f32_e32 v168, v168, v248
	v_add_f32_e32 v169, v169, v249
	v_add_f32_e32 v170, v170, v250
	v_add_f32_e32 v176, v176, v251
	v_add_f32_e32 v177, v177, v203
	v_add_f32_e32 v196, v196, v207
	v_add_f32_e32 v197, v197, v210
	v_add_f32_e32 v201, v201, v211
	s_mov_b32 s16, 0x800000
	s_movk_i32 s8, 0x1000
	v_fmamk_f32 v168, v168, 0x3a800000, v215
	v_cmp_gt_f32_e32 vcc, s16, v168
	v_mul_f32_e32 v248, 0x4b800000, v168
	s_nop 0
	v_cndmask_b32_e32 v168, v168, v248, vcc
	v_rsq_f32_e32 v168, v168
	s_nop 0
	v_mul_f32_e32 v248, 0x45800000, v168
	v_cndmask_b32_e32 v168, v168, v248, vcc
	v_cmp_gt_u32_e32 vcc, s8, v150
	s_nop 1
	v_cndmask_b32_e32 v208, 0, v168, vcc
	v_fmamk_f32 v169, v169, 0x3a800000, v215
	v_cmp_gt_f32_e32 vcc, s16, v169
	v_mul_f32_e32 v249, 0x4b800000, v169
	s_nop 0
	v_cndmask_b32_e32 v169, v169, v249, vcc
	v_rsq_f32_e32 v169, v169
	s_nop 0
	v_mul_f32_e32 v249, 0x45800000, v169
	v_cndmask_b32_e32 v169, v169, v249, vcc
	v_cmp_gt_u32_e32 vcc, s8, v151
	s_nop 1
	v_cndmask_b32_e32 v204, 0, v169, vcc
	v_fmamk_f32 v170, v170, 0x3a800000, v215
	v_cmp_gt_f32_e32 vcc, s16, v170
	v_mul_f32_e32 v250, 0x4b800000, v170
	s_nop 0
	v_cndmask_b32_e32 v170, v170, v250, vcc
	v_rsq_f32_e32 v170, v170
	s_nop 0
	v_mul_f32_e32 v250, 0x45800000, v170
	v_cndmask_b32_e32 v170, v170, v250, vcc
	v_cmp_gt_u32_e32 vcc, s8, v152
	s_nop 1
	v_cndmask_b32_e32 v206, 0, v170, vcc
	v_fmamk_f32 v176, v176, 0x3a800000, v215
	v_cmp_gt_f32_e32 vcc, s16, v176
	v_mul_f32_e32 v251, 0x4b800000, v176
	s_nop 0
	v_cndmask_b32_e32 v176, v176, v251, vcc
	v_rsq_f32_e32 v176, v176
	s_nop 0
	v_mul_f32_e32 v251, 0x45800000, v176
	v_cndmask_b32_e32 v176, v176, v251, vcc
	v_cmp_gt_u32_e32 vcc, s8, v153
	s_nop 1
	v_cndmask_b32_e32 v130, 0, v176, vcc
	v_fmamk_f32 v177, v177, 0x3a800000, v215
	v_cmp_gt_f32_e32 vcc, s16, v177
	v_mul_f32_e32 v203, 0x4b800000, v177
	s_nop 0
	v_cndmask_b32_e32 v177, v177, v203, vcc
	v_rsq_f32_e32 v177, v177
	s_nop 0
	v_mul_f32_e32 v203, 0x45800000, v177
	v_cndmask_b32_e32 v177, v177, v203, vcc
	v_cmp_gt_u32_e32 vcc, s8, v158
	s_nop 1
	v_cndmask_b32_e32 v202, 0, v177, vcc
	v_fmamk_f32 v196, v196, 0x3a800000, v215
	v_cmp_gt_f32_e32 vcc, s16, v196
	v_mul_f32_e32 v207, 0x4b800000, v196
	s_nop 0
	v_cndmask_b32_e32 v196, v196, v207, vcc
	v_rsq_f32_e32 v196, v196
	s_nop 0
	v_mul_f32_e32 v207, 0x45800000, v196
	v_cndmask_b32_e32 v196, v196, v207, vcc
	v_cmp_gt_u32_e32 vcc, s8, v159
	s_nop 1
	v_cndmask_b32_e32 v198, 0, v196, vcc
	v_fmamk_f32 v197, v197, 0x3a800000, v215
	v_cmp_gt_f32_e32 vcc, s16, v197
	v_mul_f32_e32 v210, 0x4b800000, v197
	s_nop 0
	v_cndmask_b32_e32 v197, v197, v210, vcc
	v_rsq_f32_e32 v197, v197
	s_nop 0
	v_mul_f32_e32 v210, 0x45800000, v197
	v_cndmask_b32_e32 v197, v197, v210, vcc
	v_cmp_gt_u32_e32 vcc, s8, v160
	s_nop 1
	v_cndmask_b32_e32 v200, 0, v197, vcc
	v_fmamk_f32 v201, v201, 0x3a800000, v215
	v_cmp_gt_f32_e32 vcc, s16, v201
	v_mul_f32_e32 v211, 0x4b800000, v201
	s_nop 0
	v_cndmask_b32_e32 v201, v201, v211, vcc
	v_rsq_f32_e32 v201, v201
	s_nop 0
	v_mul_f32_e32 v211, 0x45800000, v201
	v_cndmask_b32_e32 v201, v201, v211, vcc
	v_cmp_gt_u32_e32 vcc, s8, v161
	s_nop 1
	v_cndmask_b32_e32 v132, 0, v201, vcc
	v_pk_mul_f32 v[156:157], v[128:129], v[130:131] op_sel_hi:[1,0]
	v_pk_mul_f32 v[154:155], v[126:127], v[130:131] op_sel_hi:[1,0]
	v_pk_mul_f32 v[84:85], v[84:85], v[130:131] op_sel_hi:[1,0]
	v_pk_mul_f32 v[82:83], v[82:83], v[130:131] op_sel_hi:[1,0]
	v_pk_mul_f32 v[160:161], v[124:125], v[130:131] op_sel_hi:[1,0]
	v_pk_mul_f32 v[158:159], v[122:123], v[130:131] op_sel_hi:[1,0]
	v_pk_mul_f32 v[88:89], v[88:89], v[130:131] op_sel_hi:[1,0]
	v_pk_mul_f32 v[86:87], v[86:87], v[130:131] op_sel_hi:[1,0]
	v_pk_mul_f32 v[120:121], v[120:121], v[132:133] op_sel_hi:[1,0]
	v_pk_mul_f32 v[118:119], v[118:119], v[132:133] op_sel_hi:[1,0]
	v_pk_mul_f32 v[60:61], v[60:61], v[132:133] op_sel_hi:[1,0]
	v_pk_mul_f32 v[58:59], v[58:59], v[132:133] op_sel_hi:[1,0]
	v_pk_mul_f32 v[116:117], v[116:117], v[132:133] op_sel_hi:[1,0]
	v_pk_mul_f32 v[114:115], v[114:115], v[132:133] op_sel_hi:[1,0]
	v_pk_mul_f32 v[64:65], v[64:65], v[132:133] op_sel_hi:[1,0]
	v_pk_mul_f32 v[62:63], v[62:63], v[132:133] op_sel_hi:[1,0]
	v_cmp_gt_i32_e64 s[46:47], 14, v162
	v_cmp_lt_i32_e64 s[44:45], 13, v162
	v_lshlrev_b32_e32 v122, 3, v163
	s_and_saveexec_b64 s[8:9], s[44:45]
	s_cbranch_execz .LBB0_65
	v_lshlrev_b32_e32 v123, 2, v162
	s_movk_i32 s16, 0xffc8
	v_add3_u32 v123, v123, v122, s16
	v_readlane_b32 s16, v255, 6
	v_readlane_b32 s17, v255, 7
	s_nop 0
	v_add_u32_e32 v124, s16, v123
	v_readlane_b32 s16, v254, 13
	v_add_u32_e32 v123, s17, v123
	s_nop 0
	v_lshl_add_u32 v124, v124, 4, s16
	v_lshl_add_u32 v123, v123, 4, s16
	ds_write_b128 v124, v[154:157]
	ds_write_b128 v124, v[82:85] offset:16
	ds_write_b128 v124, v[158:161] offset:32
	ds_write_b128 v124, v[86:89] offset:48
	ds_write_b128 v123, v[118:121]
	ds_write_b128 v123, v[58:61] offset:16
	ds_write_b128 v123, v[114:117] offset:32
	ds_write_b128 v123, v[62:65] offset:48

; DI float gelu_tanh(float x) { return 0.5f * x * (1.f + tanhf(0.7978845608028654f * (x + 0.044715f * x * x * x))); }
; __device__ __forceinline__ unsigned cvt_pk_bf16(float lo, float hi) { unsigned r; asm volatile("v_cvt_pk_bf16_f32 %0, %1, %2" : "=v"(r) : "v"(lo), "v"(hi)); return r; }
;     DI bf16_t* z() const { return (bf16_t*)(ws + WS_Z); }
;     DI float* b1(int l, int v) const { return (float*)(ws + WS_B1) + (l * 2 + v) * 128; }
;     __device__ __forceinline__ void operator()(const f32x4 (&acc)[2][2][4][2], const Unit& u, int wr, int wc, int fr, int fq) const {
;     ...
;             for (int m = 0; m < 4; ++m) {
;                 const int row = row0 + ai * HALF + m * 16;
;                 float sc = 1.f;
;                 if (MODE == EM_SCALEH) sc = ::rstd_h(ssq_in, row + rowoff);
;                 if (MODE == EM_SCALEQ) sc = ::rstd_q(ssq_in, row);
;                 if (MODE == EM_SCALEKV) sc = ::rstd_kv(ssq_in, row);
;                 float ss[2] = {0.f, 0.f};
; #pragma unroll
;                 for (int bj = 0; bj < 2; ++bj) {
;                     const int col = col0 + bj * HALF;
;                     f32x4 v0 = acc[ai][bj][m][0] * sc, v1 = acc[ai][bj][m][1] * sc;
;                     if (MODE == EM_GELU) { if (col < nvalid) { const f32x4 b0 = *(const f32x4*)(bias + col), b1 = *(const f32x4*)(bias + col + 4);
; #pragma unroll
;                         for (int i = 0; i < 4; ++i) { v0[i] = ::gelu_tanh(v0[i] + b0[i]); v1[i] = ::gelu_tanh(v1[i] + b1[i]); } } }
;                     if (MODE == EM_RES) { const f32x4* hi = (const f32x4*)(Hin + (size_t)row * 1024 + col); f32x4* hp = (f32x4*)(H + (size_t)row * 1024 + col); v0 += hi[0]; v1 += hi[1]; hp[0] = v0; hp[1] = v1; }
;                     if (STATS) ss[bj] = ((v0[0] * v0[0] + v0[1] * v0[1]) + (v0[2] * v0[2] + v0[3] * v0[3])) + ((v1[0] * v1[0] + v1[1] * v1[1]) + (v1[2] * v1[2] + v1[3] * v1[3]));
;                     if (col < nvalid) { u32x4 w; w.x = cvt_pk_bf16(v0[0], v0[1]); w.y = cvt_pk_bf16(v0[2], v0[3]); w.z = cvt_pk_bf16(v1[0], v1[1]); w.w = cvt_pk_bf16(v1[2], v1[3]);
;                         *(u32x4*)(O + (size_t)row * ldc + col) = w; }
;                 }
;                 if (STATS == 1) { float t = ss[0] + ss[1]; t += __shfl_xor(t, 16); t += __shfl_xor(t, 32); if (fq == 0) ssq_out[(size_t)row * 16 + u.pn * 4 + wc] = t; }
.LBB0_138:
	v_lshlrev_b32_e32 v168, 12, v152
	v_lshl_add_u32 v168, v154, 2, v168
	v_lshlrev_b32_e32 v169, 11, v152
	v_lshl_add_u32 v169, v154, 1, v169
	v_lshlrev_b32_e32 v170, 6, v152
	v_xor_b32_e32 v176, 16, v221
	v_lshlrev_b32_e32 v176, 2, v176
	s_lshl_b32 s32, s46, 20
	s_add_u32 s24, s10, s32
	s_addc_u32 s25, s11, 0
	s_lshl_b32 s32, s66, 10
	s_add_u32 s24, s24, s32
	s_addc_u32 s25, s25, 0
	s_lshl_b32 s32, s46, 20
	s_add_u32 s48, s8, s32
	s_addc_u32 s49, s9, 0
	s_lshl_b32 s32, s66, 10
	s_add_u32 s48, s48, s32
	s_addc_u32 s49, s49, 0
	s_lshl_b32 s32, s46, 19
	s_add_u32 s68, s52, s32
	s_addc_u32 s69, s53, 0
	s_lshl_b32 s32, s66, 9
	s_add_u32 s68, s68, s32
	s_addc_u32 s69, s69, 0
	s_lshl_b32 s32, s46, 14
	s_add_u32 s98, s54, s32
	s_addc_u32 s99, s55, 0
	s_lshl_b32 s32, s66, 2
	s_add_i32 s32, s32, s90
	s_lshl_b32 s32, s32, 2
	s_add_u32 s98, s98, s32
	s_addc_u32 s99, s99, 0
	global_load_dwordx4 v[140:143], v168, s[24:25]
	global_load_dwordx4 v[144:147], v168, s[24:25] offset:16
	global_load_dwordx4 v[156:159], v168, s[24:25] offset:512
	global_load_dwordx4 v[160:163], v168, s[24:25] offset:528
	s_add_u32 s24, s24, 0x10000
	s_addc_u32 s25, s25, 0
	global_load_dwordx4 v[164:167], v168, s[24:25]
	global_load_dwordx4 v[186:189], v168, s[24:25] offset:16
	global_load_dwordx4 v[190:193], v168, s[24:25] offset:512
	global_load_dwordx4 v[194:197], v168, s[24:25] offset:528
	s_add_u32 s24, s24, 0x10000
	s_addc_u32 s25, s25, 0
	global_load_dwordx4 v[198:201], v168, s[24:25]
	global_load_dwordx4 v[202:205], v168, s[24:25] offset:16
	global_load_dwordx4 v[210:213], v168, s[24:25] offset:512
	global_load_dwordx4 v[234:237], v168, s[24:25] offset:528
	s_add_u32 s24, s24, 0x10000
	s_addc_u32 s25, s25, 0
	global_load_dwordx4 v[238:241], v168, s[24:25]
	global_load_dwordx4 v[242:245], v168, s[24:25] offset:16
	global_load_dwordx4 v[246:249], v168, s[24:25] offset:512
	global_load_dwordx4 v[148:151], v168, s[24:25] offset:528
	s_waitcnt vmcnt(12)
	v_pk_add_f32 v[126:127], v[126:127], v[140:141]
	v_pk_add_f32 v[128:129], v[128:129], v[142:143]
	v_pk_add_f32 v[122:123], v[122:123], v[144:145]
	v_pk_add_f32 v[124:125], v[124:125], v[146:147]
	v_pk_add_f32 v[118:119], v[118:119], v[156:157]
	v_pk_add_f32 v[120:121], v[120:121], v[158:159]
	v_pk_add_f32 v[114:115], v[114:115], v[160:161]
	v_pk_add_f32 v[116:117], v[116:117], v[162:163]
	global_store_dwordx4 v168, v[126:129], s[48:49]
	global_store_dwordx4 v168, v[122:125], s[48:49] offset:16
	global_store_dwordx4 v168, v[118:121], s[48:49] offset:512
	global_store_dwordx4 v168, v[114:117], s[48:49] offset:528
	v_cvt_pk_bf16_f32 v140, v126, v127
	v_cvt_pk_bf16_f32 v141, v128, v129
	v_cvt_pk_bf16_f32 v142, v122, v123
	v_cvt_pk_bf16_f32 v143, v124, v125
	v_cvt_pk_bf16_f32 v156, v118, v119
	v_cvt_pk_bf16_f32 v157, v120, v121
	v_cvt_pk_bf16_f32 v158, v114, v115
	v_cvt_pk_bf16_f32 v159, v116, v117
	global_store_dwordx4 v169, v[140:143], s[68:69]
	global_store_dwordx4 v169, v[156:159], s[68:69] offset:256
	s_add_u32 s24, s24, 0x50000
	s_addc_u32 s25, s25, 0
	global_load_dwordx4 v[140:143], v168, s[24:25]
	global_load_dwordx4 v[144:147], v168, s[24:25] offset:16
	global_load_dwordx4 v[156:159], v168, s[24:25] offset:512
	global_load_dwordx4 v[160:163], v168, s[24:25] offset:528
	v_mul_f32_e32 v177, v126, v126
	v_mul_f32_e32 v184, v122, v122
	v_fmac_f32_e32 v177, v127, v127
	v_fmac_f32_e32 v177, v128, v128
	v_fmac_f32_e32 v177, v129, v129
	v_fmac_f32_e32 v184, v123, v123
	v_fmac_f32_e32 v184, v124, v124
	v_fmac_f32_e32 v184, v125, v125
	v_fmac_f32_e32 v177, v118, v118
	v_fmac_f32_e32 v177, v119, v119
	v_fmac_f32_e32 v177, v120, v120
	v_fmac_f32_e32 v177, v121, v121
	v_fmac_f32_e32 v184, v114, v114
	v_fmac_f32_e32 v184, v115, v115
	v_fmac_f32_e32 v184, v116, v116
	v_fmac_f32_e32 v184, v117, v117
	v_add_f32_e32 v177, v177, v184
	ds_bpermute_b32 v184, v176, v177
	s_waitcnt lgkmcnt(0)
	v_add_f32_e32 v177, v177, v184
	v_mov_b32_e32 v184, v177
	s_nop 1
	v_permlane32_swap_b32_e32 v184, v177
	v_add_f32_e32 v206, v177, v184
	s_and_saveexec_b64 s[16:17], s[42:43]
	global_store_dword v170, v206, s[98:99]
	s_or_b64 exec, exec, s[16:17]
	s_add_u32 s48, s48, 0x10000
	s_addc_u32 s49, s49, 0
	s_add_u32 s68, s68, 0x8000
	s_addc_u32 s69, s69, 0
	s_add_u32 s98, s98, 0x400
	s_addc_u32 s99, s99, 0
	s_waitcnt vmcnt(19)
	v_pk_add_f32 v[110:111], v[110:111], v[164:165]
	v_pk_add_f32 v[112:113], v[112:113], v[166:167]
	v_pk_add_f32 v[106:107], v[106:107], v[186:187]
	v_pk_add_f32 v[108:109], v[108:109], v[188:189]
	v_pk_add_f32 v[102:103], v[102:103], v[190:191]
	v_pk_add_f32 v[104:105], v[104:105], v[192:193]
	v_pk_add_f32 v[98:99], v[98:99], v[194:195]
	v_pk_add_f32 v[100:101], v[100:101], v[196:197]
	global_store_dwordx4 v168, v[110:113], s[48:49]
	global_store_dwordx4 v168, v[106:109], s[48:49] offset:16
	global_store_dwordx4 v168, v[102:105], s[48:49] offset:512
	global_store_dwordx4 v168, v[98:101], s[48:49] offset:528
	v_cvt_pk_bf16_f32 v164, v110, v111
	v_cvt_pk_bf16_f32 v165, v112, v113
	v_cvt_pk_bf16_f32 v166, v106, v107
	v_cvt_pk_bf16_f32 v167, v108, v109
	v_cvt_pk_bf16_f32 v190, v102, v103
	v_cvt_pk_bf16_f32 v191, v104, v105
	v_cvt_pk_bf16_f32 v192, v98, v99
	v_cvt_pk_bf16_f32 v193, v100, v101
	global_store_dwordx4 v169, v[164:167], s[68:69]
	global_store_dwordx4 v169, v[190:193], s[68:69] offset:256
	s_add_u32 s24, s24, 0x10000
	s_addc_u32 s25, s25, 0
	global_load_dwordx4 v[164:167], v168, s[24:25]
	global_load_dwordx4 v[186:189], v168, s[24:25] offset:16
	global_load_dwordx4 v[190:193], v168, s[24:25] offset:512
	global_load_dwordx4 v[194:197], v168, s[24:25] offset:528
	v_mul_f32_e32 v177, v110, v110
	v_mul_f32_e32 v184, v106, v106
	v_fmac_f32_e32 v177, v111, v111
	v_fmac_f32_e32 v177, v112, v112
	v_fmac_f32_e32 v177, v113, v113
	v_fmac_f32_e32 v184, v107, v107
	v_fmac_f32_e32 v184, v108, v108
	v_fmac_f32_e32 v184, v109, v109
	v_fmac_f32_e32 v177, v102, v102
	v_fmac_f32_e32 v177, v103, v103
	v_fmac_f32_e32 v177, v104, v104
	v_fmac_f32_e32 v177, v105, v105
	v_fmac_f32_e32 v184, v98, v98
	v_fmac_f32_e32 v184, v99, v99
	v_fmac_f32_e32 v184, v100, v100
	v_fmac_f32_e32 v184, v101, v101
	v_add_f32_e32 v177, v177, v184
	ds_bpermute_b32 v184, v176, v177
	s_waitcnt lgkmcnt(0)
; DI float gelu_tanh(float x) { return 0.5f * x * (1.f + tanhf(0.7978845608028654f * (x + 0.044715f * x * x * x))); }
; __device__ __forceinline__ unsigned cvt_pk_bf16(float lo, float hi) { unsigned r; asm volatile("v_cvt_pk_bf16_f32 %0, %1, %2" : "=v"(r) : "v"(lo), "v"(hi)); return r; }
;     DI bf16_t* z() const { return (bf16_t*)(ws + WS_Z); }
;     DI float* b1(int l, int v) const { return (float*)(ws + WS_B1) + (l * 2 + v) * 128; }
;     __device__ __forceinline__ void operator()(const f32x4 (&acc)[2][2][4][2], const Unit& u, int wr, int wc, int fr, int fq) const {
;     ...
;             for (int m = 0; m < 4; ++m) {
;                 const int row = row0 + ai * HALF + m * 16;
;                 float sc = 1.f;
;                 if (MODE == EM_SCALEH) sc = ::rstd_h(ssq_in, row + rowoff);
;                 if (MODE == EM_SCALEQ) sc = ::rstd_q(ssq_in, row);
;                 if (MODE == EM_SCALEKV) sc = ::rstd_kv(ssq_in, row);
;                 float ss[2] = {0.f, 0.f};
; #pragma unroll
;                 for (int bj = 0; bj < 2; ++bj) {
;                     const int col = col0 + bj * HALF;
;                     f32x4 v0 = acc[ai][bj][m][0] * sc, v1 = acc[ai][bj][m][1] * sc;
;                     if (MODE == EM_GELU) { if (col < nvalid) { const f32x4 b0 = *(const f32x4*)(bias + col), b1 = *(const f32x4*)(bias + col + 4);
; #pragma unroll
;                         for (int i = 0; i < 4; ++i) { v0[i] = ::gelu_tanh(v0[i] + b0[i]); v1[i] = ::gelu_tanh(v1[i] + b1[i]); } } }
;                     if (MODE == EM_RES) { const f32x4* hi = (const f32x4*)(Hin + (size_t)row * 1024 + col); f32x4* hp = (f32x4*)(H + (size_t)row * 1024 + col); v0 += hi[0]; v1 += hi[1]; hp[0] = v0; hp[1] = v1; }
;                     if (STATS) ss[bj] = ((v0[0] * v0[0] + v0[1] * v0[1]) + (v0[2] * v0[2] + v0[3] * v0[3])) + ((v1[0] * v1[0] + v1[1] * v1[1]) + (v1[2] * v1[2] + v1[3] * v1[3]));
;                     if (col < nvalid) { u32x4 w; w.x = cvt_pk_bf16(v0[0], v0[1]); w.y = cvt_pk_bf16(v0[2], v0[3]); w.z = cvt_pk_bf16(v1[0], v1[1]); w.w = cvt_pk_bf16(v1[2], v1[3]);
;                         *(u32x4*)(O + (size_t)row * ldc + col) = w; }
;                 }
;                 if (STATS == 1) { float t = ss[0] + ss[1]; t += __shfl_xor(t, 16); t += __shfl_xor(t, 32); if (fq == 0) ssq_out[(size_t)row * 16 + u.pn * 4 + wc] = t; }
	v_add_f32_e32 v177, v177, v184
	v_mov_b32_e32 v184, v177
	s_nop 1
	v_permlane32_swap_b32_e32 v184, v177
	v_add_f32_e32 v206, v177, v184
	s_and_saveexec_b64 s[16:17], s[42:43]
	global_store_dword v170, v206, s[98:99]
	s_or_b64 exec, exec, s[16:17]
	s_add_u32 s48, s48, 0x10000
	s_addc_u32 s49, s49, 0
	s_add_u32 s68, s68, 0x8000
	s_addc_u32 s69, s69, 0
	s_add_u32 s98, s98, 0x400
	s_addc_u32 s99, s99, 0
	s_waitcnt vmcnt(26)
	v_pk_add_f32 v[94:95], v[94:95], v[198:199]
	v_pk_add_f32 v[96:97], v[96:97], v[200:201]
	v_pk_add_f32 v[90:91], v[90:91], v[202:203]
	v_pk_add_f32 v[92:93], v[92:93], v[204:205]
	v_pk_add_f32 v[86:87], v[86:87], v[210:211]
	v_pk_add_f32 v[88:89], v[88:89], v[212:213]
	v_pk_add_f32 v[82:83], v[82:83], v[234:235]
	v_pk_add_f32 v[84:85], v[84:85], v[236:237]
	global_store_dwordx4 v168, v[94:97], s[48:49]
	global_store_dwordx4 v168, v[90:93], s[48:49] offset:16
	global_store_dwordx4 v168, v[86:89], s[48:49] offset:512
	global_store_dwordx4 v168, v[82:85], s[48:49] offset:528
	v_cvt_pk_bf16_f32 v198, v94, v95
	v_cvt_pk_bf16_f32 v199, v96, v97
	v_cvt_pk_bf16_f32 v200, v90, v91
	v_cvt_pk_bf16_f32 v201, v92, v93
	v_cvt_pk_bf16_f32 v210, v86, v87
	v_cvt_pk_bf16_f32 v211, v88, v89
	v_cvt_pk_bf16_f32 v212, v82, v83
	v_cvt_pk_bf16_f32 v213, v84, v85
	global_store_dwordx4 v169, v[198:201], s[68:69]
	global_store_dwordx4 v169, v[210:213], s[68:69] offset:256
	s_add_u32 s24, s24, 0x10000
	s_addc_u32 s25, s25, 0
	global_load_dwordx4 v[198:201], v168, s[24:25]
	global_load_dwordx4 v[202:205], v168, s[24:25] offset:16
	global_load_dwordx4 v[210:213], v168, s[24:25] offset:512
	global_load_dwordx4 v[234:237], v168, s[24:25] offset:528
	v_mul_f32_e32 v177, v94, v94
	v_mul_f32_e32 v184, v90, v90
	v_fmac_f32_e32 v177, v95, v95
	v_fmac_f32_e32 v177, v96, v96
	v_fmac_f32_e32 v177, v97, v97
	v_fmac_f32_e32 v184, v91, v91
	v_fmac_f32_e32 v184, v92, v92
	v_fmac_f32_e32 v184, v93, v93
	v_fmac_f32_e32 v177, v86, v86
	v_fmac_f32_e32 v177, v87, v87
	v_fmac_f32_e32 v177, v88, v88
	v_fmac_f32_e32 v177, v89, v89
	v_fmac_f32_e32 v184, v82, v82
	v_fmac_f32_e32 v184, v83, v83
	v_fmac_f32_e32 v184, v84, v84
	v_fmac_f32_e32 v184, v85, v85
	v_add_f32_e32 v177, v177, v184
	ds_bpermute_b32 v184, v176, v177
	s_waitcnt lgkmcnt(0)
	v_add_f32_e32 v177, v177, v184
	v_mov_b32_e32 v184, v177
	s_nop 1
	v_permlane32_swap_b32_e32 v184, v177
	v_add_f32_e32 v206, v177, v184
	s_and_saveexec_b64 s[16:17], s[42:43]
	global_store_dword v170, v206, s[98:99]
	s_or_b64 exec, exec, s[16:17]
	s_add_u32 s48, s48, 0x10000
	s_addc_u32 s49, s49, 0
	s_add_u32 s68, s68, 0x8000
	s_addc_u32 s69, s69, 0
	s_add_u32 s98, s98, 0x400
	s_addc_u32 s99, s99, 0
	s_waitcnt vmcnt(33)
	v_pk_add_f32 v[78:79], v[78:79], v[238:239]
	v_pk_add_f32 v[80:81], v[80:81], v[240:241]
	v_pk_add_f32 v[74:75], v[74:75], v[242:243]
	v_pk_add_f32 v[76:77], v[76:77], v[244:245]
	v_pk_add_f32 v[70:71], v[70:71], v[246:247]
	v_pk_add_f32 v[72:73], v[72:73], v[248:249]
	v_pk_add_f32 v[66:67], v[66:67], v[148:149]
	v_pk_add_f32 v[68:69], v[68:69], v[150:151]
	global_store_dwordx4 v168, v[78:81], s[48:49]
	global_store_dwordx4 v168, v[74:77], s[48:49] offset:16
	global_store_dwordx4 v168, v[70:73], s[48:49] offset:512
	global_store_dwordx4 v168, v[66:69], s[48:49] offset:528
	v_cvt_pk_bf16_f32 v238, v78, v79
	v_cvt_pk_bf16_f32 v239, v80, v81
	v_cvt_pk_bf16_f32 v240, v74, v75
	v_cvt_pk_bf16_f32 v241, v76, v77
	v_cvt_pk_bf16_f32 v246, v70, v71
	v_cvt_pk_bf16_f32 v247, v72, v73
	v_cvt_pk_bf16_f32 v248, v66, v67
	v_cvt_pk_bf16_f32 v249, v68, v69
	global_store_dwordx4 v169, v[238:241], s[68:69]
	global_store_dwordx4 v169, v[246:249], s[68:69] offset:256
	s_add_u32 s24, s24, 0x10000
	s_addc_u32 s25, s25, 0
	global_load_dwordx4 v[238:241], v168, s[24:25]
	global_load_dwordx4 v[242:245], v168, s[24:25] offset:16
	global_load_dwordx4 v[246:249], v168, s[24:25] offset:512
	global_load_dwordx4 v[148:151], v168, s[24:25] offset:528
	v_mul_f32_e32 v177, v78, v78
	v_mul_f32_e32 v184, v74, v74
	v_fmac_f32_e32 v177, v79, v79
	v_fmac_f32_e32 v177, v80, v80
	v_fmac_f32_e32 v177, v81, v81
	v_fmac_f32_e32 v184, v75, v75
	v_fmac_f32_e32 v184, v76, v76
	v_fmac_f32_e32 v184, v77, v77
	v_fmac_f32_e32 v177, v70, v70
	v_fmac_f32_e32 v177, v71, v71
	v_fmac_f32_e32 v177, v72, v72
	v_fmac_f32_e32 v177, v73, v73
	v_fmac_f32_e32 v184, v66, v66
	v_fmac_f32_e32 v184, v67, v67
	v_fmac_f32_e32 v184, v68, v68
	v_fmac_f32_e32 v184, v69, v69
	v_add_f32_e32 v177, v177, v184
	ds_bpermute_b32 v184, v176, v177
	s_waitcnt lgkmcnt(0)
	v_add_f32_e32 v177, v177, v184
	v_mov_b32_e32 v184, v177
	s_nop 1
	v_permlane32_swap_b32_e32 v184, v177
	v_add_f32_e32 v206, v177, v184
	s_and_saveexec_b64 s[16:17], s[42:43]
	global_store_dword v170, v206, s[98:99]
	s_or_b64 exec, exec, s[16:17]
	s_add_u32 s48, s48, 0x50000
	s_addc_u32 s49, s49, 0
	s_add_u32 s68, s68, 0x28000
	s_addc_u32 s69, s69, 0
	s_add_u32 s98, s98, 0x1400
	s_addc_u32 s99, s99, 0
	s_waitcnt vmcnt(34)
; DI float gelu_tanh(float x) { return 0.5f * x * (1.f + tanhf(0.7978845608028654f * (x + 0.044715f * x * x * x))); }
; __device__ __forceinline__ unsigned cvt_pk_bf16(float lo, float hi) { unsigned r; asm volatile("v_cvt_pk_bf16_f32 %0, %1, %2" : "=v"(r) : "v"(lo), "v"(hi)); return r; }
;     DI bf16_t* z() const { return (bf16_t*)(ws + WS_Z); }
;     DI float* b1(int l, int v) const { return (float*)(ws + WS_B1) + (l * 2 + v) * 128; }
;     __device__ __forceinline__ void operator()(const f32x4 (&acc)[2][2][4][2], const Unit& u, int wr, int wc, int fr, int fq) const {
;     ...
;             for (int m = 0; m < 4; ++m) {
;                 const int row = row0 + ai * HALF + m * 16;
;                 float sc = 1.f;
;                 if (MODE == EM_SCALEH) sc = ::rstd_h(ssq_in, row + rowoff);
;                 if (MODE == EM_SCALEQ) sc = ::rstd_q(ssq_in, row);
;                 if (MODE == EM_SCALEKV) sc = ::rstd_kv(ssq_in, row);
;                 float ss[2] = {0.f, 0.f};
; #pragma unroll
;                 for (int bj = 0; bj < 2; ++bj) {
;                     const int col = col0 + bj * HALF;
;                     f32x4 v0 = acc[ai][bj][m][0] * sc, v1 = acc[ai][bj][m][1] * sc;
;                     if (MODE == EM_GELU) { if (col < nvalid) { const f32x4 b0 = *(const f32x4*)(bias + col), b1 = *(const f32x4*)(bias + col + 4);
; #pragma unroll
;                         for (int i = 0; i < 4; ++i) { v0[i] = ::gelu_tanh(v0[i] + b0[i]); v1[i] = ::gelu_tanh(v1[i] + b1[i]); } } }
;                     if (MODE == EM_RES) { const f32x4* hi = (const f32x4*)(Hin + (size_t)row * 1024 + col); f32x4* hp = (f32x4*)(H + (size_t)row * 1024 + col); v0 += hi[0]; v1 += hi[1]; hp[0] = v0; hp[1] = v1; }
;                     if (STATS) ss[bj] = ((v0[0] * v0[0] + v0[1] * v0[1]) + (v0[2] * v0[2] + v0[3] * v0[3])) + ((v1[0] * v1[0] + v1[1] * v1[1]) + (v1[2] * v1[2] + v1[3] * v1[3]));
;                     if (col < nvalid) { u32x4 w; w.x = cvt_pk_bf16(v0[0], v0[1]); w.y = cvt_pk_bf16(v0[2], v0[3]); w.z = cvt_pk_bf16(v1[0], v1[1]); w.w = cvt_pk_bf16(v1[2], v1[3]);
;                         *(u32x4*)(O + (size_t)row * ldc + col) = w; }
;                 }
;                 if (STATS == 1) { float t = ss[0] + ss[1]; t += __shfl_xor(t, 16); t += __shfl_xor(t, 32); if (fq == 0) ssq_out[(size_t)row * 16 + u.pn * 4 + wc] = t; }
	v_pk_add_f32 v[62:63], v[62:63], v[140:141]
	v_pk_add_f32 v[64:65], v[64:65], v[142:143]
	v_pk_add_f32 v[58:59], v[58:59], v[144:145]
	v_pk_add_f32 v[60:61], v[60:61], v[146:147]
	v_pk_add_f32 v[54:55], v[54:55], v[156:157]
	v_pk_add_f32 v[56:57], v[56:57], v[158:159]
	v_pk_add_f32 v[50:51], v[50:51], v[160:161]
	v_pk_add_f32 v[52:53], v[52:53], v[162:163]
	global_store_dwordx4 v168, v[62:65], s[48:49]
	global_store_dwordx4 v168, v[58:61], s[48:49] offset:16
	global_store_dwordx4 v168, v[54:57], s[48:49] offset:512
	global_store_dwordx4 v168, v[50:53], s[48:49] offset:528
	v_cvt_pk_bf16_f32 v140, v62, v63
	v_cvt_pk_bf16_f32 v141, v64, v65
	v_cvt_pk_bf16_f32 v142, v58, v59
	v_cvt_pk_bf16_f32 v143, v60, v61
	v_cvt_pk_bf16_f32 v156, v54, v55
	v_cvt_pk_bf16_f32 v157, v56, v57
	v_cvt_pk_bf16_f32 v158, v50, v51
	v_cvt_pk_bf16_f32 v159, v52, v53
	global_store_dwordx4 v169, v[140:143], s[68:69]
	global_store_dwordx4 v169, v[156:159], s[68:69] offset:256
	v_mul_f32_e32 v177, v62, v62
	v_mul_f32_e32 v184, v58, v58
	v_fmac_f32_e32 v177, v63, v63
	v_fmac_f32_e32 v177, v64, v64
	v_fmac_f32_e32 v177, v65, v65
	v_fmac_f32_e32 v184, v59, v59
	v_fmac_f32_e32 v184, v60, v60
	v_fmac_f32_e32 v184, v61, v61
	v_fmac_f32_e32 v177, v54, v54
	v_fmac_f32_e32 v177, v55, v55
	v_fmac_f32_e32 v177, v56, v56
	v_fmac_f32_e32 v177, v57, v57
	v_fmac_f32_e32 v184, v50, v50
	v_fmac_f32_e32 v184, v51, v51
	v_fmac_f32_e32 v184, v52, v52
	v_fmac_f32_e32 v184, v53, v53
	v_add_f32_e32 v177, v177, v184
	ds_bpermute_b32 v184, v176, v177
	s_waitcnt lgkmcnt(0)
	v_add_f32_e32 v177, v177, v184
	v_mov_b32_e32 v184, v177
	s_nop 1
	v_permlane32_swap_b32_e32 v184, v177
	v_add_f32_e32 v206, v177, v184
	s_and_saveexec_b64 s[16:17], s[42:43]
	global_store_dword v170, v206, s[98:99]
	s_or_b64 exec, exec, s[16:17]
	s_add_u32 s48, s48, 0x10000
	s_addc_u32 s49, s49, 0
	s_add_u32 s68, s68, 0x8000
	s_addc_u32 s69, s69, 0
	s_add_u32 s98, s98, 0x400
	s_addc_u32 s99, s99, 0
	s_waitcnt vmcnt(30)
	v_pk_add_f32 v[46:47], v[46:47], v[164:165]
	v_pk_add_f32 v[48:49], v[48:49], v[166:167]
	v_pk_add_f32 v[42:43], v[42:43], v[186:187]
	v_pk_add_f32 v[44:45], v[44:45], v[188:189]
	v_pk_add_f32 v[38:39], v[38:39], v[190:191]
	v_pk_add_f32 v[40:41], v[40:41], v[192:193]
	v_pk_add_f32 v[34:35], v[34:35], v[194:195]
	v_pk_add_f32 v[36:37], v[36:37], v[196:197]
	global_store_dwordx4 v168, v[46:49], s[48:49]
	global_store_dwordx4 v168, v[42:45], s[48:49] offset:16
	global_store_dwordx4 v168, v[38:41], s[48:49] offset:512
	global_store_dwordx4 v168, v[34:37], s[48:49] offset:528
	v_cvt_pk_bf16_f32 v164, v46, v47
	v_cvt_pk_bf16_f32 v165, v48, v49
	v_cvt_pk_bf16_f32 v166, v42, v43
	v_cvt_pk_bf16_f32 v167, v44, v45
	v_cvt_pk_bf16_f32 v190, v38, v39
	v_cvt_pk_bf16_f32 v191, v40, v41
	v_cvt_pk_bf16_f32 v192, v34, v35
	v_cvt_pk_bf16_f32 v193, v36, v37
	global_store_dwordx4 v169, v[164:167], s[68:69]
	global_store_dwordx4 v169, v[190:193], s[68:69] offset:256
	v_mul_f32_e32 v177, v46, v46
	v_mul_f32_e32 v184, v42, v42
	v_fmac_f32_e32 v177, v47, v47
	v_fmac_f32_e32 v177, v48, v48
	v_fmac_f32_e32 v177, v49, v49
	v_fmac_f32_e32 v184, v43, v43
	v_fmac_f32_e32 v184, v44, v44
	v_fmac_f32_e32 v184, v45, v45
	v_fmac_f32_e32 v177, v38, v38
	v_fmac_f32_e32 v177, v39, v39
	v_fmac_f32_e32 v177, v40, v40
	v_fmac_f32_e32 v177, v41, v41
	v_fmac_f32_e32 v184, v34, v34
	v_fmac_f32_e32 v184, v35, v35
	v_fmac_f32_e32 v184, v36, v36
	v_fmac_f32_e32 v184, v37, v37
	v_add_f32_e32 v177, v177, v184
	ds_bpermute_b32 v184, v176, v177
	s_waitcnt lgkmcnt(0)
	v_add_f32_e32 v177, v177, v184
	v_mov_b32_e32 v184, v177
	s_nop 1
	v_permlane32_swap_b32_e32 v184, v177
	v_add_f32_e32 v206, v177, v184
	s_and_saveexec_b64 s[16:17], s[42:43]
	global_store_dword v170, v206, s[98:99]
	s_or_b64 exec, exec, s[16:17]
	s_add_u32 s48, s48, 0x10000
	s_addc_u32 s49, s49, 0
	s_add_u32 s68, s68, 0x8000
	s_addc_u32 s69, s69, 0
	s_add_u32 s98, s98, 0x400
	s_addc_u32 s99, s99, 0
	s_waitcnt vmcnt(26)
; DI float gelu_tanh(float x) { return 0.5f * x * (1.f + tanhf(0.7978845608028654f * (x + 0.044715f * x * x * x))); }
; __device__ __forceinline__ unsigned cvt_pk_bf16(float lo, float hi) { unsigned r; asm volatile("v_cvt_pk_bf16_f32 %0, %1, %2" : "=v"(r) : "v"(lo), "v"(hi)); return r; }
;     DI bf16_t* z() const { return (bf16_t*)(ws + WS_Z); }
;     DI float* b1(int l, int v) const { return (float*)(ws + WS_B1) + (l * 2 + v) * 128; }
;     __device__ __forceinline__ void operator()(const f32x4 (&acc)[2][2][4][2], const Unit& u, int wr, int wc, int fr, int fq) const {
;     ...
;             for (int m = 0; m < 4; ++m) {
;                 const int row = row0 + ai * HALF + m * 16;
;                 float sc = 1.f;
;                 if (MODE == EM_SCALEH) sc = ::rstd_h(ssq_in, row + rowoff);
;                 if (MODE == EM_SCALEQ) sc = ::rstd_q(ssq_in, row);
;                 if (MODE == EM_SCALEKV) sc = ::rstd_kv(ssq_in, row);
;                 float ss[2] = {0.f, 0.f};
; #pragma unroll
;                 for (int bj = 0; bj < 2; ++bj) {
;                     const int col = col0 + bj * HALF;
;                     f32x4 v0 = acc[ai][bj][m][0] * sc, v1 = acc[ai][bj][m][1] * sc;
;                     if (MODE == EM_GELU) { if (col < nvalid) { const f32x4 b0 = *(const f32x4*)(bias + col), b1 = *(const f32x4*)(bias + col + 4);
; #pragma unroll
;                         for (int i = 0; i < 4; ++i) { v0[i] = ::gelu_tanh(v0[i] + b0[i]); v1[i] = ::gelu_tanh(v1[i] + b1[i]); } } }
;                     if (MODE == EM_RES) { const f32x4* hi = (const f32x4*)(Hin + (size_t)row * 1024 + col); f32x4* hp = (f32x4*)(H + (size_t)row * 1024 + col); v0 += hi[0]; v1 += hi[1]; hp[0] = v0; hp[1] = v1; }
;                     if (STATS) ss[bj] = ((v0[0] * v0[0] + v0[1] * v0[1]) + (v0[2] * v0[2] + v0[3] * v0[3])) + ((v1[0] * v1[0] + v1[1] * v1[1]) + (v1[2] * v1[2] + v1[3] * v1[3]));
;                     if (col < nvalid) { u32x4 w; w.x = cvt_pk_bf16(v0[0], v0[1]); w.y = cvt_pk_bf16(v0[2], v0[3]); w.z = cvt_pk_bf16(v1[0], v1[1]); w.w = cvt_pk_bf16(v1[2], v1[3]);
;                         *(u32x4*)(O + (size_t)row * ldc + col) = w; }
;                 }
;                 if (STATS == 1) { float t = ss[0] + ss[1]; t += __shfl_xor(t, 16); t += __shfl_xor(t, 32); if (fq == 0) ssq_out[(size_t)row * 16 + u.pn * 4 + wc] = t; }
	v_pk_add_f32 v[30:31], v[30:31], v[198:199]
	v_pk_add_f32 v[32:33], v[32:33], v[200:201]
	v_pk_add_f32 v[26:27], v[26:27], v[202:203]
	v_pk_add_f32 v[28:29], v[28:29], v[204:205]
	v_pk_add_f32 v[22:23], v[22:23], v[210:211]
	v_pk_add_f32 v[24:25], v[24:25], v[212:213]
	v_pk_add_f32 v[18:19], v[18:19], v[234:235]
	v_pk_add_f32 v[20:21], v[20:21], v[236:237]
	global_store_dwordx4 v168, v[30:33], s[48:49]
	global_store_dwordx4 v168, v[26:29], s[48:49] offset:16
	global_store_dwordx4 v168, v[22:25], s[48:49] offset:512
	global_store_dwordx4 v168, v[18:21], s[48:49] offset:528
	v_cvt_pk_bf16_f32 v198, v30, v31
	v_cvt_pk_bf16_f32 v199, v32, v33
	v_cvt_pk_bf16_f32 v200, v26, v27
	v_cvt_pk_bf16_f32 v201, v28, v29
	v_cvt_pk_bf16_f32 v210, v22, v23
	v_cvt_pk_bf16_f32 v211, v24, v25
	v_cvt_pk_bf16_f32 v212, v18, v19
	v_cvt_pk_bf16_f32 v213, v20, v21
	global_store_dwordx4 v169, v[198:201], s[68:69]
	global_store_dwordx4 v169, v[210:213], s[68:69] offset:256
	v_mul_f32_e32 v177, v30, v30
	v_mul_f32_e32 v184, v26, v26
	v_fmac_f32_e32 v177, v31, v31
	v_fmac_f32_e32 v177, v32, v32
	v_fmac_f32_e32 v177, v33, v33
	v_fmac_f32_e32 v184, v27, v27
	v_fmac_f32_e32 v184, v28, v28
	v_fmac_f32_e32 v184, v29, v29
	v_fmac_f32_e32 v177, v22, v22
	v_fmac_f32_e32 v177, v23, v23
	v_fmac_f32_e32 v177, v24, v24
	v_fmac_f32_e32 v177, v25, v25
	v_fmac_f32_e32 v184, v18, v18
	v_fmac_f32_e32 v184, v19, v19
	v_fmac_f32_e32 v184, v20, v20
	v_fmac_f32_e32 v184, v21, v21
	v_add_f32_e32 v177, v177, v184
	ds_bpermute_b32 v184, v176, v177
	s_waitcnt lgkmcnt(0)
	v_add_f32_e32 v177, v177, v184
	v_mov_b32_e32 v184, v177
	s_nop 1
	v_permlane32_swap_b32_e32 v184, v177
	v_add_f32_e32 v206, v177, v184
	s_and_saveexec_b64 s[16:17], s[42:43]
	global_store_dword v170, v206, s[98:99]
	s_or_b64 exec, exec, s[16:17]
	s_add_u32 s48, s48, 0x10000
	s_addc_u32 s49, s49, 0
	s_add_u32 s68, s68, 0x8000
	s_addc_u32 s69, s69, 0
	s_add_u32 s98, s98, 0x400
	s_addc_u32 s99, s99, 0
	s_waitcnt vmcnt(22)
	v_pk_add_f32 v[14:15], v[14:15], v[238:239]
	v_pk_add_f32 v[16:17], v[16:17], v[240:241]
	v_pk_add_f32 v[10:11], v[10:11], v[242:243]
	v_pk_add_f32 v[12:13], v[12:13], v[244:245]
	v_pk_add_f32 v[6:7], v[6:7], v[246:247]
	v_pk_add_f32 v[8:9], v[8:9], v[248:249]
	v_pk_add_f32 v[2:3], v[2:3], v[148:149]
	v_pk_add_f32 v[4:5], v[4:5], v[150:151]
	global_store_dwordx4 v168, v[14:17], s[48:49]
	global_store_dwordx4 v168, v[10:13], s[48:49] offset:16
	global_store_dwordx4 v168, v[6:9], s[48:49] offset:512
	global_store_dwordx4 v168, v[2:5], s[48:49] offset:528
	v_cvt_pk_bf16_f32 v238, v14, v15
	v_cvt_pk_bf16_f32 v239, v16, v17
	v_cvt_pk_bf16_f32 v240, v10, v11
	v_cvt_pk_bf16_f32 v241, v12, v13
	v_cvt_pk_bf16_f32 v246, v6, v7
	v_cvt_pk_bf16_f32 v247, v8, v9
	v_cvt_pk_bf16_f32 v248, v2, v3
	v_cvt_pk_bf16_f32 v249, v4, v5
	global_store_dwordx4 v169, v[238:241], s[68:69]
	global_store_dwordx4 v169, v[246:249], s[68:69] offset:256
	v_mul_f32_e32 v177, v14, v14
	v_mul_f32_e32 v184, v10, v10
	v_fmac_f32_e32 v177, v15, v15
	v_fmac_f32_e32 v177, v16, v16
	v_fmac_f32_e32 v177, v17, v17
	v_fmac_f32_e32 v184, v11, v11
	v_fmac_f32_e32 v184, v12, v12
	v_fmac_f32_e32 v184, v13, v13
	v_fmac_f32_e32 v177, v6, v6
	v_fmac_f32_e32 v177, v7, v7
	v_fmac_f32_e32 v177, v8, v8
	v_fmac_f32_e32 v177, v9, v9
	v_fmac_f32_e32 v184, v2, v2
	v_fmac_f32_e32 v184, v3, v3
	v_fmac_f32_e32 v184, v4, v4
	v_fmac_f32_e32 v184, v5, v5
	v_add_f32_e32 v177, v177, v184
	ds_bpermute_b32 v184, v176, v177
	s_waitcnt lgkmcnt(0)
	v_add_f32_e32 v177, v177, v184
	v_mov_b32_e32 v184, v177
	s_nop 1
	v_permlane32_swap_b32_e32 v184, v177
	v_add_f32_e32 v206, v177, v184
	s_and_saveexec_b64 s[16:17], s[42:43]
	global_store_dword v170, v206, s[98:99]
	s_or_b64 exec, exec, s[16:17]
	s_andn2_b64 vcc, exec, s[44:45]
	s_mov_b64 s[16:17], -1
	s_cbranch_vccnz .LBB0_127
	v_readlane_b32 s16, v254, 44
	v_readlane_b32 s17, v254, 45
	s_andn2_b64 vcc, exec, s[16:17]
	s_cbranch_vccnz .LBB0_126
	s_barrier
	s_branch .LBB0_126

.LBB0_1428:
	v_readfirstlane_b32 s52, v138
.Lsel_step0:
	s_mov_b32 s17, -1
	s_cmp_lt_i32 s16, 64
	s_cbranch_scc1 .Lsel_nn0
	s_lshr_b32 s24, s16, 6
	s_lshl_b64 s[24:25], -1, s24
	s_andn2_b64 s[24:25], s[48:49], s[24:25]
	s_cmp_eq_u64 s[24:25], 0
	s_cbranch_scc1 .Lsel_nn0
	s_flbit_i32_b64 s17, s[24:25]
	s_lshl_b32 s17, s17, 6
	s_xor_b32 s17, s17, 0xfc0
.Lsel_nn0:
	s_cmp_lt_i32 s17, 0
	s_cselect_b32 s24, s43, s17
	v_add_u32_e32 v6, s24, v136
	v_add_u32_e32 v2, s24, v137
	v_lshlrev_b32_e32 v6, 12, v6
	v_lshlrev_b32_e32 v2, 12, v2
	v_mov_b32_e32 v7, v1
	v_mov_b32_e32 v3, v1
	v_lshl_add_u64 v[6:7], v[122:123], 0, v[6:7]
	v_lshl_add_u64 v[2:3], v[124:125], 0, v[2:3]
	global_load_dwordx4 v[6:9], v[6:7], off offset:2816
	global_load_dwordx4 v[2:5], v[2:3], off offset:3584
	ds_read_b128 v[126:129], v161 offset:0
	ds_read_b128 v[130:133], v161 offset:4608
	ds_read_b128 v[164:167], v161 offset:32
	ds_read_b128 v[10:13], v161 offset:4640
	s_waitcnt lgkmcnt(3)
	v_mfma_f32_32x32x16_bf16 v[96:111], v[126:129], v[144:147], 0
	ds_read_b128 v[126:129], v161 offset:64
	s_waitcnt lgkmcnt(3)
	v_mfma_f32_32x32x16_bf16 v[80:95], v[130:133], v[144:147], 0
	ds_read_b128 v[130:133], v161 offset:4672
	s_waitcnt lgkmcnt(3)
	v_mfma_f32_32x32x16_bf16 v[96:111], v[164:167], v[148:151], v[96:111]
	ds_read_b128 v[164:167], v161 offset:96
	s_waitcnt lgkmcnt(3)
	v_mfma_f32_32x32x16_bf16 v[80:95], v[10:13], v[148:151], v[80:95]
	ds_read_b128 v[10:13], v161 offset:4704
	s_waitcnt lgkmcnt(3)
	v_mfma_f32_32x32x16_bf16 v[96:111], v[126:129], v[152:155], v[96:111]
	s_waitcnt lgkmcnt(2)
	v_mfma_f32_32x32x16_bf16 v[80:95], v[130:133], v[152:155], v[80:95]
	s_waitcnt lgkmcnt(1)
	v_mfma_f32_32x32x16_bf16 v[96:111], v[164:167], v[156:159], v[96:111]
	s_waitcnt lgkmcnt(0)
	v_mfma_f32_32x32x16_bf16 v[80:95], v[10:13], v[156:159], v[80:95]
	v_add_u32_e32 v163, s43, v139
	v_sub_u32_e32 v163, v163, v205
	v_cvt_f32_i32_e32 v163, v163
	v_mul_f32_e32 v0, v186, v163
	s_lshr_b32 s24, s43, 6
	v_lshrrev_b64 v[14:15], s24, v[120:121]
	v_and_b32_e32 v14, 1, v14
	v_cmp_eq_u32_e32 vcc, 1, v14
	s_nop 1
	v_cndmask_b32_e32 v0, v225, v0, vcc
	s_nop 7
	v_fma_f32 v96, v96, s84, v0
	v_fmamk_f32 v15, v186, 0x3f800000, v0
	v_fma_f32 v97, v97, s84, v15
	v_fmamk_f32 v14, v186, 0x40000000, v0
	v_fma_f32 v98, v98, s84, v14
	v_fmamk_f32 v15, v186, 0x40400000, v0
	v_fma_f32 v99, v99, s84, v15
	v_fmamk_f32 v14, v186, 0x41000000, v0
	v_fma_f32 v100, v100, s84, v14
	v_fmamk_f32 v15, v186, 0x41100000, v0
	v_fma_f32 v101, v101, s84, v15
	v_fmamk_f32 v14, v186, 0x41200000, v0
	v_fma_f32 v102, v102, s84, v14
	v_fmamk_f32 v15, v186, 0x41300000, v0
	v_fma_f32 v103, v103, s84, v15
	v_fmamk_f32 v14, v186, 0x41800000, v0
	v_fma_f32 v104, v104, s84, v14
	v_fmamk_f32 v15, v186, 0x41880000, v0
	v_fma_f32 v105, v105, s84, v15
	v_fmamk_f32 v14, v186, 0x41900000, v0
	v_fma_f32 v106, v106, s84, v14
	v_fmamk_f32 v15, v186, 0x41980000, v0
	v_fma_f32 v107, v107, s84, v15
	v_fmamk_f32 v14, v186, 0x41c00000, v0
	v_fma_f32 v108, v108, s84, v14
	v_fmamk_f32 v15, v186, 0x41c80000, v0
	v_fma_f32 v109, v109, s84, v15
	v_fmamk_f32 v14, v186, 0x41d00000, v0
	v_fma_f32 v110, v110, s84, v14
	v_fmamk_f32 v15, v186, 0x41d80000, v0
	v_fma_f32 v111, v111, s84, v15
	v_fmamk_f32 v14, v186, 0x42000000, v0
	v_fma_f32 v80, v80, s84, v14
	v_fmamk_f32 v15, v186, 0x42040000, v0
	v_fma_f32 v81, v81, s84, v15
	v_fmamk_f32 v14, v186, 0x42080000, v0
	v_fma_f32 v82, v82, s84, v14
	v_fmamk_f32 v15, v186, 0x420c0000, v0
	v_fma_f32 v83, v83, s84, v15
	v_fmamk_f32 v14, v186, 0x42200000, v0
	v_fma_f32 v84, v84, s84, v14
	v_fmamk_f32 v15, v186, 0x42240000, v0
	v_fma_f32 v85, v85, s84, v15
	v_fmamk_f32 v14, v186, 0x42280000, v0
	v_fma_f32 v86, v86, s84, v14
	v_fmamk_f32 v15, v186, 0x422c0000, v0
	v_fma_f32 v87, v87, s84, v15
	v_fmamk_f32 v14, v186, 0x42400000, v0
	v_fma_f32 v88, v88, s84, v14
	v_fmamk_f32 v15, v186, 0x42440000, v0
	v_fma_f32 v89, v89, s84, v15
	v_fmamk_f32 v14, v186, 0x42480000, v0
	v_fma_f32 v90, v90, s84, v14
	v_fmamk_f32 v15, v186, 0x424c0000, v0
	v_fma_f32 v91, v91, s84, v15
	v_fmamk_f32 v14, v186, 0x42600000, v0
	v_fma_f32 v92, v92, s84, v14
	v_fmamk_f32 v15, v186, 0x42640000, v0
	v_fma_f32 v93, v93, s84, v15
	v_fmamk_f32 v14, v186, 0x42680000, v0
	v_fma_f32 v94, v94, s84, v14
	v_fmamk_f32 v15, v186, 0x426c0000, v0
	v_fma_f32 v95, v95, s84, v15
	s_add_i32 s24, s43, 63
	s_cmp_gt_i32 s24, s52
	s_cbranch_scc1 .Lsel_mask0
; template <bool PV> DI void online_step_mx(f32x16& x0, f32x16& x1, float mx, float& m, float& l, f32x16 (&O)[2]) {
;     const float mn = fmaxf(m, mx), alpha = __builtin_amdgcn_exp2f(m - mn);
;     float ls = 0.f;
; #pragma unroll
;     for (int i = 0; i < 16; ++i) { x0[i] = __builtin_amdgcn_exp2f(x0[i] - mn); x1[i] = __builtin_amdgcn_exp2f(x1[i] - mn); ls += x0[i] + x1[i]; }
;     ls += __shfl_xor(ls, 32);
;     l = l * alpha + ls; m = mn;
;     if (PV) { if (__any(alpha != 1.f)) {
; #pragma unroll
;         for (int i = 0; i < 16; ++i) { O[0][i] *= alpha; O[1][i] *= alpha; } } }
; }
.Lsel_mdone0:
	v_max3_f32 v0, v96, v97, v98
	v_max3_f32 v163, v99, v100, v101
	v_max3_f32 v0, v0, v102, v103
	v_max3_f32 v163, v163, v104, v105
	v_max3_f32 v0, v0, v106, v107
	v_max3_f32 v163, v163, v108, v109
	v_max3_f32 v0, v0, v110, v111
	v_max3_f32 v163, v163, v80, v81
	v_max3_f32 v0, v0, v82, v83
	v_max3_f32 v163, v163, v84, v85
	v_max3_f32 v0, v0, v86, v87
	v_max3_f32 v163, v163, v88, v89
	v_max3_f32 v0, v0, v90, v91
	v_max3_f32 v163, v163, v92, v93
	v_max3_f32 v0, v0, v94, v95
	v_max_f32_e32 v0, v0, v163
	v_mov_b32_e32 v163, v0
	s_nop 1
	v_permlane32_swap_b32_e32 v163, v0
	v_max_f32_e32 v0, v0, v163
	v_sub_f32_e32 v163, v0, v162
	v_cmp_lt_f32_e32 vcc, s87, v163
	s_cbranch_vccz .Lsel_skip0
	v_max_f32_e32 v163, v162, v0
	v_sub_f32_e32 v96, v96, v163
	v_sub_f32_e32 v97, v97, v163
	v_sub_f32_e32 v98, v98, v163
	v_sub_f32_e32 v99, v99, v163
	v_sub_f32_e32 v100, v100, v163
	v_sub_f32_e32 v101, v101, v163
	v_sub_f32_e32 v102, v102, v163
	v_sub_f32_e32 v103, v103, v163
	v_exp_f32_e32 v96, v96
	v_exp_f32_e32 v97, v97
	v_exp_f32_e32 v98, v98
	v_exp_f32_e32 v99, v99
	v_exp_f32_e32 v100, v100
	v_exp_f32_e32 v101, v101
	v_exp_f32_e32 v102, v102
	v_exp_f32_e32 v103, v103
	v_add_f32_e32 v14, v96, v98
	v_add_f32_e32 v15, v97, v99
	v_add_f32_e32 v14, v14, v100
	v_add_f32_e32 v15, v15, v101
	v_add_f32_e32 v14, v14, v102
	v_add_f32_e32 v15, v15, v103
	v_cvt_pk_bf16_f32 v96, v96, v97
	v_cvt_pk_bf16_f32 v97, v98, v99
	v_cvt_pk_bf16_f32 v98, v100, v101
	v_cvt_pk_bf16_f32 v99, v102, v103
	v_sub_f32_e32 v104, v104, v163
	v_sub_f32_e32 v105, v105, v163
	v_sub_f32_e32 v106, v106, v163
	v_sub_f32_e32 v107, v107, v163
	v_sub_f32_e32 v108, v108, v163
	v_sub_f32_e32 v109, v109, v163
	v_sub_f32_e32 v110, v110, v163
	v_sub_f32_e32 v111, v111, v163
	v_exp_f32_e32 v104, v104
	v_exp_f32_e32 v105, v105
	v_exp_f32_e32 v106, v106
	v_exp_f32_e32 v107, v107
	v_exp_f32_e32 v108, v108
	v_exp_f32_e32 v109, v109
	v_exp_f32_e32 v110, v110
	v_exp_f32_e32 v111, v111
	v_add_f32_e32 v14, v14, v104
	v_add_f32_e32 v15, v15, v105
	v_add_f32_e32 v14, v14, v106
	v_add_f32_e32 v15, v15, v107
	v_add_f32_e32 v14, v14, v108
	v_add_f32_e32 v15, v15, v109
	v_add_f32_e32 v14, v14, v110
	v_add_f32_e32 v15, v15, v111
	v_cvt_pk_bf16_f32 v104, v104, v105
	v_cvt_pk_bf16_f32 v105, v106, v107
	v_cvt_pk_bf16_f32 v106, v108, v109
	v_cvt_pk_bf16_f32 v107, v110, v111
	v_sub_f32_e32 v80, v80, v163
	v_sub_f32_e32 v81, v81, v163
	v_sub_f32_e32 v82, v82, v163
	v_sub_f32_e32 v83, v83, v163
	v_sub_f32_e32 v84, v84, v163
	v_sub_f32_e32 v85, v85, v163
	v_sub_f32_e32 v86, v86, v163
	v_sub_f32_e32 v87, v87, v163
	v_exp_f32_e32 v80, v80
	v_exp_f32_e32 v81, v81
	v_exp_f32_e32 v82, v82
	v_exp_f32_e32 v83, v83
	v_exp_f32_e32 v84, v84
	v_exp_f32_e32 v85, v85
	v_exp_f32_e32 v86, v86
	v_exp_f32_e32 v87, v87
	v_add_f32_e32 v14, v14, v80
	v_add_f32_e32 v15, v15, v81
	v_add_f32_e32 v14, v14, v82
	v_add_f32_e32 v15, v15, v83
	v_add_f32_e32 v14, v14, v84
	v_add_f32_e32 v15, v15, v85
	v_add_f32_e32 v14, v14, v86
	v_add_f32_e32 v15, v15, v87
	v_cvt_pk_bf16_f32 v80, v80, v81
	v_cvt_pk_bf16_f32 v81, v82, v83
	v_cvt_pk_bf16_f32 v82, v84, v85
	v_cvt_pk_bf16_f32 v83, v86, v87
	v_sub_f32_e32 v88, v88, v163
	v_sub_f32_e32 v89, v89, v163
	v_sub_f32_e32 v90, v90, v163
	v_sub_f32_e32 v91, v91, v163
	v_sub_f32_e32 v92, v92, v163
	v_sub_f32_e32 v93, v93, v163
	v_sub_f32_e32 v94, v94, v163
	v_sub_f32_e32 v95, v95, v163
	v_exp_f32_e32 v88, v88
	v_exp_f32_e32 v89, v89
	v_exp_f32_e32 v90, v90
	v_exp_f32_e32 v91, v91
	v_exp_f32_e32 v92, v92
	v_exp_f32_e32 v93, v93
	v_exp_f32_e32 v94, v94
	v_exp_f32_e32 v95, v95
	v_add_f32_e32 v14, v14, v88
	v_add_f32_e32 v15, v15, v89
	v_add_f32_e32 v14, v14, v90
	v_add_f32_e32 v15, v15, v91
	v_add_f32_e32 v14, v14, v92
	v_add_f32_e32 v15, v15, v93
	v_add_f32_e32 v14, v14, v94
	v_add_f32_e32 v15, v15, v95
	v_cvt_pk_bf16_f32 v88, v88, v89
	v_cvt_pk_bf16_f32 v89, v90, v91
	v_cvt_pk_bf16_f32 v90, v92, v93
	v_cvt_pk_bf16_f32 v91, v94, v95
	v_add_f32_e32 v14, v14, v15
	v_sub_f32_e32 v0, v162, v163
	v_mov_b32_e32 v15, v14
	v_exp_f32_e32 v0, v0
	s_nop 0
	v_permlane32_swap_b32_e32 v15, v14
	v_add_f32_e32 v14, v14, v15
	v_mov_b32_e32 v162, v163
	v_fmac_f32_e32 v14, v209, v0
	v_cmp_neq_f32_e32 vcc, 1.0, v0
	v_mov_b32_e32 v209, v14
	s_cbranch_vccz .Lsel_nors0
	s_nop 3
	v_mul_f32_e32 v48, v48, v0
	v_mul_f32_e32 v49, v49, v0
	v_mul_f32_e32 v50, v50, v0
	v_mul_f32_e32 v51, v51, v0
	v_mul_f32_e32 v52, v52, v0
	v_mul_f32_e32 v53, v53, v0
	v_mul_f32_e32 v54, v54, v0
	v_mul_f32_e32 v55, v55, v0
	v_mul_f32_e32 v56, v56, v0
	v_mul_f32_e32 v57, v57, v0
	v_mul_f32_e32 v58, v58, v0
	v_mul_f32_e32 v59, v59, v0
	v_mul_f32_e32 v60, v60, v0
	v_mul_f32_e32 v61, v61, v0
	v_mul_f32_e32 v62, v62, v0
	v_mul_f32_e32 v63, v63, v0
	v_mul_f32_e32 v64, v64, v0
	v_mul_f32_e32 v65, v65, v0
	v_mul_f32_e32 v66, v66, v0
	v_mul_f32_e32 v67, v67, v0
	v_mul_f32_e32 v68, v68, v0
	v_mul_f32_e32 v69, v69, v0
	v_mul_f32_e32 v70, v70, v0
	v_mul_f32_e32 v71, v71, v0
	v_mul_f32_e32 v72, v72, v0
	v_mul_f32_e32 v73, v73, v0
	v_mul_f32_e32 v74, v74, v0
	v_mul_f32_e32 v75, v75, v0
	v_mul_f32_e32 v76, v76, v0
	v_mul_f32_e32 v77, v77, v0
	v_mul_f32_e32 v78, v78, v0
	v_mul_f32_e32 v79, v79, v0
.Lsel_nors0:
	ds_read_b128 v[126:129], v161 offset:26624
	ds_read_b128 v[130:133], v161 offset:31232
	ds_read_b128 v[164:167], v161 offset:26656
	ds_read_b128 v[10:13], v161 offset:31264
	s_waitcnt lgkmcnt(3)
	v_mfma_f32_32x32x16_bf16 v[48:63], v[126:129], v[96:99], v[48:63]
	ds_read_b128 v[126:129], v161 offset:26688
	s_waitcnt lgkmcnt(3)
	v_mfma_f32_32x32x16_bf16 v[64:79], v[130:133], v[96:99], v[64:79]
	ds_read_b128 v[130:133], v161 offset:31296
	s_waitcnt lgkmcnt(3)
	v_mfma_f32_32x32x16_bf16 v[48:63], v[164:167], v[104:107], v[48:63]
	ds_read_b128 v[164:167], v161 offset:26720
	s_waitcnt lgkmcnt(3)
	v_mfma_f32_32x32x16_bf16 v[64:79], v[10:13], v[104:107], v[64:79]
	ds_read_b128 v[10:13], v161 offset:31328
	s_waitcnt lgkmcnt(3)
	v_mfma_f32_32x32x16_bf16 v[48:63], v[126:129], v[80:83], v[48:63]
	s_waitcnt lgkmcnt(2)
	v_mfma_f32_32x32x16_bf16 v[64:79], v[130:133], v[80:83], v[64:79]
	s_waitcnt lgkmcnt(1)
	v_mfma_f32_32x32x16_bf16 v[48:63], v[164:167], v[88:91], v[48:63]
	s_waitcnt lgkmcnt(0)
	v_mfma_f32_32x32x16_bf16 v[64:79], v[10:13], v[88:91], v[64:79]
.Lsel_skip0:
	s_cmp_lt_i32 s16, 0
	s_cbranch_scc1 .Lsel_last0
	s_waitcnt vmcnt(2)
	v_add_u32_e32 v135, v142, v143
	ds_write_b128 v141, v[116:119] offset:13312
	ds_write_b16 v135, v112 offset:35840
	ds_write_b16_d16_hi v135, v112 offset:35984
	ds_write_b16 v135, v113 offset:36128
	ds_write_b16_d16_hi v135, v113 offset:36272
	ds_write_b16 v135, v114 offset:36416
	ds_write_b16_d16_hi v135, v114 offset:36560
	ds_write_b16 v135, v115 offset:36704
	ds_write_b16_d16_hi v135, v115 offset:36848
	s_waitcnt lgkmcnt(0)
	s_barrier
	s_mov_b32 s43, s16
	s_mov_b32 s16, s17

.Lsel_nn1:
	s_cmp_lt_i32 s17, 0
	s_cselect_b32 s24, s43, s17
	v_add_u32_e32 v116, s24, v136
	v_add_u32_e32 v112, s24, v137
	v_lshlrev_b32_e32 v116, 12, v116
	v_lshlrev_b32_e32 v112, 12, v112
	v_mov_b32_e32 v117, v1
	v_mov_b32_e32 v113, v1
	v_lshl_add_u64 v[116:117], v[122:123], 0, v[116:117]
	v_lshl_add_u64 v[112:113], v[124:125], 0, v[112:113]
	global_load_dwordx4 v[116:119], v[116:117], off offset:2816
	global_load_dwordx4 v[112:115], v[112:113], off offset:3584
	ds_read_b128 v[126:129], v161 offset:13312
	ds_read_b128 v[130:133], v161 offset:17920
	ds_read_b128 v[164:167], v161 offset:13344
	ds_read_b128 v[10:13], v161 offset:17952
	s_waitcnt lgkmcnt(3)
	v_mfma_f32_32x32x16_bf16 v[96:111], v[126:129], v[144:147], 0
	ds_read_b128 v[126:129], v161 offset:13376
	s_waitcnt lgkmcnt(3)
	v_mfma_f32_32x32x16_bf16 v[80:95], v[130:133], v[144:147], 0
	ds_read_b128 v[130:133], v161 offset:17984
	s_waitcnt lgkmcnt(3)
	v_mfma_f32_32x32x16_bf16 v[96:111], v[164:167], v[148:151], v[96:111]
	ds_read_b128 v[164:167], v161 offset:13408
	s_waitcnt lgkmcnt(3)
	v_mfma_f32_32x32x16_bf16 v[80:95], v[10:13], v[148:151], v[80:95]
	ds_read_b128 v[10:13], v161 offset:18016
	s_waitcnt lgkmcnt(3)
	v_mfma_f32_32x32x16_bf16 v[96:111], v[126:129], v[152:155], v[96:111]
	s_waitcnt lgkmcnt(2)
	v_mfma_f32_32x32x16_bf16 v[80:95], v[130:133], v[152:155], v[80:95]
	s_waitcnt lgkmcnt(1)
	v_mfma_f32_32x32x16_bf16 v[96:111], v[164:167], v[156:159], v[96:111]
	s_waitcnt lgkmcnt(0)
	v_mfma_f32_32x32x16_bf16 v[80:95], v[10:13], v[156:159], v[80:95]
	v_add_u32_e32 v163, s43, v139
	v_sub_u32_e32 v163, v163, v205
	v_cvt_f32_i32_e32 v163, v163
	v_mul_f32_e32 v0, v186, v163
	s_lshr_b32 s24, s43, 6
	v_lshrrev_b64 v[14:15], s24, v[120:121]
	v_and_b32_e32 v14, 1, v14
	v_cmp_eq_u32_e32 vcc, 1, v14
	s_nop 1
	v_cndmask_b32_e32 v0, v225, v0, vcc
	s_nop 7
	v_fma_f32 v96, v96, s84, v0
	v_fmamk_f32 v15, v186, 0x3f800000, v0
	v_fma_f32 v97, v97, s84, v15
	v_fmamk_f32 v14, v186, 0x40000000, v0
	v_fma_f32 v98, v98, s84, v14
	v_fmamk_f32 v15, v186, 0x40400000, v0
	v_fma_f32 v99, v99, s84, v15
	v_fmamk_f32 v14, v186, 0x41000000, v0
	v_fma_f32 v100, v100, s84, v14
	v_fmamk_f32 v15, v186, 0x41100000, v0
	v_fma_f32 v101, v101, s84, v15
	v_fmamk_f32 v14, v186, 0x41200000, v0
	v_fma_f32 v102, v102, s84, v14
	v_fmamk_f32 v15, v186, 0x41300000, v0
	v_fma_f32 v103, v103, s84, v15
	v_fmamk_f32 v14, v186, 0x41800000, v0
	v_fma_f32 v104, v104, s84, v14
	v_fmamk_f32 v15, v186, 0x41880000, v0
	v_fma_f32 v105, v105, s84, v15
	v_fmamk_f32 v14, v186, 0x41900000, v0
	v_fma_f32 v106, v106, s84, v14
	v_fmamk_f32 v15, v186, 0x41980000, v0
	v_fma_f32 v107, v107, s84, v15
	v_fmamk_f32 v14, v186, 0x41c00000, v0
	v_fma_f32 v108, v108, s84, v14
	v_fmamk_f32 v15, v186, 0x41c80000, v0
	v_fma_f32 v109, v109, s84, v15
	v_fmamk_f32 v14, v186, 0x41d00000, v0
	v_fma_f32 v110, v110, s84, v14
	v_fmamk_f32 v15, v186, 0x41d80000, v0
	v_fma_f32 v111, v111, s84, v15
	v_fmamk_f32 v14, v186, 0x42000000, v0
	v_fma_f32 v80, v80, s84, v14
	v_fmamk_f32 v15, v186, 0x42040000, v0
	v_fma_f32 v81, v81, s84, v15
	v_fmamk_f32 v14, v186, 0x42080000, v0
	v_fma_f32 v82, v82, s84, v14
	v_fmamk_f32 v15, v186, 0x420c0000, v0
	v_fma_f32 v83, v83, s84, v15
	v_fmamk_f32 v14, v186, 0x42200000, v0
	v_fma_f32 v84, v84, s84, v14
	v_fmamk_f32 v15, v186, 0x42240000, v0
	v_fma_f32 v85, v85, s84, v15
	v_fmamk_f32 v14, v186, 0x42280000, v0
	v_fma_f32 v86, v86, s84, v14
	v_fmamk_f32 v15, v186, 0x422c0000, v0
	v_fma_f32 v87, v87, s84, v15
	v_fmamk_f32 v14, v186, 0x42400000, v0
	v_fma_f32 v88, v88, s84, v14
	v_fmamk_f32 v15, v186, 0x42440000, v0
	v_fma_f32 v89, v89, s84, v15
	v_fmamk_f32 v14, v186, 0x42480000, v0
	v_fma_f32 v90, v90, s84, v14
	v_fmamk_f32 v15, v186, 0x424c0000, v0
	v_fma_f32 v91, v91, s84, v15
	v_fmamk_f32 v14, v186, 0x42600000, v0
	v_fma_f32 v92, v92, s84, v14
	v_fmamk_f32 v15, v186, 0x42640000, v0
	v_fma_f32 v93, v93, s84, v15
	v_fmamk_f32 v14, v186, 0x42680000, v0
	v_fma_f32 v94, v94, s84, v14
	v_fmamk_f32 v15, v186, 0x426c0000, v0
	v_fma_f32 v95, v95, s84, v15
	s_add_i32 s24, s43, 63
	s_cmp_gt_i32 s24, s52
	s_cbranch_scc1 .Lsel_mask1

.Lsel_nors1:
	ds_read_b128 v[126:129], v161 offset:35840
	ds_read_b128 v[130:133], v161 offset:40448
	ds_read_b128 v[164:167], v161 offset:35872
	ds_read_b128 v[10:13], v161 offset:40480
	s_waitcnt lgkmcnt(3)
	v_mfma_f32_32x32x16_bf16 v[48:63], v[126:129], v[96:99], v[48:63]
	ds_read_b128 v[126:129], v161 offset:35904
	s_waitcnt lgkmcnt(3)
	v_mfma_f32_32x32x16_bf16 v[64:79], v[130:133], v[96:99], v[64:79]
	ds_read_b128 v[130:133], v161 offset:40512
	s_waitcnt lgkmcnt(3)
	v_mfma_f32_32x32x16_bf16 v[48:63], v[164:167], v[104:107], v[48:63]
	ds_read_b128 v[164:167], v161 offset:35936
	s_waitcnt lgkmcnt(3)
	v_mfma_f32_32x32x16_bf16 v[64:79], v[10:13], v[104:107], v[64:79]
	ds_read_b128 v[10:13], v161 offset:40544
	s_waitcnt lgkmcnt(3)
	v_mfma_f32_32x32x16_bf16 v[48:63], v[126:129], v[80:83], v[48:63]
	s_waitcnt lgkmcnt(2)
	v_mfma_f32_32x32x16_bf16 v[64:79], v[130:133], v[80:83], v[64:79]
	s_waitcnt lgkmcnt(1)
	v_mfma_f32_32x32x16_bf16 v[48:63], v[164:167], v[88:91], v[48:63]
	s_waitcnt lgkmcnt(0)
	v_mfma_f32_32x32x16_bf16 v[64:79], v[10:13], v[88:91], v[64:79]
.Lsel_skip1:
	s_cmp_lt_i32 s16, 0
	s_cbranch_scc1 .Lsel_last1
	s_waitcnt vmcnt(2)
	v_add_u32_e32 v135, v142, v143
	ds_write_b128 v141, v[6:9] offset:0
	ds_write_b16 v135, v2 offset:26624
	ds_write_b16_d16_hi v135, v2 offset:26768
	ds_write_b16 v135, v3 offset:26912
	ds_write_b16_d16_hi v135, v3 offset:27056
	ds_write_b16 v135, v4 offset:27200
	ds_write_b16_d16_hi v135, v4 offset:27344
	ds_write_b16 v135, v5 offset:27488
	ds_write_b16_d16_hi v135, v5 offset:27632
	s_waitcnt lgkmcnt(0)
	s_barrier
	s_mov_b32 s43, s16
	s_mov_b32 s16, s17
	s_branch .Lsel_step0
.Lsel_mask0:
	v_subrev_u32_e32 v163, s43, v205
	v_sub_u32_e32 v163, v163, v139
	v_cmp_le_i32_e64 s[24:25], 0, v163
	v_cmp_le_i32_e64 s[46:47], 1, v163
	v_cmp_le_i32_e64 s[50:51], 2, v163
	v_cmp_le_i32_e64 s[54:55], 3, v163
	v_cndmask_b32_e64 v96, v225, v96, s[24:25]
	v_cndmask_b32_e64 v97, v225, v97, s[46:47]
	v_cndmask_b32_e64 v98, v225, v98, s[50:51]
	v_cndmask_b32_e64 v99, v225, v99, s[54:55]
	v_cmp_le_i32_e64 s[24:25], 8, v163
	v_cmp_le_i32_e64 s[46:47], 9, v163
	v_cmp_le_i32_e64 s[50:51], 10, v163
	v_cmp_le_i32_e64 s[54:55], 11, v163
	v_cndmask_b32_e64 v100, v225, v100, s[24:25]
	v_cndmask_b32_e64 v101, v225, v101, s[46:47]
	v_cndmask_b32_e64 v102, v225, v102, s[50:51]
	v_cndmask_b32_e64 v103, v225, v103, s[54:55]
	v_cmp_le_i32_e64 s[24:25], 16, v163
	v_cmp_le_i32_e64 s[46:47], 17, v163
	v_cmp_le_i32_e64 s[50:51], 18, v163
	v_cmp_le_i32_e64 s[54:55], 19, v163
	v_cndmask_b32_e64 v104, v225, v104, s[24:25]
	v_cndmask_b32_e64 v105, v225, v105, s[46:47]
	v_cndmask_b32_e64 v106, v225, v106, s[50:51]
	v_cndmask_b32_e64 v107, v225, v107, s[54:55]
	v_cmp_le_i32_e64 s[24:25], 24, v163
	v_cmp_le_i32_e64 s[46:47], 25, v163
	v_cmp_le_i32_e64 s[50:51], 26, v163
	v_cmp_le_i32_e64 s[54:55], 27, v163
	v_cndmask_b32_e64 v108, v225, v108, s[24:25]
	v_cndmask_b32_e64 v109, v225, v109, s[46:47]
	v_cndmask_b32_e64 v110, v225, v110, s[50:51]
	v_cndmask_b32_e64 v111, v225, v111, s[54:55]
	v_cmp_le_i32_e64 s[24:25], 32, v163
	v_cmp_le_i32_e64 s[46:47], 33, v163
	v_cmp_le_i32_e64 s[50:51], 34, v163
	v_cmp_le_i32_e64 s[54:55], 35, v163
	v_cndmask_b32_e64 v80, v225, v80, s[24:25]
	v_cndmask_b32_e64 v81, v225, v81, s[46:47]
	v_cndmask_b32_e64 v82, v225, v82, s[50:51]
	v_cndmask_b32_e64 v83, v225, v83, s[54:55]
	v_cmp_le_i32_e64 s[24:25], 40, v163
	v_cmp_le_i32_e64 s[46:47], 41, v163
	v_cmp_le_i32_e64 s[50:51], 42, v163
	v_cmp_le_i32_e64 s[54:55], 43, v163
	v_cndmask_b32_e64 v84, v225, v84, s[24:25]
	v_cndmask_b32_e64 v85, v225, v85, s[46:47]
	v_cndmask_b32_e64 v86, v225, v86, s[50:51]
	v_cndmask_b32_e64 v87, v225, v87, s[54:55]
	v_cmp_le_i32_e64 s[24:25], 48, v163
	v_cmp_le_i32_e64 s[46:47], 49, v163
	v_cmp_le_i32_e64 s[50:51], 50, v163
	v_cmp_le_i32_e64 s[54:55], 51, v163
	v_cndmask_b32_e64 v88, v225, v88, s[24:25]
	v_cndmask_b32_e64 v89, v225, v89, s[46:47]
	v_cndmask_b32_e64 v90, v225, v90, s[50:51]
	v_cndmask_b32_e64 v91, v225, v91, s[54:55]
	v_cmp_le_i32_e64 s[24:25], 56, v163
	v_cmp_le_i32_e64 s[46:47], 57, v163
	v_cmp_le_i32_e64 s[50:51], 58, v163
	v_cmp_le_i32_e64 s[54:55], 59, v163
	v_cndmask_b32_e64 v92, v225, v92, s[24:25]
	v_cndmask_b32_e64 v93, v225, v93, s[46:47]
	v_cndmask_b32_e64 v94, v225, v94, s[50:51]
	v_cndmask_b32_e64 v95, v225, v95, s[54:55]
	s_branch .Lsel_mdone0

; DI void unit_nsa(Frame& F, int b, int g, int qt, int tid) {
;     ...
;     { const float sc = g1 / l;
; #pragma unroll
;       for (int i = 0; i < 16; ++i) { Of[0][i] += sc * O[0][i]; Of[1][i] += sc * O[1][i]; } }
.Lsel_last0:
.Lsel_last1:
	s_waitcnt lgkmcnt(0)
	s_barrier
	s_nop 7
	s_nop 3

.LBB0_1456:
	v_readfirstlane_b32 s42, v213
	v_add_u32_e32 v170, v235, v236
	s_cmp_lt_i32 s23, 0
	s_cselect_b32 s24, s96, s23
	v_add_u32_e32 v10, s24, v210
	v_add_u32_e32 v12, s24, v211
	v_ashrrev_i32_e32 v11, 31, v10
	v_ashrrev_i32_e32 v13, 31, v12
	v_lshlrev_b64 v[10:11], 12, v[10:11]
	v_lshlrev_b64 v[12:13], 12, v[12:13]
	v_lshl_add_u64 v[192:193], v[188:189], 0, v[10:11]
	v_lshl_add_u64 v[194:195], v[190:191], 0, v[12:13]
.Lwin_step0:
	s_sub_i32 s24, s23, 64
	s_cmp_ge_i32 s24, s22
	s_cselect_b32 s24, s24, -1
	s_cmp_gt_i32 s23, -1
	s_cselect_b32 s25, s24, -1
	s_cmp_gt_i32 s25, -1
	s_cselect_b32 s16, 0xfffc0000, 0
	s_cselect_b32 s17, -1, 0
	v_lshl_add_u64 v[192:193], v[192:193], 0, s[16:17]
	v_lshl_add_u64 v[194:195], v[194:195], 0, s[16:17]
	global_load_dwordx4 v[6:9], v[192:193], off offset:3072
	global_load_dwordx4 v[2:5], v[194:195], off offset:3840
	ds_read_b128 v[240:243], v238 offset:0
	ds_read_b128 v[244:247], v238 offset:4608
	ds_read_b128 v[248:251], v238 offset:32
	ds_read_b128 v[196:199], v238 offset:4640
	s_waitcnt lgkmcnt(3)
	v_mfma_f32_32x32x16_bf16 v[112:127], v[240:243], v[144:147], 0
	ds_read_b128 v[240:243], v238 offset:64
	s_waitcnt lgkmcnt(3)
	v_mfma_f32_32x32x16_bf16 v[128:143], v[244:247], v[144:147], 0
	ds_read_b128 v[244:247], v238 offset:4672
	s_waitcnt lgkmcnt(3)
	v_mfma_f32_32x32x16_bf16 v[112:127], v[248:251], v[148:151], v[112:127]
	ds_read_b128 v[248:251], v238 offset:96
	s_waitcnt lgkmcnt(3)
	v_mfma_f32_32x32x16_bf16 v[128:143], v[196:199], v[148:151], v[128:143]
	ds_read_b128 v[196:199], v238 offset:4704
	s_waitcnt lgkmcnt(3)
	v_mfma_f32_32x32x16_bf16 v[112:127], v[240:243], v[152:155], v[112:127]
	s_waitcnt lgkmcnt(2)
	v_mfma_f32_32x32x16_bf16 v[128:143], v[244:247], v[152:155], v[128:143]
	s_waitcnt lgkmcnt(1)
	v_mfma_f32_32x32x16_bf16 v[112:127], v[248:251], v[156:159], v[112:127]
	s_waitcnt lgkmcnt(0)
	v_mfma_f32_32x32x16_bf16 v[128:143], v[196:199], v[156:159], v[128:143]
	v_add_u32_e32 v11, s96, v233
	v_sub_u32_e32 v11, v11, v205
	v_cvt_f32_i32_e32 v11, v11
	v_mul_f32_e32 v10, v186, v11
	s_nop 7
	v_fma_f32 v112, v112, s84, v10
	v_fmamk_f32 v13, v186, 0x3f800000, v10
	v_fma_f32 v113, v113, s84, v13
	v_fmamk_f32 v12, v186, 0x40000000, v10
	v_fma_f32 v114, v114, s84, v12
	v_fmamk_f32 v13, v186, 0x40400000, v10
	v_fma_f32 v115, v115, s84, v13
	v_fmamk_f32 v12, v186, 0x41000000, v10
	v_fma_f32 v116, v116, s84, v12
	v_fmamk_f32 v13, v186, 0x41100000, v10
	v_fma_f32 v117, v117, s84, v13
	v_fmamk_f32 v12, v186, 0x41200000, v10
	v_fma_f32 v118, v118, s84, v12
	v_fmamk_f32 v13, v186, 0x41300000, v10
	v_fma_f32 v119, v119, s84, v13
	v_fmamk_f32 v12, v186, 0x41800000, v10
	v_fma_f32 v120, v120, s84, v12
	v_fmamk_f32 v13, v186, 0x41880000, v10
	v_fma_f32 v121, v121, s84, v13
	v_fmamk_f32 v12, v186, 0x41900000, v10
	v_fma_f32 v122, v122, s84, v12
	v_fmamk_f32 v13, v186, 0x41980000, v10
	v_fma_f32 v123, v123, s84, v13
	v_fmamk_f32 v12, v186, 0x41c00000, v10
	v_fma_f32 v124, v124, s84, v12
	v_fmamk_f32 v13, v186, 0x41c80000, v10
	v_fma_f32 v125, v125, s84, v13
	v_fmamk_f32 v12, v186, 0x41d00000, v10
	v_fma_f32 v126, v126, s84, v12
	v_fmamk_f32 v13, v186, 0x41d80000, v10
	v_fma_f32 v127, v127, s84, v13
	v_fmamk_f32 v12, v186, 0x42000000, v10
	v_fma_f32 v128, v128, s84, v12
	v_fmamk_f32 v13, v186, 0x42040000, v10
	v_fma_f32 v129, v129, s84, v13
	v_fmamk_f32 v12, v186, 0x42080000, v10
	v_fma_f32 v130, v130, s84, v12
	v_fmamk_f32 v13, v186, 0x420c0000, v10
	v_fma_f32 v131, v131, s84, v13
	v_fmamk_f32 v12, v186, 0x42200000, v10
	v_fma_f32 v132, v132, s84, v12
	v_fmamk_f32 v13, v186, 0x42240000, v10
	v_fma_f32 v133, v133, s84, v13
	v_fmamk_f32 v12, v186, 0x42280000, v10
	v_fma_f32 v134, v134, s84, v12
	v_fmamk_f32 v13, v186, 0x422c0000, v10
	v_fma_f32 v135, v135, s84, v13
	v_fmamk_f32 v12, v186, 0x42400000, v10
	v_fma_f32 v136, v136, s84, v12
	v_fmamk_f32 v13, v186, 0x42440000, v10
	v_fma_f32 v137, v137, s84, v13
	v_fmamk_f32 v12, v186, 0x42480000, v10
	v_fma_f32 v138, v138, s84, v12
	v_fmamk_f32 v13, v186, 0x424c0000, v10
	v_fma_f32 v139, v139, s84, v13
	v_fmamk_f32 v12, v186, 0x42600000, v10
	v_fma_f32 v140, v140, s84, v12
	v_fmamk_f32 v13, v186, 0x42640000, v10
	v_fma_f32 v141, v141, s84, v13
	v_fmamk_f32 v12, v186, 0x42680000, v10
	v_fma_f32 v142, v142, s84, v12
	v_fmamk_f32 v13, v186, 0x426c0000, v10
	v_fma_f32 v143, v143, s84, v13
	s_add_i32 s24, s96, 63
	s_cmp_gt_i32 s24, s42
	s_cbranch_scc1 .Lwin_mask0
	s_sub_i32 s24, s42, s96
	s_add_i32 s24, s24, 31
	s_cmpk_gt_i32 s24, 0x1ff
	s_cbranch_scc1 .Lwin_mask0
; template <bool PV> DI void online_step_mx(f32x16& x0, f32x16& x1, float mx, float& m, float& l, f32x16 (&O)[2]) {
;     const float mn = fmaxf(m, mx), alpha = __builtin_amdgcn_exp2f(m - mn);
;     float ls = 0.f;
; #pragma unroll
;     for (int i = 0; i < 16; ++i) { x0[i] = __builtin_amdgcn_exp2f(x0[i] - mn); x1[i] = __builtin_amdgcn_exp2f(x1[i] - mn); ls += x0[i] + x1[i]; }
;     ls += __shfl_xor(ls, 32);
;     l = l * alpha + ls; m = mn;
;     if (PV) { if (__any(alpha != 1.f)) {
; #pragma unroll
;         for (int i = 0; i < 16; ++i) { O[0][i] *= alpha; O[1][i] *= alpha; } } }
; }
.Lwin_mdone0:
	v_max3_f32 v10, v112, v113, v114
	v_max3_f32 v11, v115, v116, v117
	v_max3_f32 v10, v10, v118, v119
	v_max3_f32 v11, v11, v120, v121
	v_max3_f32 v10, v10, v122, v123
	v_max3_f32 v11, v11, v124, v125
	v_max3_f32 v10, v10, v126, v127
	v_max3_f32 v11, v11, v128, v129
	v_max3_f32 v10, v10, v130, v131
	v_max3_f32 v11, v11, v132, v133
	v_max3_f32 v10, v10, v134, v135
	v_max3_f32 v11, v11, v136, v137
	v_max3_f32 v10, v10, v138, v139
	v_max3_f32 v11, v11, v140, v141
	v_max3_f32 v10, v10, v142, v143
	v_max_f32_e32 v10, v10, v11
	v_mov_b32_e32 v11, v10
	s_nop 1
	v_permlane32_swap_b32_e32 v11, v10
	v_max_f32_e32 v10, v10, v11
	v_sub_f32_e32 v11, v10, v239
	v_cmp_lt_f32_e32 vcc, s87, v11
	s_cbranch_vccz .Lwin_skip0
	v_max_f32_e32 v11, v239, v10
	v_sub_f32_e32 v112, v112, v11
	v_sub_f32_e32 v113, v113, v11
	v_sub_f32_e32 v114, v114, v11
	v_sub_f32_e32 v115, v115, v11
	v_sub_f32_e32 v116, v116, v11
	v_sub_f32_e32 v117, v117, v11
	v_sub_f32_e32 v118, v118, v11
	v_sub_f32_e32 v119, v119, v11
	v_exp_f32_e32 v112, v112
	v_exp_f32_e32 v113, v113
	v_exp_f32_e32 v114, v114
	v_exp_f32_e32 v115, v115
	v_exp_f32_e32 v116, v116
	v_exp_f32_e32 v117, v117
	v_exp_f32_e32 v118, v118
	v_exp_f32_e32 v119, v119
	v_add_f32_e32 v12, v112, v114
	v_add_f32_e32 v13, v113, v115
	v_add_f32_e32 v12, v12, v116
	v_add_f32_e32 v13, v13, v117
	v_add_f32_e32 v12, v12, v118
	v_add_f32_e32 v13, v13, v119
	v_cvt_pk_bf16_f32 v112, v112, v113
	v_cvt_pk_bf16_f32 v113, v114, v115
	v_cvt_pk_bf16_f32 v114, v116, v117
	v_cvt_pk_bf16_f32 v115, v118, v119
	v_sub_f32_e32 v120, v120, v11
	v_sub_f32_e32 v121, v121, v11
	v_sub_f32_e32 v122, v122, v11
	v_sub_f32_e32 v123, v123, v11
	v_sub_f32_e32 v124, v124, v11
	v_sub_f32_e32 v125, v125, v11
	v_sub_f32_e32 v126, v126, v11
	v_sub_f32_e32 v127, v127, v11
	v_exp_f32_e32 v120, v120
	v_exp_f32_e32 v121, v121
	v_exp_f32_e32 v122, v122
	v_exp_f32_e32 v123, v123
	v_exp_f32_e32 v124, v124
	v_exp_f32_e32 v125, v125
	v_exp_f32_e32 v126, v126
	v_exp_f32_e32 v127, v127
	v_add_f32_e32 v12, v12, v120
	v_add_f32_e32 v13, v13, v121
	v_add_f32_e32 v12, v12, v122
	v_add_f32_e32 v13, v13, v123
	v_add_f32_e32 v12, v12, v124
	v_add_f32_e32 v13, v13, v125
	v_add_f32_e32 v12, v12, v126
	v_add_f32_e32 v13, v13, v127
	v_cvt_pk_bf16_f32 v120, v120, v121
	v_cvt_pk_bf16_f32 v121, v122, v123
	v_cvt_pk_bf16_f32 v122, v124, v125
	v_cvt_pk_bf16_f32 v123, v126, v127
	v_sub_f32_e32 v128, v128, v11
	v_sub_f32_e32 v129, v129, v11
	v_sub_f32_e32 v130, v130, v11
	v_sub_f32_e32 v131, v131, v11
	v_sub_f32_e32 v132, v132, v11
	v_sub_f32_e32 v133, v133, v11
	v_sub_f32_e32 v134, v134, v11
	v_sub_f32_e32 v135, v135, v11
	v_exp_f32_e32 v128, v128
	v_exp_f32_e32 v129, v129
	v_exp_f32_e32 v130, v130
	v_exp_f32_e32 v131, v131
	v_exp_f32_e32 v132, v132
	v_exp_f32_e32 v133, v133
	v_exp_f32_e32 v134, v134
	v_exp_f32_e32 v135, v135
	v_add_f32_e32 v12, v12, v128
	v_add_f32_e32 v13, v13, v129
	v_add_f32_e32 v12, v12, v130
	v_add_f32_e32 v13, v13, v131
	v_add_f32_e32 v12, v12, v132
	v_add_f32_e32 v13, v13, v133
	v_add_f32_e32 v12, v12, v134
	v_add_f32_e32 v13, v13, v135
	v_cvt_pk_bf16_f32 v128, v128, v129
	v_cvt_pk_bf16_f32 v129, v130, v131
	v_cvt_pk_bf16_f32 v130, v132, v133
	v_cvt_pk_bf16_f32 v131, v134, v135
	v_sub_f32_e32 v136, v136, v11
	v_sub_f32_e32 v137, v137, v11
	v_sub_f32_e32 v138, v138, v11
	v_sub_f32_e32 v139, v139, v11
	v_sub_f32_e32 v140, v140, v11
	v_sub_f32_e32 v141, v141, v11
	v_sub_f32_e32 v142, v142, v11
	v_sub_f32_e32 v143, v143, v11
	v_exp_f32_e32 v136, v136
	v_exp_f32_e32 v137, v137
	v_exp_f32_e32 v138, v138
	v_exp_f32_e32 v139, v139
	v_exp_f32_e32 v140, v140
	v_exp_f32_e32 v141, v141
	v_exp_f32_e32 v142, v142
	v_exp_f32_e32 v143, v143
	v_add_f32_e32 v12, v12, v136
	v_add_f32_e32 v13, v13, v137
	v_add_f32_e32 v12, v12, v138
	v_add_f32_e32 v13, v13, v139
	v_add_f32_e32 v12, v12, v140
	v_add_f32_e32 v13, v13, v141
	v_add_f32_e32 v12, v12, v142
	v_add_f32_e32 v13, v13, v143
	v_cvt_pk_bf16_f32 v136, v136, v137
	v_cvt_pk_bf16_f32 v137, v138, v139
	v_cvt_pk_bf16_f32 v138, v140, v141
	v_cvt_pk_bf16_f32 v139, v142, v143
	v_add_f32_e32 v12, v12, v13
	v_sub_f32_e32 v10, v239, v11
	v_mov_b32_e32 v13, v12
	v_exp_f32_e32 v10, v10
	s_nop 0
	v_permlane32_swap_b32_e32 v13, v12
	v_add_f32_e32 v12, v12, v13
	v_mov_b32_e32 v239, v11
	v_fmac_f32_e32 v12, v212, v10
	v_cmp_neq_f32_e32 vcc, 1.0, v10
	v_mov_b32_e32 v212, v12
	s_cbranch_vccz .Lwin_nors0
	s_nop 3
	v_mul_f32_e32 v80, v80, v10
	v_mul_f32_e32 v81, v81, v10
	v_mul_f32_e32 v82, v82, v10
	v_mul_f32_e32 v83, v83, v10
	v_mul_f32_e32 v84, v84, v10
	v_mul_f32_e32 v85, v85, v10
	v_mul_f32_e32 v86, v86, v10
	v_mul_f32_e32 v87, v87, v10
	v_mul_f32_e32 v88, v88, v10
	v_mul_f32_e32 v89, v89, v10
	v_mul_f32_e32 v90, v90, v10
	v_mul_f32_e32 v91, v91, v10
	v_mul_f32_e32 v92, v92, v10
	v_mul_f32_e32 v93, v93, v10
	v_mul_f32_e32 v94, v94, v10
	v_mul_f32_e32 v95, v95, v10
	v_mul_f32_e32 v96, v96, v10
	v_mul_f32_e32 v97, v97, v10
	v_mul_f32_e32 v98, v98, v10
	v_mul_f32_e32 v99, v99, v10
	v_mul_f32_e32 v100, v100, v10
	v_mul_f32_e32 v101, v101, v10
	v_mul_f32_e32 v102, v102, v10
	v_mul_f32_e32 v103, v103, v10
	v_mul_f32_e32 v104, v104, v10
	v_mul_f32_e32 v105, v105, v10
	v_mul_f32_e32 v106, v106, v10
	v_mul_f32_e32 v107, v107, v10
	v_mul_f32_e32 v108, v108, v10
	v_mul_f32_e32 v109, v109, v10
	v_mul_f32_e32 v110, v110, v10
	v_mul_f32_e32 v111, v111, v10
; #define MFMA32(a, b, c) __builtin_amdgcn_mfma_f32_32x32x16_bf16((a), (b), (c), 0, 0, 0)
;     DI float* h() const { return (float*)(__attribute__((address_space(1))) float*)kp->out; }
; DI void pv_tile(lbf Vt, const f32x16& p0, const f32x16& p1, f32x16 (&O)[2], int r, int h) {
;     bf16x8 va0, va1, vb0, vb1;
;     pv_load(Vt, 0, r, h, va0, va1);
; #pragma unroll
;     for (int g = 0; g < 4; g += 2) {
;         pv_load(Vt, g + 1, r, h, vb0, vb1);
;         const bf16x8 pa = pack8(g >> 1 ? p1 : p0, 0);
;         __builtin_amdgcn_sched_barrier(0);
;         O[0] = MFMA32(va0, pa, O[0]); O[1] = MFMA32(va1, pa, O[1]);
;         __builtin_amdgcn_sched_barrier(0);
;         if (g + 2 < 4) pv_load(Vt, g + 2, r, h, va0, va1);
;         const bf16x8 pb = pack8(g >> 1 ? p1 : p0, 1);
;         __builtin_amdgcn_sched_barrier(0);
;         O[0] = MFMA32(vb0, pb, O[0]); O[1] = MFMA32(vb1, pb, O[1]);
;         __builtin_amdgcn_sched_barrier(0);
;     }
; }
.Lwin_nors0:
	ds_read_b128 v[240:243], v238 offset:26624
	ds_read_b128 v[244:247], v238 offset:31232
	ds_read_b128 v[248:251], v238 offset:26656
	ds_read_b128 v[196:199], v238 offset:31264
	s_waitcnt lgkmcnt(3)
	v_mfma_f32_32x32x16_bf16 v[80:95], v[240:243], v[112:115], v[80:95]
	ds_read_b128 v[240:243], v238 offset:26688
	s_waitcnt lgkmcnt(3)
	v_mfma_f32_32x32x16_bf16 v[96:111], v[244:247], v[112:115], v[96:111]
	ds_read_b128 v[244:247], v238 offset:31296
	s_waitcnt lgkmcnt(3)
	v_mfma_f32_32x32x16_bf16 v[80:95], v[248:251], v[120:123], v[80:95]
	ds_read_b128 v[248:251], v238 offset:26720
	s_waitcnt lgkmcnt(3)
	v_mfma_f32_32x32x16_bf16 v[96:111], v[196:199], v[120:123], v[96:111]
	ds_read_b128 v[196:199], v238 offset:31328
	s_waitcnt lgkmcnt(3)
	v_mfma_f32_32x32x16_bf16 v[80:95], v[240:243], v[128:131], v[80:95]
	s_waitcnt lgkmcnt(2)
	v_mfma_f32_32x32x16_bf16 v[96:111], v[244:247], v[128:131], v[96:111]
	s_waitcnt lgkmcnt(1)
	v_mfma_f32_32x32x16_bf16 v[80:95], v[248:251], v[136:139], v[80:95]
	s_waitcnt lgkmcnt(0)
	v_mfma_f32_32x32x16_bf16 v[96:111], v[196:199], v[136:139], v[96:111]
.Lwin_skip0:
	s_cmp_lt_i32 s23, 0
	s_cbranch_scc1 .Lwin_last0
	s_waitcnt vmcnt(2)
	ds_write_b128 v234, v[164:167] offset:13312
	ds_write_b16 v170, v160 offset:35840
	ds_write_b16_d16_hi v170, v160 offset:35984
	ds_write_b16 v170, v161 offset:36128
	ds_write_b16_d16_hi v170, v161 offset:36272
	ds_write_b16 v170, v162 offset:36416
	ds_write_b16_d16_hi v170, v162 offset:36560
	ds_write_b16 v170, v163 offset:36704
	ds_write_b16_d16_hi v170, v163 offset:36848
	s_waitcnt lgkmcnt(0)
	s_barrier
	s_mov_b32 s96, s23
	s_mov_b32 s23, s25
.Lwin_step1:
	s_sub_i32 s24, s23, 64
	s_cmp_ge_i32 s24, s22
	s_cselect_b32 s24, s24, -1
	s_cmp_gt_i32 s23, -1
	s_cselect_b32 s25, s24, -1
	s_cmp_gt_i32 s25, -1
	s_cselect_b32 s16, 0xfffc0000, 0
	s_cselect_b32 s17, -1, 0
	v_lshl_add_u64 v[192:193], v[192:193], 0, s[16:17]
	v_lshl_add_u64 v[194:195], v[194:195], 0, s[16:17]
	global_load_dwordx4 v[164:167], v[192:193], off offset:3072
	global_load_dwordx4 v[160:163], v[194:195], off offset:3840
	ds_read_b128 v[240:243], v238 offset:13312
	ds_read_b128 v[244:247], v238 offset:17920
	ds_read_b128 v[248:251], v238 offset:13344
	ds_read_b128 v[196:199], v238 offset:17952
	s_waitcnt lgkmcnt(3)
	v_mfma_f32_32x32x16_bf16 v[112:127], v[240:243], v[144:147], 0
	ds_read_b128 v[240:243], v238 offset:13376
	s_waitcnt lgkmcnt(3)
	v_mfma_f32_32x32x16_bf16 v[128:143], v[244:247], v[144:147], 0
	ds_read_b128 v[244:247], v238 offset:17984
	s_waitcnt lgkmcnt(3)
	v_mfma_f32_32x32x16_bf16 v[112:127], v[248:251], v[148:151], v[112:127]
	ds_read_b128 v[248:251], v238 offset:13408
	s_waitcnt lgkmcnt(3)
	v_mfma_f32_32x32x16_bf16 v[128:143], v[196:199], v[148:151], v[128:143]
	ds_read_b128 v[196:199], v238 offset:18016
	s_waitcnt lgkmcnt(3)
	v_mfma_f32_32x32x16_bf16 v[112:127], v[240:243], v[152:155], v[112:127]
	s_waitcnt lgkmcnt(2)
	v_mfma_f32_32x32x16_bf16 v[128:143], v[244:247], v[152:155], v[128:143]
	s_waitcnt lgkmcnt(1)
	v_mfma_f32_32x32x16_bf16 v[112:127], v[248:251], v[156:159], v[112:127]
	s_waitcnt lgkmcnt(0)
	v_mfma_f32_32x32x16_bf16 v[128:143], v[196:199], v[156:159], v[128:143]
	v_add_u32_e32 v11, s96, v233
	v_sub_u32_e32 v11, v11, v205
	v_cvt_f32_i32_e32 v11, v11
	v_mul_f32_e32 v10, v186, v11
	s_nop 7
	v_fma_f32 v112, v112, s84, v10
	v_fmamk_f32 v13, v186, 0x3f800000, v10
	v_fma_f32 v113, v113, s84, v13
	v_fmamk_f32 v12, v186, 0x40000000, v10
	v_fma_f32 v114, v114, s84, v12
	v_fmamk_f32 v13, v186, 0x40400000, v10
	v_fma_f32 v115, v115, s84, v13
	v_fmamk_f32 v12, v186, 0x41000000, v10
	v_fma_f32 v116, v116, s84, v12
	v_fmamk_f32 v13, v186, 0x41100000, v10
	v_fma_f32 v117, v117, s84, v13
	v_fmamk_f32 v12, v186, 0x41200000, v10
	v_fma_f32 v118, v118, s84, v12
	v_fmamk_f32 v13, v186, 0x41300000, v10
	v_fma_f32 v119, v119, s84, v13
	v_fmamk_f32 v12, v186, 0x41800000, v10
	v_fma_f32 v120, v120, s84, v12
	v_fmamk_f32 v13, v186, 0x41880000, v10
	v_fma_f32 v121, v121, s84, v13
	v_fmamk_f32 v12, v186, 0x41900000, v10
	v_fma_f32 v122, v122, s84, v12
	v_fmamk_f32 v13, v186, 0x41980000, v10
	v_fma_f32 v123, v123, s84, v13
	v_fmamk_f32 v12, v186, 0x41c00000, v10
	v_fma_f32 v124, v124, s84, v12
	v_fmamk_f32 v13, v186, 0x41c80000, v10
	v_fma_f32 v125, v125, s84, v13
	v_fmamk_f32 v12, v186, 0x41d00000, v10
	v_fma_f32 v126, v126, s84, v12
	v_fmamk_f32 v13, v186, 0x41d80000, v10
	v_fma_f32 v127, v127, s84, v13
	v_fmamk_f32 v12, v186, 0x42000000, v10
	v_fma_f32 v128, v128, s84, v12
	v_fmamk_f32 v13, v186, 0x42040000, v10
	v_fma_f32 v129, v129, s84, v13
	v_fmamk_f32 v12, v186, 0x42080000, v10
	v_fma_f32 v130, v130, s84, v12
	v_fmamk_f32 v13, v186, 0x420c0000, v10
	v_fma_f32 v131, v131, s84, v13
	v_fmamk_f32 v12, v186, 0x42200000, v10
	v_fma_f32 v132, v132, s84, v12
	v_fmamk_f32 v13, v186, 0x42240000, v10
	v_fma_f32 v133, v133, s84, v13
	v_fmamk_f32 v12, v186, 0x42280000, v10
	v_fma_f32 v134, v134, s84, v12
	v_fmamk_f32 v13, v186, 0x422c0000, v10
	v_fma_f32 v135, v135, s84, v13
	v_fmamk_f32 v12, v186, 0x42400000, v10
	v_fma_f32 v136, v136, s84, v12
	v_fmamk_f32 v13, v186, 0x42440000, v10
	v_fma_f32 v137, v137, s84, v13
	v_fmamk_f32 v12, v186, 0x42480000, v10
	v_fma_f32 v138, v138, s84, v12
	v_fmamk_f32 v13, v186, 0x424c0000, v10
	v_fma_f32 v139, v139, s84, v13
	v_fmamk_f32 v12, v186, 0x42600000, v10
	v_fma_f32 v140, v140, s84, v12
	v_fmamk_f32 v13, v186, 0x42640000, v10
	v_fma_f32 v141, v141, s84, v13
	v_fmamk_f32 v12, v186, 0x42680000, v10
	v_fma_f32 v142, v142, s84, v12
	v_fmamk_f32 v13, v186, 0x426c0000, v10
	v_fma_f32 v143, v143, s84, v13
	s_add_i32 s24, s96, 63
	s_cmp_gt_i32 s24, s42
	s_cbranch_scc1 .Lwin_mask1
	s_sub_i32 s24, s42, s96
	s_add_i32 s24, s24, 31
	s_cmpk_gt_i32 s24, 0x1ff
	s_cbranch_scc1 .Lwin_mask1

.Lwin_nors1:
	ds_read_b128 v[240:243], v238 offset:35840
	ds_read_b128 v[244:247], v238 offset:40448
	ds_read_b128 v[248:251], v238 offset:35872
	ds_read_b128 v[196:199], v238 offset:40480
	s_waitcnt lgkmcnt(3)
	v_mfma_f32_32x32x16_bf16 v[80:95], v[240:243], v[112:115], v[80:95]
	ds_read_b128 v[240:243], v238 offset:35904
	s_waitcnt lgkmcnt(3)
	v_mfma_f32_32x32x16_bf16 v[96:111], v[244:247], v[112:115], v[96:111]
	ds_read_b128 v[244:247], v238 offset:40512
	s_waitcnt lgkmcnt(3)
	v_mfma_f32_32x32x16_bf16 v[80:95], v[248:251], v[120:123], v[80:95]
	ds_read_b128 v[248:251], v238 offset:35936
	s_waitcnt lgkmcnt(3)
	v_mfma_f32_32x32x16_bf16 v[96:111], v[196:199], v[120:123], v[96:111]
	ds_read_b128 v[196:199], v238 offset:40544
	s_waitcnt lgkmcnt(3)
	v_mfma_f32_32x32x16_bf16 v[80:95], v[240:243], v[128:131], v[80:95]
	s_waitcnt lgkmcnt(2)
	v_mfma_f32_32x32x16_bf16 v[96:111], v[244:247], v[128:131], v[96:111]
	s_waitcnt lgkmcnt(1)
	v_mfma_f32_32x32x16_bf16 v[80:95], v[248:251], v[136:139], v[80:95]
	s_waitcnt lgkmcnt(0)
	v_mfma_f32_32x32x16_bf16 v[96:111], v[196:199], v[136:139], v[96:111]
.Lwin_skip1:
	s_cmp_lt_i32 s23, 0
	s_cbranch_scc1 .Lwin_last1
	s_waitcnt vmcnt(2)
	ds_write_b128 v234, v[6:9] offset:0
	ds_write_b16 v170, v2 offset:26624
	ds_write_b16_d16_hi v170, v2 offset:26768
	ds_write_b16 v170, v3 offset:26912
	ds_write_b16_d16_hi v170, v3 offset:27056
	ds_write_b16 v170, v4 offset:27200
	ds_write_b16_d16_hi v170, v4 offset:27344
	ds_write_b16 v170, v5 offset:27488
	ds_write_b16_d16_hi v170, v5 offset:27632
	s_waitcnt lgkmcnt(0)
	s_barrier
	s_mov_b32 s96, s23
	s_mov_b32 s23, s25
	s_branch .Lwin_step0
.Lwin_mask0:
	v_subrev_u32_e32 v11, s96, v205
	v_sub_u32_e32 v11, v11, v233
	v_subrev_u32_e32 v12, 0, v11
	v_subrev_u32_e32 v13, 1, v11
	v_subrev_u32_e32 v14, 2, v11
	v_subrev_u32_e32 v15, 3, v11
	v_cmp_gt_u32_e64 s[16:17], s33, v12
	v_cmp_gt_u32_e64 s[98:99], s33, v13
	v_cmp_gt_u32_e64 s[46:47], s33, v14
	v_cmp_gt_u32_e64 s[48:49], s33, v15
	v_cndmask_b32_e64 v112, v225, v112, s[16:17]
	v_cndmask_b32_e64 v113, v225, v113, s[98:99]
	v_cndmask_b32_e64 v114, v225, v114, s[46:47]
	v_cndmask_b32_e64 v115, v225, v115, s[48:49]
	v_subrev_u32_e32 v12, 8, v11
	v_subrev_u32_e32 v13, 9, v11
	v_subrev_u32_e32 v14, 10, v11
	v_subrev_u32_e32 v15, 11, v11
	v_cmp_gt_u32_e64 s[16:17], s33, v12
	v_cmp_gt_u32_e64 s[98:99], s33, v13
	v_cmp_gt_u32_e64 s[46:47], s33, v14
	v_cmp_gt_u32_e64 s[48:49], s33, v15
	v_cndmask_b32_e64 v116, v225, v116, s[16:17]
	v_cndmask_b32_e64 v117, v225, v117, s[98:99]
	v_cndmask_b32_e64 v118, v225, v118, s[46:47]
	v_cndmask_b32_e64 v119, v225, v119, s[48:49]
	v_subrev_u32_e32 v12, 16, v11
	v_subrev_u32_e32 v13, 17, v11
	v_subrev_u32_e32 v14, 18, v11
	v_subrev_u32_e32 v15, 19, v11
	v_cmp_gt_u32_e64 s[16:17], s33, v12
	v_cmp_gt_u32_e64 s[98:99], s33, v13
	v_cmp_gt_u32_e64 s[46:47], s33, v14
	v_cmp_gt_u32_e64 s[48:49], s33, v15
	v_cndmask_b32_e64 v120, v225, v120, s[16:17]
	v_cndmask_b32_e64 v121, v225, v121, s[98:99]
	v_cndmask_b32_e64 v122, v225, v122, s[46:47]
	v_cndmask_b32_e64 v123, v225, v123, s[48:49]
	v_subrev_u32_e32 v12, 24, v11
	v_subrev_u32_e32 v13, 25, v11
	v_subrev_u32_e32 v14, 26, v11
	v_subrev_u32_e32 v15, 27, v11
	v_cmp_gt_u32_e64 s[16:17], s33, v12
	v_cmp_gt_u32_e64 s[98:99], s33, v13
	v_cmp_gt_u32_e64 s[46:47], s33, v14
	v_cmp_gt_u32_e64 s[48:49], s33, v15
	v_cndmask_b32_e64 v124, v225, v124, s[16:17]
	v_cndmask_b32_e64 v125, v225, v125, s[98:99]
	v_cndmask_b32_e64 v126, v225, v126, s[46:47]
	v_cndmask_b32_e64 v127, v225, v127, s[48:49]
	v_subrev_u32_e32 v12, 32, v11
	v_subrev_u32_e32 v13, 33, v11
	v_subrev_u32_e32 v14, 34, v11
	v_subrev_u32_e32 v15, 35, v11
	v_cmp_gt_u32_e64 s[16:17], s33, v12
	v_cmp_gt_u32_e64 s[98:99], s33, v13
	v_cmp_gt_u32_e64 s[46:47], s33, v14
	v_cmp_gt_u32_e64 s[48:49], s33, v15
	v_cndmask_b32_e64 v128, v225, v128, s[16:17]
	v_cndmask_b32_e64 v129, v225, v129, s[98:99]
	v_cndmask_b32_e64 v130, v225, v130, s[46:47]
	v_cndmask_b32_e64 v131, v225, v131, s[48:49]
	v_subrev_u32_e32 v12, 40, v11
	v_subrev_u32_e32 v13, 41, v11
	v_subrev_u32_e32 v14, 42, v11
	v_subrev_u32_e32 v15, 43, v11
	v_cmp_gt_u32_e64 s[16:17], s33, v12
	v_cmp_gt_u32_e64 s[98:99], s33, v13
	v_cmp_gt_u32_e64 s[46:47], s33, v14
	v_cmp_gt_u32_e64 s[48:49], s33, v15
	v_cndmask_b32_e64 v132, v225, v132, s[16:17]
	v_cndmask_b32_e64 v133, v225, v133, s[98:99]
	v_cndmask_b32_e64 v134, v225, v134, s[46:47]
	v_cndmask_b32_e64 v135, v225, v135, s[48:49]
	v_subrev_u32_e32 v12, 48, v11
	v_subrev_u32_e32 v13, 49, v11
	v_subrev_u32_e32 v14, 50, v11
	v_subrev_u32_e32 v15, 51, v11
	v_cmp_gt_u32_e64 s[16:17], s33, v12
	v_cmp_gt_u32_e64 s[98:99], s33, v13
	v_cmp_gt_u32_e64 s[46:47], s33, v14
	v_cmp_gt_u32_e64 s[48:49], s33, v15
	v_cndmask_b32_e64 v136, v225, v136, s[16:17]
	v_cndmask_b32_e64 v137, v225, v137, s[98:99]
	v_cndmask_b32_e64 v138, v225, v138, s[46:47]
	v_cndmask_b32_e64 v139, v225, v139, s[48:49]
	v_subrev_u32_e32 v12, 56, v11
	v_subrev_u32_e32 v13, 57, v11
	v_subrev_u32_e32 v14, 58, v11
	v_subrev_u32_e32 v15, 59, v11
	v_cmp_gt_u32_e64 s[16:17], s33, v12
	v_cmp_gt_u32_e64 s[98:99], s33, v13
	v_cmp_gt_u32_e64 s[46:47], s33, v14
	v_cmp_gt_u32_e64 s[48:49], s33, v15
	v_cndmask_b32_e64 v140, v225, v140, s[16:17]
	v_cndmask_b32_e64 v141, v225, v141, s[98:99]
	v_cndmask_b32_e64 v142, v225, v142, s[46:47]
	v_cndmask_b32_e64 v143, v225, v143, s[48:49]
	s_branch .Lwin_mdone0

; DI void online_raw(f32x16& s0, f32x16& s1, float c1, float& m, float& l, f32x16 (&O)[2]) {
;     float mx = fmaxf(s0[0], s1[0]);
; #pragma unroll
;     for (int i = 1; i < 16; ++i) mx = fmaxf(mx, fmaxf(s0[i], s1[i]));
;     mx = fmaxf(mx, __shfl_xor(mx, 32));
;     const float mxe = mx * c1;
;     if (__any(mxe - m > 8.f)) {
;         const float mn = fmaxf(m, mxe), alpha = __builtin_amdgcn_exp2f(m - mn);
;         l *= alpha; m = mn;
; #pragma unroll
;         for (int i = 0; i < 16; ++i) { O[0][i] *= alpha; O[1][i] *= alpha; }
;     }
;     const float nmn = -m;
;     float ls = 0.f;
; #pragma unroll
;     for (int i = 0; i < 16; ++i) { s0[i] = __builtin_amdgcn_exp2f(fmaf(s0[i], c1, nmn)); s1[i] = __builtin_amdgcn_exp2f(fmaf(s1[i], c1, nmn)); ls += s0[i] + s1[i]; }
;     ls += __shfl_xor(ls, 32);
;     l += ls;
; }
.Lmla_full0:
	ds_read_b128 v[186:189], v135 offset:13312
	ds_read_b128 v[190:193], v135 offset:19968
	ds_read_b128 v[194:197], v135 offset:13344
	ds_read_b128 v[202:205], v135 offset:20000
	ds_read_b128 v[210:213], v135 offset:13376
	ds_read_b128 v[234:237], v135 offset:20032
	global_load_dwordx4 v[86:89], v118, s[10:11]
	global_load_dwordx4 v[82:85], v119, s[10:11] offset:1024
	global_load_dwordx4 v[90:93], v120, s[48:49]
	v_max3_f32 v170, v34, v35, v36
	v_max3_f32 v176, v37, v38, v39
	v_max3_f32 v170, v170, v40, v41
	v_max3_f32 v176, v176, v42, v43
	s_waitcnt lgkmcnt(4)
	v_mfma_f32_32x32x16_bf16 v[138:153], v[186:189], v[66:69], 0
	v_max3_f32 v170, v170, v44, v45
	v_max3_f32 v176, v176, v46, v47
	v_max3_f32 v170, v170, v48, v49
	v_max3_f32 v176, v176, v50, v51
	v_mfma_f32_32x32x16_bf16 v[154:169], v[190:193], v[66:69], 0
	ds_read_b128 v[238:241], v135 offset:13408
	ds_read_b128 v[242:245], v135 offset:20064
	v_max3_f32 v170, v170, v52, v53
	v_max3_f32 v176, v176, v54, v55
	v_max3_f32 v170, v170, v56, v57
	v_max3_f32 v176, v176, v58, v59
	s_waitcnt lgkmcnt(4)
	v_mfma_f32_32x32x16_bf16 v[138:153], v[194:197], v[70:73], v[138:153]
	v_max3_f32 v170, v170, v60, v61
	v_max3_f32 v176, v176, v62, v63
	v_max3_f32 v170, v170, v64, v65
	v_max_f32_e32 v170, v170, v176
	v_mfma_f32_32x32x16_bf16 v[154:169], v[202:205], v[70:73], v[154:169]
	ds_read_b128 v[186:189], v135 offset:13440
	ds_read_b128 v[190:193], v135 offset:20096
	v_mov_b32_e32 v176, v170
	s_nop 1
	v_permlane32_swap_b32_e32 v176, v170
	v_max_f32_e32 v170, v170, v176
	v_fma_f32 v176, v170, s40, -v137
	v_cmp_lt_f32_e32 vcc, s28, v176
	s_cbranch_vccnz .Lmla_resc_f0
.Lmla_rback_f0:
	v_fma_f32 v34, v34, s40, -v137
	v_fma_f32 v35, v35, s40, -v137
	v_fma_f32 v36, v36, s40, -v137
	v_fma_f32 v37, v37, s40, -v137
	s_waitcnt lgkmcnt(4)
	v_mfma_f32_32x32x16_bf16 v[138:153], v[210:213], v[74:77], v[138:153]
	v_exp_f32_e32 v34, v34
	v_exp_f32_e32 v35, v35
	v_exp_f32_e32 v36, v36
	v_exp_f32_e32 v37, v37
	v_fma_f32 v38, v38, s40, -v137
	v_fma_f32 v39, v39, s40, -v137
	v_fma_f32 v40, v40, s40, -v137
	v_mfma_f32_32x32x16_bf16 v[154:169], v[234:237], v[74:77], v[154:169]
	ds_read_b128 v[194:197], v135 offset:13472
	ds_read_b128 v[202:205], v135 offset:20128
	v_fma_f32 v41, v41, s40, -v137
	v_exp_f32_e32 v38, v38
	v_exp_f32_e32 v39, v39
	v_exp_f32_e32 v40, v40
	v_exp_f32_e32 v41, v41
	v_add_f32_e32 v134, v134, v34
	s_waitcnt lgkmcnt(4)
	v_mfma_f32_32x32x16_bf16 v[138:153], v[238:241], v[78:81], v[138:153]
	v_add_f32_e32 v134, v134, v36
	v_add_f32_e32 v177, v35, v37
	v_add_f32_e32 v134, v134, v38
	v_add_f32_e32 v177, v177, v39
	v_add_f32_e32 v134, v134, v40
	v_add_f32_e32 v177, v177, v41
	v_cvt_pk_bf16_f32 v34, v34, v35
	v_mfma_f32_32x32x16_bf16 v[154:169], v[242:245], v[78:81], v[154:169]
	ds_read_b128 v[210:213], v136 offset:0
	ds_read_b128 v[234:237], v136 offset:4608
	v_cvt_pk_bf16_f32 v35, v36, v37
	v_cvt_pk_bf16_f32 v36, v38, v39
	v_cvt_pk_bf16_f32 v37, v40, v41
	v_fma_f32 v42, v42, s40, -v137
	v_fma_f32 v43, v43, s40, -v137
	v_fma_f32 v44, v44, s40, -v137
	v_fma_f32 v45, v45, s40, -v137
	s_waitcnt lgkmcnt(4)
	v_mfma_f32_32x32x16_bf16 v[138:153], v[186:189], v[94:97], v[138:153]
	v_exp_f32_e32 v42, v42
	v_exp_f32_e32 v43, v43
	v_exp_f32_e32 v44, v44
	v_exp_f32_e32 v45, v45
	v_fma_f32 v46, v46, s40, -v137
	v_fma_f32 v47, v47, s40, -v137
	v_fma_f32 v48, v48, s40, -v137
	v_mfma_f32_32x32x16_bf16 v[154:169], v[190:193], v[94:97], v[154:169]
	ds_read_b128 v[238:241], v136 offset:32
	ds_read_b128 v[242:245], v136 offset:4640
	v_fma_f32 v49, v49, s40, -v137
	v_exp_f32_e32 v46, v46
	v_exp_f32_e32 v47, v47
	v_exp_f32_e32 v48, v48
	v_exp_f32_e32 v49, v49
	v_add_f32_e32 v134, v134, v42
	v_add_f32_e32 v177, v177, v43
	s_waitcnt lgkmcnt(4)
	v_mfma_f32_32x32x16_bf16 v[138:153], v[194:197], v[98:101], v[138:153]
	v_add_f32_e32 v134, v134, v44
	v_add_f32_e32 v177, v177, v45
	v_add_f32_e32 v134, v134, v46
	v_add_f32_e32 v177, v177, v47
	v_add_f32_e32 v134, v134, v48
	v_add_f32_e32 v177, v177, v49
	v_cvt_pk_bf16_f32 v42, v42, v43
	v_mfma_f32_32x32x16_bf16 v[154:169], v[202:205], v[98:101], v[154:169]
	ds_read_b128 v[186:189], v136 offset:64
	ds_read_b128 v[190:193], v136 offset:4672
	v_cvt_pk_bf16_f32 v43, v44, v45
	v_cvt_pk_bf16_f32 v44, v46, v47
	v_cvt_pk_bf16_f32 v45, v48, v49
	v_fma_f32 v50, v50, s40, -v137
	v_fma_f32 v51, v51, s40, -v137
	v_fma_f32 v52, v52, s40, -v137
	v_fma_f32 v53, v53, s40, -v137
	s_waitcnt lgkmcnt(4)
	v_mfma_f32_32x32x16_bf16 v[18:33], v[210:213], v[34:37], v[18:33]
	v_exp_f32_e32 v50, v50
	v_exp_f32_e32 v51, v51
	v_exp_f32_e32 v52, v52
	v_exp_f32_e32 v53, v53
	v_fma_f32 v54, v54, s40, -v137
	v_fma_f32 v55, v55, s40, -v137
	v_fma_f32 v56, v56, s40, -v137
	v_mfma_f32_32x32x16_bf16 v[2:17], v[234:237], v[34:37], v[2:17]
	ds_read_b128 v[194:197], v136 offset:96
	ds_read_b128 v[202:205], v136 offset:4704
	v_fma_f32 v57, v57, s40, -v137
	v_exp_f32_e32 v54, v54
	v_exp_f32_e32 v55, v55
	v_exp_f32_e32 v56, v56
	v_exp_f32_e32 v57, v57
	v_add_f32_e32 v134, v134, v50
	v_add_f32_e32 v177, v177, v51
	s_waitcnt lgkmcnt(4)
	v_mfma_f32_32x32x16_bf16 v[18:33], v[238:241], v[42:45], v[18:33]
	v_add_f32_e32 v134, v134, v52
	v_add_f32_e32 v177, v177, v53
	v_add_f32_e32 v134, v134, v54
	v_add_f32_e32 v177, v177, v55
	v_add_f32_e32 v134, v134, v56
	v_add_f32_e32 v177, v177, v57
	v_cvt_pk_bf16_f32 v50, v50, v51
	v_mfma_f32_32x32x16_bf16 v[2:17], v[242:245], v[42:45], v[2:17]
	v_cvt_pk_bf16_f32 v51, v52, v53
	v_cvt_pk_bf16_f32 v52, v54, v55
	v_cvt_pk_bf16_f32 v53, v56, v57
	v_fma_f32 v58, v58, s40, -v137
	v_fma_f32 v59, v59, s40, -v137
	v_fma_f32 v60, v60, s40, -v137
	v_fma_f32 v61, v61, s40, -v137
	v_exp_f32_e32 v58, v58
	v_exp_f32_e32 v59, v59
	v_exp_f32_e32 v60, v60
	v_exp_f32_e32 v61, v61
	s_waitcnt lgkmcnt(2)
	v_mfma_f32_32x32x16_bf16 v[18:33], v[186:189], v[50:53], v[18:33]
	v_fma_f32 v62, v62, s40, -v137
	v_fma_f32 v63, v63, s40, -v137
	v_fma_f32 v64, v64, s40, -v137
	v_fma_f32 v65, v65, s40, -v137
	v_exp_f32_e32 v62, v62
	v_exp_f32_e32 v63, v63
	v_exp_f32_e32 v64, v64
	v_exp_f32_e32 v65, v65
	v_add_f32_e32 v134, v134, v58
	v_add_f32_e32 v177, v177, v59
	v_add_f32_e32 v134, v134, v60
	v_add_f32_e32 v177, v177, v61
	v_add_f32_e32 v134, v134, v62
	v_add_f32_e32 v177, v177, v63
	v_mfma_f32_32x32x16_bf16 v[2:17], v[190:193], v[50:53], v[2:17]
	v_add_f32_e32 v134, v134, v64
	v_add_f32_e32 v177, v177, v65
	v_cvt_pk_bf16_f32 v58, v58, v59
	v_cvt_pk_bf16_f32 v59, v60, v61
	v_cvt_pk_bf16_f32 v60, v62, v63
	v_cvt_pk_bf16_f32 v61, v64, v65
	v_add_f32_e32 v134, v134, v177
	s_nop 0
	s_waitcnt lgkmcnt(0)
	v_mfma_f32_32x32x16_bf16 v[18:33], v[194:197], v[58:61], v[18:33]
	v_mfma_f32_32x32x16_bf16 v[2:17], v[202:205], v[58:61], v[2:17]
	s_branch .Lmla_coop0

; #define MFMA32(a, b, c) __builtin_amdgcn_mfma_f32_32x32x16_bf16((a), (b), (c), 0, 0, 0)
;     DI float* h() const { return (float*)(__attribute__((address_space(1))) float*)kp->out; }
; DI void pv_tile(lbf Vt, const f32x16& p0, const f32x16& p1, f32x16 (&O)[2], int r, int h) {
;     bf16x8 va0, va1, vb0, vb1;
;     pv_load(Vt, 0, r, h, va0, va1);
; #pragma unroll
;     for (int g = 0; g < 4; g += 2) {
;         pv_load(Vt, g + 1, r, h, vb0, vb1);
;         const bf16x8 pa = pack8(g >> 1 ? p1 : p0, 0);
;         __builtin_amdgcn_sched_barrier(0);
;         O[0] = MFMA32(va0, pa, O[0]); O[1] = MFMA32(va1, pa, O[1]);
;         __builtin_amdgcn_sched_barrier(0);
;         if (g + 2 < 4) pv_load(Vt, g + 2, r, h, va0, va1);
;         const bf16x8 pb = pack8(g >> 1 ? p1 : p0, 1);
;         __builtin_amdgcn_sched_barrier(0);
;         O[0] = MFMA32(vb0, pb, O[0]); O[1] = MFMA32(vb1, pb, O[1]);
;         __builtin_amdgcn_sched_barrier(0);
;     }
; }
; DI void online_raw(f32x16& s0, f32x16& s1, float c1, float& m, float& l, f32x16 (&O)[2]) {
;     float mx = fmaxf(s0[0], s1[0]);
; #pragma unroll
;     for (int i = 1; i < 16; ++i) mx = fmaxf(mx, fmaxf(s0[i], s1[i]));
;     mx = fmaxf(mx, __shfl_xor(mx, 32));
;     const float mxe = mx * c1;
;     if (__any(mxe - m > 8.f)) {
;         const float mn = fmaxf(m, mxe), alpha = __builtin_amdgcn_exp2f(m - mn);
;         l *= alpha; m = mn;
; #pragma unroll
;         for (int i = 0; i < 16; ++i) { O[0][i] *= alpha; O[1][i] *= alpha; }
;     }
;     const float nmn = -m;
;     float ls = 0.f;
; #pragma unroll
;     for (int i = 0; i < 16; ++i) { s0[i] = __builtin_amdgcn_exp2f(fmaf(s0[i], c1, nmn)); s1[i] = __builtin_amdgcn_exp2f(fmaf(s1[i], c1, nmn)); ls += s0[i] + s1[i]; }
;     ls += __shfl_xor(ls, 32);
;     l += ls;
; }
.Lmla_rback_l0:
	v_fma_f32 v34, v34, s40, -v137
	v_fma_f32 v35, v35, s40, -v137
	v_fma_f32 v36, v36, s40, -v137
	v_fma_f32 v37, v37, s40, -v137
	v_exp_f32_e32 v34, v34
	v_exp_f32_e32 v35, v35
	v_exp_f32_e32 v36, v36
	v_exp_f32_e32 v37, v37
	v_fma_f32 v38, v38, s40, -v137
	v_fma_f32 v39, v39, s40, -v137
	v_fma_f32 v40, v40, s40, -v137
	v_fma_f32 v41, v41, s40, -v137
	v_exp_f32_e32 v38, v38
	v_exp_f32_e32 v39, v39
	v_exp_f32_e32 v40, v40
	v_exp_f32_e32 v41, v41
	v_add_f32_e32 v134, v134, v34
	v_add_f32_e32 v134, v134, v36
	v_add_f32_e32 v177, v35, v37
	v_add_f32_e32 v134, v134, v38
	v_add_f32_e32 v177, v177, v39
	v_add_f32_e32 v134, v134, v40
	v_add_f32_e32 v177, v177, v41
	v_cvt_pk_bf16_f32 v34, v34, v35
	v_cvt_pk_bf16_f32 v35, v36, v37
	v_cvt_pk_bf16_f32 v36, v38, v39
	v_cvt_pk_bf16_f32 v37, v40, v41
	v_fma_f32 v42, v42, s40, -v137
	v_fma_f32 v43, v43, s40, -v137
	v_fma_f32 v44, v44, s40, -v137
	v_fma_f32 v45, v45, s40, -v137
	v_exp_f32_e32 v42, v42
	v_exp_f32_e32 v43, v43
	v_exp_f32_e32 v44, v44
	v_exp_f32_e32 v45, v45
	s_waitcnt lgkmcnt(4)
	v_mfma_f32_32x32x16_bf16 v[18:33], v[186:189], v[34:37], v[18:33]
	v_fma_f32 v46, v46, s40, -v137
	v_fma_f32 v47, v47, s40, -v137
	v_fma_f32 v48, v48, s40, -v137
	v_fma_f32 v49, v49, s40, -v137
	v_exp_f32_e32 v46, v46
	v_exp_f32_e32 v47, v47
	v_exp_f32_e32 v48, v48
	v_exp_f32_e32 v49, v49
	v_add_f32_e32 v134, v134, v42
	v_add_f32_e32 v177, v177, v43
	v_add_f32_e32 v134, v134, v44
	v_add_f32_e32 v177, v177, v45
	v_add_f32_e32 v134, v134, v46
	v_add_f32_e32 v177, v177, v47
	v_mfma_f32_32x32x16_bf16 v[2:17], v[190:193], v[34:37], v[2:17]
	ds_read_b128 v[238:241], v136 offset:96
	ds_read_b128 v[242:245], v136 offset:4704
	v_add_f32_e32 v134, v134, v48
	v_add_f32_e32 v177, v177, v49
	v_cvt_pk_bf16_f32 v42, v42, v43
	v_cvt_pk_bf16_f32 v43, v44, v45
	v_cvt_pk_bf16_f32 v44, v46, v47
	v_cvt_pk_bf16_f32 v45, v48, v49
	v_fma_f32 v50, v50, s40, -v137
	v_fma_f32 v51, v51, s40, -v137
	v_fma_f32 v52, v52, s40, -v137
	v_fma_f32 v53, v53, s40, -v137
	v_exp_f32_e32 v50, v50
	v_exp_f32_e32 v51, v51
	v_exp_f32_e32 v52, v52
	v_exp_f32_e32 v53, v53
	s_waitcnt lgkmcnt(4)
	v_mfma_f32_32x32x16_bf16 v[18:33], v[194:197], v[42:45], v[18:33]
	v_fma_f32 v54, v54, s40, -v137
	v_fma_f32 v55, v55, s40, -v137
	v_fma_f32 v56, v56, s40, -v137
	v_fma_f32 v57, v57, s40, -v137
	v_exp_f32_e32 v54, v54
	v_exp_f32_e32 v55, v55
	v_exp_f32_e32 v56, v56
	v_exp_f32_e32 v57, v57
	v_add_f32_e32 v134, v134, v50
	v_add_f32_e32 v177, v177, v51
	v_add_f32_e32 v134, v134, v52
	v_add_f32_e32 v177, v177, v53
	v_add_f32_e32 v134, v134, v54
	v_add_f32_e32 v177, v177, v55
	v_mfma_f32_32x32x16_bf16 v[2:17], v[202:205], v[42:45], v[2:17]
	v_add_f32_e32 v134, v134, v56
	v_add_f32_e32 v177, v177, v57
	v_cvt_pk_bf16_f32 v50, v50, v51
	v_cvt_pk_bf16_f32 v51, v52, v53
	v_cvt_pk_bf16_f32 v52, v54, v55
	v_cvt_pk_bf16_f32 v53, v56, v57
	v_fma_f32 v58, v58, s40, -v137
	v_fma_f32 v59, v59, s40, -v137
	v_fma_f32 v60, v60, s40, -v137
	v_fma_f32 v61, v61, s40, -v137
	v_exp_f32_e32 v58, v58
	v_exp_f32_e32 v59, v59
	v_exp_f32_e32 v60, v60
	v_exp_f32_e32 v61, v61
	s_waitcnt lgkmcnt(2)
	v_mfma_f32_32x32x16_bf16 v[18:33], v[210:213], v[50:53], v[18:33]
	v_fma_f32 v62, v62, s40, -v137
	v_fma_f32 v63, v63, s40, -v137
	v_fma_f32 v64, v64, s40, -v137
	v_fma_f32 v65, v65, s40, -v137
	v_exp_f32_e32 v62, v62
	v_exp_f32_e32 v63, v63
	v_exp_f32_e32 v64, v64
	v_exp_f32_e32 v65, v65
	v_add_f32_e32 v134, v134, v58
	v_add_f32_e32 v177, v177, v59
	v_add_f32_e32 v134, v134, v60
	v_add_f32_e32 v177, v177, v61
	v_add_f32_e32 v134, v134, v62
	v_add_f32_e32 v177, v177, v63
	v_mfma_f32_32x32x16_bf16 v[2:17], v[234:237], v[50:53], v[2:17]
	v_add_f32_e32 v134, v134, v64
	v_add_f32_e32 v177, v177, v65
	v_cvt_pk_bf16_f32 v58, v58, v59
	v_cvt_pk_bf16_f32 v59, v60, v61
	v_cvt_pk_bf16_f32 v60, v62, v63
	v_cvt_pk_bf16_f32 v61, v64, v65
	v_add_f32_e32 v134, v134, v177
	s_nop 0
	s_waitcnt lgkmcnt(0)
	v_mfma_f32_32x32x16_bf16 v[18:33], v[238:241], v[58:61], v[18:33]
	v_mfma_f32_32x32x16_bf16 v[2:17], v[242:245], v[58:61], v[2:17]

; DI void online_raw(f32x16& s0, f32x16& s1, float c1, float& m, float& l, f32x16 (&O)[2]) {
;     float mx = fmaxf(s0[0], s1[0]);
; #pragma unroll
;     for (int i = 1; i < 16; ++i) mx = fmaxf(mx, fmaxf(s0[i], s1[i]));
;     mx = fmaxf(mx, __shfl_xor(mx, 32));
;     const float mxe = mx * c1;
;     if (__any(mxe - m > 8.f)) {
;         const float mn = fmaxf(m, mxe), alpha = __builtin_amdgcn_exp2f(m - mn);
;         l *= alpha; m = mn;
; #pragma unroll
;         for (int i = 0; i < 16; ++i) { O[0][i] *= alpha; O[1][i] *= alpha; }
;     }
;     const float nmn = -m;
;     float ls = 0.f;
; #pragma unroll
;     for (int i = 0; i < 16; ++i) { s0[i] = __builtin_amdgcn_exp2f(fmaf(s0[i], c1, nmn)); s1[i] = __builtin_amdgcn_exp2f(fmaf(s1[i], c1, nmn)); ls += s0[i] + s1[i]; }
;     ls += __shfl_xor(ls, 32);
;     l += ls;
; }
.Lmla_full1:
	ds_read_b128 v[186:189], v135 offset:26624
	ds_read_b128 v[190:193], v135 offset:33280
	ds_read_b128 v[194:197], v135 offset:26656
	ds_read_b128 v[202:205], v135 offset:33312
	ds_read_b128 v[210:213], v135 offset:26688
	ds_read_b128 v[234:237], v135 offset:33344
	global_load_dwordx4 v[106:109], v118, s[10:11]
	global_load_dwordx4 v[102:105], v119, s[10:11] offset:1024
	global_load_dwordx4 v[110:113], v120, s[48:49]
	v_max3_f32 v170, v138, v139, v140
	v_max3_f32 v176, v141, v142, v143
	v_max3_f32 v170, v170, v144, v145
	v_max3_f32 v176, v176, v146, v147
	s_waitcnt lgkmcnt(4)
	v_mfma_f32_32x32x16_bf16 v[34:49], v[186:189], v[66:69], 0
	v_max3_f32 v170, v170, v148, v149
	v_max3_f32 v176, v176, v150, v151
	v_max3_f32 v170, v170, v152, v153
	v_max3_f32 v176, v176, v154, v155
	v_mfma_f32_32x32x16_bf16 v[50:65], v[190:193], v[66:69], 0
	ds_read_b128 v[238:241], v135 offset:26720
	ds_read_b128 v[242:245], v135 offset:33376
	v_max3_f32 v170, v170, v156, v157
	v_max3_f32 v176, v176, v158, v159
	v_max3_f32 v170, v170, v160, v161
	v_max3_f32 v176, v176, v162, v163
	s_waitcnt lgkmcnt(4)
	v_mfma_f32_32x32x16_bf16 v[34:49], v[194:197], v[70:73], v[34:49]
	v_max3_f32 v170, v170, v164, v165
	v_max3_f32 v176, v176, v166, v167
	v_max3_f32 v170, v170, v168, v169
	v_max_f32_e32 v170, v170, v176
	v_mfma_f32_32x32x16_bf16 v[50:65], v[202:205], v[70:73], v[50:65]
	ds_read_b128 v[186:189], v135 offset:26752
	ds_read_b128 v[190:193], v135 offset:33408
	v_mov_b32_e32 v176, v170
	s_nop 1
	v_permlane32_swap_b32_e32 v176, v170
	v_max_f32_e32 v170, v170, v176
	v_fma_f32 v176, v170, s40, -v137
	v_cmp_lt_f32_e32 vcc, s28, v176
	s_cbranch_vccnz .Lmla_resc_f1
.Lmla_rback_f1:
	v_fma_f32 v138, v138, s40, -v137
	v_fma_f32 v139, v139, s40, -v137
	v_fma_f32 v140, v140, s40, -v137
	v_fma_f32 v141, v141, s40, -v137
	s_waitcnt lgkmcnt(4)
	v_mfma_f32_32x32x16_bf16 v[34:49], v[210:213], v[74:77], v[34:49]
	v_exp_f32_e32 v138, v138
	v_exp_f32_e32 v139, v139
	v_exp_f32_e32 v140, v140
	v_exp_f32_e32 v141, v141
	v_fma_f32 v142, v142, s40, -v137
	v_fma_f32 v143, v143, s40, -v137
	v_fma_f32 v144, v144, s40, -v137
	v_mfma_f32_32x32x16_bf16 v[50:65], v[234:237], v[74:77], v[50:65]
	ds_read_b128 v[194:197], v135 offset:26784
	ds_read_b128 v[202:205], v135 offset:33440
	v_fma_f32 v145, v145, s40, -v137
	v_exp_f32_e32 v142, v142
	v_exp_f32_e32 v143, v143
	v_exp_f32_e32 v144, v144
	v_exp_f32_e32 v145, v145
	v_add_f32_e32 v134, v134, v138
	s_waitcnt lgkmcnt(4)
	v_mfma_f32_32x32x16_bf16 v[34:49], v[238:241], v[78:81], v[34:49]
	v_add_f32_e32 v134, v134, v140
	v_add_f32_e32 v177, v139, v141
	v_add_f32_e32 v134, v134, v142
	v_add_f32_e32 v177, v177, v143
	v_add_f32_e32 v134, v134, v144
	v_add_f32_e32 v177, v177, v145
	v_cvt_pk_bf16_f32 v138, v138, v139
	v_mfma_f32_32x32x16_bf16 v[50:65], v[242:245], v[78:81], v[50:65]
	ds_read_b128 v[210:213], v136 offset:9216
	ds_read_b128 v[234:237], v136 offset:13824
	v_cvt_pk_bf16_f32 v139, v140, v141
	v_cvt_pk_bf16_f32 v140, v142, v143
	v_cvt_pk_bf16_f32 v141, v144, v145
	v_fma_f32 v146, v146, s40, -v137
	v_fma_f32 v147, v147, s40, -v137
	v_fma_f32 v148, v148, s40, -v137
	v_fma_f32 v149, v149, s40, -v137
	s_waitcnt lgkmcnt(4)
	v_mfma_f32_32x32x16_bf16 v[34:49], v[186:189], v[94:97], v[34:49]
	v_exp_f32_e32 v146, v146
	v_exp_f32_e32 v147, v147
	v_exp_f32_e32 v148, v148
	v_exp_f32_e32 v149, v149
	v_fma_f32 v150, v150, s40, -v137
	v_fma_f32 v151, v151, s40, -v137
	v_fma_f32 v152, v152, s40, -v137
	v_mfma_f32_32x32x16_bf16 v[50:65], v[190:193], v[94:97], v[50:65]
	ds_read_b128 v[238:241], v136 offset:9248
	ds_read_b128 v[242:245], v136 offset:13856
	v_fma_f32 v153, v153, s40, -v137
	v_exp_f32_e32 v150, v150
	v_exp_f32_e32 v151, v151
	v_exp_f32_e32 v152, v152
	v_exp_f32_e32 v153, v153
	v_add_f32_e32 v134, v134, v146
	v_add_f32_e32 v177, v177, v147
	s_waitcnt lgkmcnt(4)
	v_mfma_f32_32x32x16_bf16 v[34:49], v[194:197], v[98:101], v[34:49]
	v_add_f32_e32 v134, v134, v148
	v_add_f32_e32 v177, v177, v149
	v_add_f32_e32 v134, v134, v150
	v_add_f32_e32 v177, v177, v151
	v_add_f32_e32 v134, v134, v152
	v_add_f32_e32 v177, v177, v153
	v_cvt_pk_bf16_f32 v146, v146, v147
	v_mfma_f32_32x32x16_bf16 v[50:65], v[202:205], v[98:101], v[50:65]
	ds_read_b128 v[186:189], v136 offset:9280
	ds_read_b128 v[190:193], v136 offset:13888
	v_cvt_pk_bf16_f32 v147, v148, v149
	v_cvt_pk_bf16_f32 v148, v150, v151
	v_cvt_pk_bf16_f32 v149, v152, v153
	v_fma_f32 v154, v154, s40, -v137
	v_fma_f32 v155, v155, s40, -v137
	v_fma_f32 v156, v156, s40, -v137
	v_fma_f32 v157, v157, s40, -v137
	s_waitcnt lgkmcnt(4)
	v_mfma_f32_32x32x16_bf16 v[18:33], v[210:213], v[138:141], v[18:33]
	v_exp_f32_e32 v154, v154
	v_exp_f32_e32 v155, v155
	v_exp_f32_e32 v156, v156
	v_exp_f32_e32 v157, v157
	v_fma_f32 v158, v158, s40, -v137
	v_fma_f32 v159, v159, s40, -v137
	v_fma_f32 v160, v160, s40, -v137
	v_mfma_f32_32x32x16_bf16 v[2:17], v[234:237], v[138:141], v[2:17]
	ds_read_b128 v[194:197], v136 offset:9312
	ds_read_b128 v[202:205], v136 offset:13920
	v_fma_f32 v161, v161, s40, -v137
	v_exp_f32_e32 v158, v158
	v_exp_f32_e32 v159, v159
	v_exp_f32_e32 v160, v160
	v_exp_f32_e32 v161, v161
	v_add_f32_e32 v134, v134, v154
	v_add_f32_e32 v177, v177, v155
	s_waitcnt lgkmcnt(4)
	v_mfma_f32_32x32x16_bf16 v[18:33], v[238:241], v[146:149], v[18:33]
	v_add_f32_e32 v134, v134, v156
	v_add_f32_e32 v177, v177, v157
	v_add_f32_e32 v134, v134, v158
	v_add_f32_e32 v177, v177, v159
	v_add_f32_e32 v134, v134, v160
	v_add_f32_e32 v177, v177, v161
	v_cvt_pk_bf16_f32 v154, v154, v155
	v_mfma_f32_32x32x16_bf16 v[2:17], v[242:245], v[146:149], v[2:17]
	v_cvt_pk_bf16_f32 v155, v156, v157
	v_cvt_pk_bf16_f32 v156, v158, v159
	v_cvt_pk_bf16_f32 v157, v160, v161
	v_fma_f32 v162, v162, s40, -v137
	v_fma_f32 v163, v163, s40, -v137
	v_fma_f32 v164, v164, s40, -v137
	v_fma_f32 v165, v165, s40, -v137
	v_exp_f32_e32 v162, v162
	v_exp_f32_e32 v163, v163
	v_exp_f32_e32 v164, v164
	v_exp_f32_e32 v165, v165
	s_waitcnt lgkmcnt(2)
	v_mfma_f32_32x32x16_bf16 v[18:33], v[186:189], v[154:157], v[18:33]
	v_fma_f32 v166, v166, s40, -v137
	v_fma_f32 v167, v167, s40, -v137
	v_fma_f32 v168, v168, s40, -v137
	v_fma_f32 v169, v169, s40, -v137
	v_exp_f32_e32 v166, v166
	v_exp_f32_e32 v167, v167
	v_exp_f32_e32 v168, v168
	v_exp_f32_e32 v169, v169
	v_add_f32_e32 v134, v134, v162
	v_add_f32_e32 v177, v177, v163
	v_add_f32_e32 v134, v134, v164
	v_add_f32_e32 v177, v177, v165
	v_add_f32_e32 v134, v134, v166
	v_add_f32_e32 v177, v177, v167
	v_mfma_f32_32x32x16_bf16 v[2:17], v[190:193], v[154:157], v[2:17]
	v_add_f32_e32 v134, v134, v168
	v_add_f32_e32 v177, v177, v169
	v_cvt_pk_bf16_f32 v162, v162, v163
	v_cvt_pk_bf16_f32 v163, v164, v165
	v_cvt_pk_bf16_f32 v164, v166, v167
	v_cvt_pk_bf16_f32 v165, v168, v169
	v_add_f32_e32 v134, v134, v177
	s_nop 0
	s_waitcnt lgkmcnt(0)
	v_mfma_f32_32x32x16_bf16 v[18:33], v[194:197], v[162:165], v[18:33]
	v_mfma_f32_32x32x16_bf16 v[2:17], v[202:205], v[162:165], v[2:17]
	s_branch .Lmla_coop1

; #define MFMA32(a, b, c) __builtin_amdgcn_mfma_f32_32x32x16_bf16((a), (b), (c), 0, 0, 0)
;     DI float* h() const { return (float*)(__attribute__((address_space(1))) float*)kp->out; }
; DI void pv_tile(lbf Vt, const f32x16& p0, const f32x16& p1, f32x16 (&O)[2], int r, int h) {
;     bf16x8 va0, va1, vb0, vb1;
;     pv_load(Vt, 0, r, h, va0, va1);
; #pragma unroll
;     for (int g = 0; g < 4; g += 2) {
;         pv_load(Vt, g + 1, r, h, vb0, vb1);
;         const bf16x8 pa = pack8(g >> 1 ? p1 : p0, 0);
;         __builtin_amdgcn_sched_barrier(0);
;         O[0] = MFMA32(va0, pa, O[0]); O[1] = MFMA32(va1, pa, O[1]);
;         __builtin_amdgcn_sched_barrier(0);
;         if (g + 2 < 4) pv_load(Vt, g + 2, r, h, va0, va1);
;         const bf16x8 pb = pack8(g >> 1 ? p1 : p0, 1);
;         __builtin_amdgcn_sched_barrier(0);
;         O[0] = MFMA32(vb0, pb, O[0]); O[1] = MFMA32(vb1, pb, O[1]);
;         __builtin_amdgcn_sched_barrier(0);
;     }
; }
; DI void online_raw(f32x16& s0, f32x16& s1, float c1, float& m, float& l, f32x16 (&O)[2]) {
;     float mx = fmaxf(s0[0], s1[0]);
; #pragma unroll
;     for (int i = 1; i < 16; ++i) mx = fmaxf(mx, fmaxf(s0[i], s1[i]));
;     mx = fmaxf(mx, __shfl_xor(mx, 32));
;     const float mxe = mx * c1;
;     if (__any(mxe - m > 8.f)) {
;         const float mn = fmaxf(m, mxe), alpha = __builtin_amdgcn_exp2f(m - mn);
;         l *= alpha; m = mn;
; #pragma unroll
;         for (int i = 0; i < 16; ++i) { O[0][i] *= alpha; O[1][i] *= alpha; }
;     }
;     const float nmn = -m;
;     float ls = 0.f;
; #pragma unroll
;     for (int i = 0; i < 16; ++i) { s0[i] = __builtin_amdgcn_exp2f(fmaf(s0[i], c1, nmn)); s1[i] = __builtin_amdgcn_exp2f(fmaf(s1[i], c1, nmn)); ls += s0[i] + s1[i]; }
;     ls += __shfl_xor(ls, 32);
;     l += ls;
; }
.Lmla_rback_l1:
	v_fma_f32 v138, v138, s40, -v137
	v_fma_f32 v139, v139, s40, -v137
	v_fma_f32 v140, v140, s40, -v137
	v_fma_f32 v141, v141, s40, -v137
	v_exp_f32_e32 v138, v138
	v_exp_f32_e32 v139, v139
	v_exp_f32_e32 v140, v140
	v_exp_f32_e32 v141, v141
	v_fma_f32 v142, v142, s40, -v137
	v_fma_f32 v143, v143, s40, -v137
	v_fma_f32 v144, v144, s40, -v137
	v_fma_f32 v145, v145, s40, -v137
	v_exp_f32_e32 v142, v142
	v_exp_f32_e32 v143, v143
	v_exp_f32_e32 v144, v144
	v_exp_f32_e32 v145, v145
	v_add_f32_e32 v134, v134, v138
	v_add_f32_e32 v134, v134, v140
	v_add_f32_e32 v177, v139, v141
	v_add_f32_e32 v134, v134, v142
	v_add_f32_e32 v177, v177, v143
	v_add_f32_e32 v134, v134, v144
	v_add_f32_e32 v177, v177, v145
	v_cvt_pk_bf16_f32 v138, v138, v139
	v_cvt_pk_bf16_f32 v139, v140, v141
	v_cvt_pk_bf16_f32 v140, v142, v143
	v_cvt_pk_bf16_f32 v141, v144, v145
	v_fma_f32 v146, v146, s40, -v137
	v_fma_f32 v147, v147, s40, -v137
	v_fma_f32 v148, v148, s40, -v137
	v_fma_f32 v149, v149, s40, -v137
	v_exp_f32_e32 v146, v146
	v_exp_f32_e32 v147, v147
	v_exp_f32_e32 v148, v148
	v_exp_f32_e32 v149, v149
	s_waitcnt lgkmcnt(4)
	v_mfma_f32_32x32x16_bf16 v[18:33], v[186:189], v[138:141], v[18:33]
	v_fma_f32 v150, v150, s40, -v137
	v_fma_f32 v151, v151, s40, -v137
	v_fma_f32 v152, v152, s40, -v137
	v_fma_f32 v153, v153, s40, -v137
	v_exp_f32_e32 v150, v150
	v_exp_f32_e32 v151, v151
	v_exp_f32_e32 v152, v152
	v_exp_f32_e32 v153, v153
	v_add_f32_e32 v134, v134, v146
	v_add_f32_e32 v177, v177, v147
	v_add_f32_e32 v134, v134, v148
	v_add_f32_e32 v177, v177, v149
	v_add_f32_e32 v134, v134, v150
	v_add_f32_e32 v177, v177, v151
	v_mfma_f32_32x32x16_bf16 v[2:17], v[190:193], v[138:141], v[2:17]
	ds_read_b128 v[238:241], v136 offset:9312
	ds_read_b128 v[242:245], v136 offset:13920
	v_add_f32_e32 v134, v134, v152
	v_add_f32_e32 v177, v177, v153
	v_cvt_pk_bf16_f32 v146, v146, v147
	v_cvt_pk_bf16_f32 v147, v148, v149
	v_cvt_pk_bf16_f32 v148, v150, v151
	v_cvt_pk_bf16_f32 v149, v152, v153
	v_fma_f32 v154, v154, s40, -v137
	v_fma_f32 v155, v155, s40, -v137
	v_fma_f32 v156, v156, s40, -v137
	v_fma_f32 v157, v157, s40, -v137
	v_exp_f32_e32 v154, v154
	v_exp_f32_e32 v155, v155
	v_exp_f32_e32 v156, v156
	v_exp_f32_e32 v157, v157
	s_waitcnt lgkmcnt(4)
	v_mfma_f32_32x32x16_bf16 v[18:33], v[194:197], v[146:149], v[18:33]
	v_fma_f32 v158, v158, s40, -v137
	v_fma_f32 v159, v159, s40, -v137
	v_fma_f32 v160, v160, s40, -v137
	v_fma_f32 v161, v161, s40, -v137
	v_exp_f32_e32 v158, v158
	v_exp_f32_e32 v159, v159
	v_exp_f32_e32 v160, v160
	v_exp_f32_e32 v161, v161
	v_add_f32_e32 v134, v134, v154
	v_add_f32_e32 v177, v177, v155
	v_add_f32_e32 v134, v134, v156
	v_add_f32_e32 v177, v177, v157
	v_add_f32_e32 v134, v134, v158
	v_add_f32_e32 v177, v177, v159
	v_mfma_f32_32x32x16_bf16 v[2:17], v[202:205], v[146:149], v[2:17]
	v_add_f32_e32 v134, v134, v160
	v_add_f32_e32 v177, v177, v161
	v_cvt_pk_bf16_f32 v154, v154, v155
	v_cvt_pk_bf16_f32 v155, v156, v157
	v_cvt_pk_bf16_f32 v156, v158, v159
	v_cvt_pk_bf16_f32 v157, v160, v161
	v_fma_f32 v162, v162, s40, -v137
	v_fma_f32 v163, v163, s40, -v137
	v_fma_f32 v164, v164, s40, -v137
	v_fma_f32 v165, v165, s40, -v137
	v_exp_f32_e32 v162, v162
	v_exp_f32_e32 v163, v163
	v_exp_f32_e32 v164, v164
	v_exp_f32_e32 v165, v165
	s_waitcnt lgkmcnt(2)
	v_mfma_f32_32x32x16_bf16 v[18:33], v[210:213], v[154:157], v[18:33]
	v_fma_f32 v166, v166, s40, -v137
	v_fma_f32 v167, v167, s40, -v137
	v_fma_f32 v168, v168, s40, -v137
	v_fma_f32 v169, v169, s40, -v137
	v_exp_f32_e32 v166, v166
	v_exp_f32_e32 v167, v167
	v_exp_f32_e32 v168, v168
	v_exp_f32_e32 v169, v169
	v_add_f32_e32 v134, v134, v162
	v_add_f32_e32 v177, v177, v163
	v_add_f32_e32 v134, v134, v164
	v_add_f32_e32 v177, v177, v165
	v_add_f32_e32 v134, v134, v166
	v_add_f32_e32 v177, v177, v167
	v_mfma_f32_32x32x16_bf16 v[2:17], v[234:237], v[154:157], v[2:17]
	v_add_f32_e32 v134, v134, v168
	v_add_f32_e32 v177, v177, v169
	v_cvt_pk_bf16_f32 v162, v162, v163
	v_cvt_pk_bf16_f32 v163, v164, v165
	v_cvt_pk_bf16_f32 v164, v166, v167
	v_cvt_pk_bf16_f32 v165, v168, v169
	v_add_f32_e32 v134, v134, v177
	s_nop 0
	s_waitcnt lgkmcnt(0)
	v_mfma_f32_32x32x16_bf16 v[18:33], v[238:241], v[162:165], v[18:33]
	v_mfma_f32_32x32x16_bf16 v[2:17], v[242:245], v[162:165], v[2:17]

; DI void online_raw(f32x16& s0, f32x16& s1, float c1, float& m, float& l, f32x16 (&O)[2]) {
;     float mx = fmaxf(s0[0], s1[0]);
; #pragma unroll
;     for (int i = 1; i < 16; ++i) mx = fmaxf(mx, fmaxf(s0[i], s1[i]));
;     mx = fmaxf(mx, __shfl_xor(mx, 32));
;     const float mxe = mx * c1;
;     if (__any(mxe - m > 8.f)) {
;         const float mn = fmaxf(m, mxe), alpha = __builtin_amdgcn_exp2f(m - mn);
;         l *= alpha; m = mn;
; #pragma unroll
;         for (int i = 0; i < 16; ++i) { O[0][i] *= alpha; O[1][i] *= alpha; }
;     }
;     const float nmn = -m;
;     float ls = 0.f;
; #pragma unroll
;     for (int i = 0; i < 16; ++i) { s0[i] = __builtin_amdgcn_exp2f(fmaf(s0[i], c1, nmn)); s1[i] = __builtin_amdgcn_exp2f(fmaf(s1[i], c1, nmn)); ls += s0[i] + s1[i]; }
;     ls += __shfl_xor(ls, 32);
;     l += ls;
; }
.Lmla_full2:
	ds_read_b128 v[186:189], v135 offset:39936
	ds_read_b128 v[190:193], v135 offset:46592
	ds_read_b128 v[194:197], v135 offset:39968
	ds_read_b128 v[202:205], v135 offset:46624
	ds_read_b128 v[210:213], v135 offset:40000
	ds_read_b128 v[234:237], v135 offset:46656
	global_load_dwordx4 v[86:89], v118, s[10:11]
	global_load_dwordx4 v[82:85], v119, s[10:11] offset:1024
	global_load_dwordx4 v[90:93], v120, s[48:49]
	v_max3_f32 v170, v34, v35, v36
	v_max3_f32 v176, v37, v38, v39
	v_max3_f32 v170, v170, v40, v41
	v_max3_f32 v176, v176, v42, v43
	s_waitcnt lgkmcnt(4)
	v_mfma_f32_32x32x16_bf16 v[138:153], v[186:189], v[66:69], 0
	v_max3_f32 v170, v170, v44, v45
	v_max3_f32 v176, v176, v46, v47
	v_max3_f32 v170, v170, v48, v49
	v_max3_f32 v176, v176, v50, v51
	v_mfma_f32_32x32x16_bf16 v[154:169], v[190:193], v[66:69], 0
	ds_read_b128 v[238:241], v135 offset:40032
	ds_read_b128 v[242:245], v135 offset:46688
	v_max3_f32 v170, v170, v52, v53
	v_max3_f32 v176, v176, v54, v55
	v_max3_f32 v170, v170, v56, v57
	v_max3_f32 v176, v176, v58, v59
	s_waitcnt lgkmcnt(4)
	v_mfma_f32_32x32x16_bf16 v[138:153], v[194:197], v[70:73], v[138:153]
	v_max3_f32 v170, v170, v60, v61
	v_max3_f32 v176, v176, v62, v63
	v_max3_f32 v170, v170, v64, v65
	v_max_f32_e32 v170, v170, v176
	v_mfma_f32_32x32x16_bf16 v[154:169], v[202:205], v[70:73], v[154:169]
	ds_read_b128 v[186:189], v135 offset:40064
	ds_read_b128 v[190:193], v135 offset:46720
	v_mov_b32_e32 v176, v170
	s_nop 1
	v_permlane32_swap_b32_e32 v176, v170
	v_max_f32_e32 v170, v170, v176
	v_fma_f32 v176, v170, s40, -v137
	v_cmp_lt_f32_e32 vcc, s28, v176
	s_cbranch_vccnz .Lmla_resc_f2
.Lmla_rback_f2:
	v_fma_f32 v34, v34, s40, -v137
	v_fma_f32 v35, v35, s40, -v137
	v_fma_f32 v36, v36, s40, -v137
	v_fma_f32 v37, v37, s40, -v137
	s_waitcnt lgkmcnt(4)
	v_mfma_f32_32x32x16_bf16 v[138:153], v[210:213], v[74:77], v[138:153]
	v_exp_f32_e32 v34, v34
	v_exp_f32_e32 v35, v35
	v_exp_f32_e32 v36, v36
	v_exp_f32_e32 v37, v37
	v_fma_f32 v38, v38, s40, -v137
	v_fma_f32 v39, v39, s40, -v137
	v_fma_f32 v40, v40, s40, -v137
	v_mfma_f32_32x32x16_bf16 v[154:169], v[234:237], v[74:77], v[154:169]
	ds_read_b128 v[194:197], v135 offset:40096
	ds_read_b128 v[202:205], v135 offset:46752
	v_fma_f32 v41, v41, s40, -v137
	v_exp_f32_e32 v38, v38
	v_exp_f32_e32 v39, v39
	v_exp_f32_e32 v40, v40
	v_exp_f32_e32 v41, v41
	v_add_f32_e32 v134, v134, v34
	s_waitcnt lgkmcnt(4)
	v_mfma_f32_32x32x16_bf16 v[138:153], v[238:241], v[78:81], v[138:153]
	v_add_f32_e32 v134, v134, v36
	v_add_f32_e32 v177, v35, v37
	v_add_f32_e32 v134, v134, v38
	v_add_f32_e32 v177, v177, v39
	v_add_f32_e32 v134, v134, v40
	v_add_f32_e32 v177, v177, v41
	v_cvt_pk_bf16_f32 v34, v34, v35
	v_mfma_f32_32x32x16_bf16 v[154:169], v[242:245], v[78:81], v[154:169]
	ds_read_b128 v[210:213], v136 offset:18432
	ds_read_b128 v[234:237], v136 offset:23040
	v_cvt_pk_bf16_f32 v35, v36, v37
	v_cvt_pk_bf16_f32 v36, v38, v39
	v_cvt_pk_bf16_f32 v37, v40, v41
	v_fma_f32 v42, v42, s40, -v137
	v_fma_f32 v43, v43, s40, -v137
	v_fma_f32 v44, v44, s40, -v137
	v_fma_f32 v45, v45, s40, -v137
	s_waitcnt lgkmcnt(4)
	v_mfma_f32_32x32x16_bf16 v[138:153], v[186:189], v[94:97], v[138:153]
	v_exp_f32_e32 v42, v42
	v_exp_f32_e32 v43, v43
	v_exp_f32_e32 v44, v44
	v_exp_f32_e32 v45, v45
	v_fma_f32 v46, v46, s40, -v137
	v_fma_f32 v47, v47, s40, -v137
	v_fma_f32 v48, v48, s40, -v137
	v_mfma_f32_32x32x16_bf16 v[154:169], v[190:193], v[94:97], v[154:169]
	ds_read_b128 v[238:241], v136 offset:18464
	ds_read_b128 v[242:245], v136 offset:23072
	v_fma_f32 v49, v49, s40, -v137
	v_exp_f32_e32 v46, v46
	v_exp_f32_e32 v47, v47
	v_exp_f32_e32 v48, v48
	v_exp_f32_e32 v49, v49
	v_add_f32_e32 v134, v134, v42
	v_add_f32_e32 v177, v177, v43
	s_waitcnt lgkmcnt(4)
	v_mfma_f32_32x32x16_bf16 v[138:153], v[194:197], v[98:101], v[138:153]
	v_add_f32_e32 v134, v134, v44
	v_add_f32_e32 v177, v177, v45
	v_add_f32_e32 v134, v134, v46
	v_add_f32_e32 v177, v177, v47
	v_add_f32_e32 v134, v134, v48
	v_add_f32_e32 v177, v177, v49
	v_cvt_pk_bf16_f32 v42, v42, v43
	v_mfma_f32_32x32x16_bf16 v[154:169], v[202:205], v[98:101], v[154:169]
	ds_read_b128 v[186:189], v136 offset:18496
	ds_read_b128 v[190:193], v136 offset:23104
	v_cvt_pk_bf16_f32 v43, v44, v45
	v_cvt_pk_bf16_f32 v44, v46, v47
	v_cvt_pk_bf16_f32 v45, v48, v49
	v_fma_f32 v50, v50, s40, -v137
	v_fma_f32 v51, v51, s40, -v137
	v_fma_f32 v52, v52, s40, -v137
	v_fma_f32 v53, v53, s40, -v137
	s_waitcnt lgkmcnt(4)
	v_mfma_f32_32x32x16_bf16 v[18:33], v[210:213], v[34:37], v[18:33]
	v_exp_f32_e32 v50, v50
	v_exp_f32_e32 v51, v51
	v_exp_f32_e32 v52, v52
	v_exp_f32_e32 v53, v53
	v_fma_f32 v54, v54, s40, -v137
	v_fma_f32 v55, v55, s40, -v137
	v_fma_f32 v56, v56, s40, -v137
	v_mfma_f32_32x32x16_bf16 v[2:17], v[234:237], v[34:37], v[2:17]
	ds_read_b128 v[194:197], v136 offset:18528
	ds_read_b128 v[202:205], v136 offset:23136
	v_fma_f32 v57, v57, s40, -v137
	v_exp_f32_e32 v54, v54
	v_exp_f32_e32 v55, v55
	v_exp_f32_e32 v56, v56
	v_exp_f32_e32 v57, v57
	v_add_f32_e32 v134, v134, v50
	v_add_f32_e32 v177, v177, v51
	s_waitcnt lgkmcnt(4)
	v_mfma_f32_32x32x16_bf16 v[18:33], v[238:241], v[42:45], v[18:33]
	v_add_f32_e32 v134, v134, v52
	v_add_f32_e32 v177, v177, v53
	v_add_f32_e32 v134, v134, v54
	v_add_f32_e32 v177, v177, v55
	v_add_f32_e32 v134, v134, v56
	v_add_f32_e32 v177, v177, v57
	v_cvt_pk_bf16_f32 v50, v50, v51
	v_mfma_f32_32x32x16_bf16 v[2:17], v[242:245], v[42:45], v[2:17]
	v_cvt_pk_bf16_f32 v51, v52, v53
	v_cvt_pk_bf16_f32 v52, v54, v55
	v_cvt_pk_bf16_f32 v53, v56, v57
	v_fma_f32 v58, v58, s40, -v137
	v_fma_f32 v59, v59, s40, -v137
	v_fma_f32 v60, v60, s40, -v137
	v_fma_f32 v61, v61, s40, -v137
	v_exp_f32_e32 v58, v58
	v_exp_f32_e32 v59, v59
	v_exp_f32_e32 v60, v60
	v_exp_f32_e32 v61, v61
	s_waitcnt lgkmcnt(2)
	v_mfma_f32_32x32x16_bf16 v[18:33], v[186:189], v[50:53], v[18:33]
	v_fma_f32 v62, v62, s40, -v137
	v_fma_f32 v63, v63, s40, -v137
	v_fma_f32 v64, v64, s40, -v137
	v_fma_f32 v65, v65, s40, -v137
	v_exp_f32_e32 v62, v62
	v_exp_f32_e32 v63, v63
	v_exp_f32_e32 v64, v64
	v_exp_f32_e32 v65, v65
	v_add_f32_e32 v134, v134, v58
	v_add_f32_e32 v177, v177, v59
	v_add_f32_e32 v134, v134, v60
	v_add_f32_e32 v177, v177, v61
	v_add_f32_e32 v134, v134, v62
	v_add_f32_e32 v177, v177, v63
	v_mfma_f32_32x32x16_bf16 v[2:17], v[190:193], v[50:53], v[2:17]
	v_add_f32_e32 v134, v134, v64
	v_add_f32_e32 v177, v177, v65
	v_cvt_pk_bf16_f32 v58, v58, v59
	v_cvt_pk_bf16_f32 v59, v60, v61
	v_cvt_pk_bf16_f32 v60, v62, v63
	v_cvt_pk_bf16_f32 v61, v64, v65
	v_add_f32_e32 v134, v134, v177
	s_nop 0
	s_waitcnt lgkmcnt(0)
	v_mfma_f32_32x32x16_bf16 v[18:33], v[194:197], v[58:61], v[18:33]
	v_mfma_f32_32x32x16_bf16 v[2:17], v[202:205], v[58:61], v[2:17]
	s_branch .Lmla_coop2

; #define MFMA32(a, b, c) __builtin_amdgcn_mfma_f32_32x32x16_bf16((a), (b), (c), 0, 0, 0)
;     DI float* h() const { return (float*)(__attribute__((address_space(1))) float*)kp->out; }
; DI void pv_tile(lbf Vt, const f32x16& p0, const f32x16& p1, f32x16 (&O)[2], int r, int h) {
;     bf16x8 va0, va1, vb0, vb1;
;     pv_load(Vt, 0, r, h, va0, va1);
; #pragma unroll
;     for (int g = 0; g < 4; g += 2) {
;         pv_load(Vt, g + 1, r, h, vb0, vb1);
;         const bf16x8 pa = pack8(g >> 1 ? p1 : p0, 0);
;         __builtin_amdgcn_sched_barrier(0);
;         O[0] = MFMA32(va0, pa, O[0]); O[1] = MFMA32(va1, pa, O[1]);
;         __builtin_amdgcn_sched_barrier(0);
;         if (g + 2 < 4) pv_load(Vt, g + 2, r, h, va0, va1);
;         const bf16x8 pb = pack8(g >> 1 ? p1 : p0, 1);
;         __builtin_amdgcn_sched_barrier(0);
;         O[0] = MFMA32(vb0, pb, O[0]); O[1] = MFMA32(vb1, pb, O[1]);
;         __builtin_amdgcn_sched_barrier(0);
;     }
; }
; DI void online_raw(f32x16& s0, f32x16& s1, float c1, float& m, float& l, f32x16 (&O)[2]) {
;     ...
;     const float nmn = -m;
;     float ls = 0.f;
; #pragma unroll
;     for (int i = 0; i < 16; ++i) { s0[i] = __builtin_amdgcn_exp2f(fmaf(s0[i], c1, nmn)); s1[i] = __builtin_amdgcn_exp2f(fmaf(s1[i], c1, nmn)); ls += s0[i] + s1[i]; }
;     ls += __shfl_xor(ls, 32);
;     l += ls;
; }
.Lmla_rback_l2:
	v_fma_f32 v34, v34, s40, -v137
	v_fma_f32 v35, v35, s40, -v137
	v_fma_f32 v36, v36, s40, -v137
	v_fma_f32 v37, v37, s40, -v137
	v_exp_f32_e32 v34, v34
	v_exp_f32_e32 v35, v35
	v_exp_f32_e32 v36, v36
	v_exp_f32_e32 v37, v37
	v_fma_f32 v38, v38, s40, -v137
	v_fma_f32 v39, v39, s40, -v137
	v_fma_f32 v40, v40, s40, -v137
	v_fma_f32 v41, v41, s40, -v137
	v_exp_f32_e32 v38, v38
	v_exp_f32_e32 v39, v39
	v_exp_f32_e32 v40, v40
	v_exp_f32_e32 v41, v41
	v_add_f32_e32 v134, v134, v34
	v_add_f32_e32 v134, v134, v36
	v_add_f32_e32 v177, v35, v37
	v_add_f32_e32 v134, v134, v38
	v_add_f32_e32 v177, v177, v39
	v_add_f32_e32 v134, v134, v40
	v_add_f32_e32 v177, v177, v41
	v_cvt_pk_bf16_f32 v34, v34, v35
	v_cvt_pk_bf16_f32 v35, v36, v37
	v_cvt_pk_bf16_f32 v36, v38, v39
	v_cvt_pk_bf16_f32 v37, v40, v41
	v_fma_f32 v42, v42, s40, -v137
	v_fma_f32 v43, v43, s40, -v137
	v_fma_f32 v44, v44, s40, -v137
	v_fma_f32 v45, v45, s40, -v137
	v_exp_f32_e32 v42, v42
	v_exp_f32_e32 v43, v43
	v_exp_f32_e32 v44, v44
	v_exp_f32_e32 v45, v45
	s_waitcnt lgkmcnt(4)
	v_mfma_f32_32x32x16_bf16 v[18:33], v[186:189], v[34:37], v[18:33]
	v_fma_f32 v46, v46, s40, -v137
	v_fma_f32 v47, v47, s40, -v137
	v_fma_f32 v48, v48, s40, -v137
	v_fma_f32 v49, v49, s40, -v137
	v_exp_f32_e32 v46, v46
	v_exp_f32_e32 v47, v47
	v_exp_f32_e32 v48, v48
	v_exp_f32_e32 v49, v49
	v_add_f32_e32 v134, v134, v42
	v_add_f32_e32 v177, v177, v43
	v_add_f32_e32 v134, v134, v44
	v_add_f32_e32 v177, v177, v45
	v_add_f32_e32 v134, v134, v46
	v_add_f32_e32 v177, v177, v47
	v_mfma_f32_32x32x16_bf16 v[2:17], v[190:193], v[34:37], v[2:17]
	ds_read_b128 v[238:241], v136 offset:18528
	ds_read_b128 v[242:245], v136 offset:23136
	v_add_f32_e32 v134, v134, v48
	v_add_f32_e32 v177, v177, v49
	v_cvt_pk_bf16_f32 v42, v42, v43
	v_cvt_pk_bf16_f32 v43, v44, v45
	v_cvt_pk_bf16_f32 v44, v46, v47
	v_cvt_pk_bf16_f32 v45, v48, v49
	v_fma_f32 v50, v50, s40, -v137
	v_fma_f32 v51, v51, s40, -v137
	v_fma_f32 v52, v52, s40, -v137
	v_fma_f32 v53, v53, s40, -v137
	v_exp_f32_e32 v50, v50
	v_exp_f32_e32 v51, v51
	v_exp_f32_e32 v52, v52
	v_exp_f32_e32 v53, v53
	s_waitcnt lgkmcnt(4)
	v_mfma_f32_32x32x16_bf16 v[18:33], v[194:197], v[42:45], v[18:33]
	v_fma_f32 v54, v54, s40, -v137
	v_fma_f32 v55, v55, s40, -v137
	v_fma_f32 v56, v56, s40, -v137
	v_fma_f32 v57, v57, s40, -v137
	v_exp_f32_e32 v54, v54
	v_exp_f32_e32 v55, v55
	v_exp_f32_e32 v56, v56
	v_exp_f32_e32 v57, v57
	v_add_f32_e32 v134, v134, v50
	v_add_f32_e32 v177, v177, v51
	v_add_f32_e32 v134, v134, v52
	v_add_f32_e32 v177, v177, v53
	v_add_f32_e32 v134, v134, v54
	v_add_f32_e32 v177, v177, v55
	v_mfma_f32_32x32x16_bf16 v[2:17], v[202:205], v[42:45], v[2:17]
	v_add_f32_e32 v134, v134, v56
	v_add_f32_e32 v177, v177, v57
	v_cvt_pk_bf16_f32 v50, v50, v51
	v_cvt_pk_bf16_f32 v51, v52, v53
	v_cvt_pk_bf16_f32 v52, v54, v55
	v_cvt_pk_bf16_f32 v53, v56, v57
	v_fma_f32 v58, v58, s40, -v137
	v_fma_f32 v59, v59, s40, -v137
	v_fma_f32 v60, v60, s40, -v137
	v_fma_f32 v61, v61, s40, -v137
	v_exp_f32_e32 v58, v58
	v_exp_f32_e32 v59, v59
	v_exp_f32_e32 v60, v60
	v_exp_f32_e32 v61, v61
	s_waitcnt lgkmcnt(2)
	v_mfma_f32_32x32x16_bf16 v[18:33], v[210:213], v[50:53], v[18:33]
	v_fma_f32 v62, v62, s40, -v137
	v_fma_f32 v63, v63, s40, -v137
	v_fma_f32 v64, v64, s40, -v137
	v_fma_f32 v65, v65, s40, -v137
	v_exp_f32_e32 v62, v62
	v_exp_f32_e32 v63, v63
	v_exp_f32_e32 v64, v64
	v_exp_f32_e32 v65, v65
	v_add_f32_e32 v134, v134, v58
	v_add_f32_e32 v177, v177, v59
	v_add_f32_e32 v134, v134, v60
	v_add_f32_e32 v177, v177, v61
	v_add_f32_e32 v134, v134, v62
	v_add_f32_e32 v177, v177, v63
	v_mfma_f32_32x32x16_bf16 v[2:17], v[234:237], v[50:53], v[2:17]
	v_add_f32_e32 v134, v134, v64
	v_add_f32_e32 v177, v177, v65
	v_cvt_pk_bf16_f32 v58, v58, v59
	v_cvt_pk_bf16_f32 v59, v60, v61
	v_cvt_pk_bf16_f32 v60, v62, v63
	v_cvt_pk_bf16_f32 v61, v64, v65
	v_add_f32_e32 v134, v134, v177
	s_nop 0
	s_waitcnt lgkmcnt(0)
	v_mfma_f32_32x32x16_bf16 v[18:33], v[238:241], v[58:61], v[18:33]
	v_mfma_f32_32x32x16_bf16 v[2:17], v[242:245], v[58:61], v[2:17]

; #define MFMA32(a, b, c) __builtin_amdgcn_mfma_f32_32x32x16_bf16((a), (b), (c), 0, 0, 0)
; #define PG8_LAS __attribute__((address_space(3)))
;     DI float* b1(int l, int v) const { return (float*)(ws + WS_B1) + (l * 2 + v) * 128; }
;     DI float* h() const { return (float*)(__attribute__((address_space(1))) float*)kp->out; }
; template <int KS> DI void qk_tile(lbf Ks, const bf16x8 (&Q)[KS], f32x16& s0, f32x16& s1, int r, int h) {
;     constexpr int KLD = KS == 6 ? 104 : 72;
; #pragma unroll
;     for (int i = 0; i < 16; ++i) { s0[i] = 0.f; s1[i] = 0.f; }
;     const PG8_LAS bf16x8* p0 = (const PG8_LAS bf16x8*)(Ks + r * KLD + 8 * h); const PG8_LAS bf16x8* p1 = (const PG8_LAS bf16x8*)(Ks + (32 + r) * KLD + 8 * h);
;     bf16x8 a0 = p0[0], a1 = p1[0], b0, b1;
; #pragma unroll
;     for (int ks = 0; ks < KS; ks += 2) {
;         b0 = p0[2 * (ks + 1)]; b1 = p1[2 * (ks + 1)];
;         __builtin_amdgcn_sched_barrier(0);
;         s0 = MFMA32(a0, Q[ks], s0); s1 = MFMA32(a1, Q[ks], s1);
;         __builtin_amdgcn_sched_barrier(0);
;         if (ks + 2 < KS) { a0 = p0[2 * (ks + 2)]; a1 = p1[2 * (ks + 2)]; }
;         __builtin_amdgcn_sched_barrier(0);
;         s0 = MFMA32(b0, Q[ks + 1], s0); s1 = MFMA32(b1, Q[ks + 1], s1);
;         __builtin_amdgcn_sched_barrier(0);
;     }
; }
; DI void online_raw(f32x16& s0, f32x16& s1, float c1, float& m, float& l, f32x16 (&O)[2]) {
;     float mx = fmaxf(s0[0], s1[0]);
; #pragma unroll
;     for (int i = 1; i < 16; ++i) mx = fmaxf(mx, fmaxf(s0[i], s1[i]));
;     mx = fmaxf(mx, __shfl_xor(mx, 32));
;     const float mxe = mx * c1;
;     if (__any(mxe - m > 8.f)) {
;         const float mn = fmaxf(m, mxe), alpha = __builtin_amdgcn_exp2f(m - mn);
;         l *= alpha; m = mn;
; #pragma unroll
;         for (int i = 0; i < 16; ++i) { O[0][i] *= alpha; O[1][i] *= alpha; }
;     }
;     const float nmn = -m;
;     float ls = 0.f;
; #pragma unroll
;     for (int i = 0; i < 16; ++i) { s0[i] = __builtin_amdgcn_exp2f(fmaf(s0[i], c1, nmn)); s1[i] = __builtin_amdgcn_exp2f(fmaf(s1[i], c1, nmn)); ls += s0[i] + s1[i]; }
;     ls += __shfl_xor(ls, 32);
;     l += ls;
; }
.Lmla_full3:
	ds_read_b128 v[186:189], v135 offset:0
	ds_read_b128 v[190:193], v135 offset:6656
	ds_read_b128 v[194:197], v135 offset:32
	ds_read_b128 v[202:205], v135 offset:6688
	ds_read_b128 v[210:213], v135 offset:64
	ds_read_b128 v[234:237], v135 offset:6720
	global_load_dwordx4 v[106:109], v118, s[10:11]
	global_load_dwordx4 v[102:105], v119, s[10:11] offset:1024
	global_load_dwordx4 v[110:113], v120, s[48:49]
	v_max3_f32 v170, v138, v139, v140
	v_max3_f32 v176, v141, v142, v143
	v_max3_f32 v170, v170, v144, v145
	v_max3_f32 v176, v176, v146, v147
	s_waitcnt lgkmcnt(4)
	v_mfma_f32_32x32x16_bf16 v[34:49], v[186:189], v[66:69], 0
	v_max3_f32 v170, v170, v148, v149
	v_max3_f32 v176, v176, v150, v151
	v_max3_f32 v170, v170, v152, v153
	v_max3_f32 v176, v176, v154, v155
	v_mfma_f32_32x32x16_bf16 v[50:65], v[190:193], v[66:69], 0
	ds_read_b128 v[238:241], v135 offset:96
	ds_read_b128 v[242:245], v135 offset:6752
	v_max3_f32 v170, v170, v156, v157
	v_max3_f32 v176, v176, v158, v159
	v_max3_f32 v170, v170, v160, v161
	v_max3_f32 v176, v176, v162, v163
	s_waitcnt lgkmcnt(4)
	v_mfma_f32_32x32x16_bf16 v[34:49], v[194:197], v[70:73], v[34:49]
	v_max3_f32 v170, v170, v164, v165
	v_max3_f32 v176, v176, v166, v167
	v_max3_f32 v170, v170, v168, v169
	v_max_f32_e32 v170, v170, v176
	v_mfma_f32_32x32x16_bf16 v[50:65], v[202:205], v[70:73], v[50:65]
	ds_read_b128 v[186:189], v135 offset:128
	ds_read_b128 v[190:193], v135 offset:6784
	v_mov_b32_e32 v176, v170
	s_nop 1
	v_permlane32_swap_b32_e32 v176, v170
	v_max_f32_e32 v170, v170, v176
	v_fma_f32 v176, v170, s40, -v137
	v_cmp_lt_f32_e32 vcc, s28, v176
	s_cbranch_vccnz .Lmla_resc_f3
.Lmla_rback_f3:
	v_fma_f32 v138, v138, s40, -v137
	v_fma_f32 v139, v139, s40, -v137
	v_fma_f32 v140, v140, s40, -v137
	v_fma_f32 v141, v141, s40, -v137
	s_waitcnt lgkmcnt(4)
	v_mfma_f32_32x32x16_bf16 v[34:49], v[210:213], v[74:77], v[34:49]
	v_exp_f32_e32 v138, v138
	v_exp_f32_e32 v139, v139
	v_exp_f32_e32 v140, v140
	v_exp_f32_e32 v141, v141
	v_fma_f32 v142, v142, s40, -v137
	v_fma_f32 v143, v143, s40, -v137
	v_fma_f32 v144, v144, s40, -v137
	v_mfma_f32_32x32x16_bf16 v[50:65], v[234:237], v[74:77], v[50:65]
	ds_read_b128 v[194:197], v135 offset:160
	ds_read_b128 v[202:205], v135 offset:6816
	v_fma_f32 v145, v145, s40, -v137
	v_exp_f32_e32 v142, v142
	v_exp_f32_e32 v143, v143
	v_exp_f32_e32 v144, v144
	v_exp_f32_e32 v145, v145
	v_add_f32_e32 v134, v134, v138
	s_waitcnt lgkmcnt(4)
	v_mfma_f32_32x32x16_bf16 v[34:49], v[238:241], v[78:81], v[34:49]
	v_add_f32_e32 v134, v134, v140
	v_add_f32_e32 v177, v139, v141
	v_add_f32_e32 v134, v134, v142
	v_add_f32_e32 v177, v177, v143
	v_add_f32_e32 v134, v134, v144
	v_add_f32_e32 v177, v177, v145
	v_cvt_pk_bf16_f32 v138, v138, v139
	v_mfma_f32_32x32x16_bf16 v[50:65], v[242:245], v[78:81], v[50:65]
	ds_read_b128 v[210:213], v136 offset:27648
	ds_read_b128 v[234:237], v136 offset:32256
	v_cvt_pk_bf16_f32 v139, v140, v141
	v_cvt_pk_bf16_f32 v140, v142, v143
	v_cvt_pk_bf16_f32 v141, v144, v145
	v_fma_f32 v146, v146, s40, -v137
	v_fma_f32 v147, v147, s40, -v137
	v_fma_f32 v148, v148, s40, -v137
	v_fma_f32 v149, v149, s40, -v137
	s_waitcnt lgkmcnt(4)
	v_mfma_f32_32x32x16_bf16 v[34:49], v[186:189], v[94:97], v[34:49]
	v_exp_f32_e32 v146, v146
	v_exp_f32_e32 v147, v147
	v_exp_f32_e32 v148, v148
	v_exp_f32_e32 v149, v149
	v_fma_f32 v150, v150, s40, -v137
	v_fma_f32 v151, v151, s40, -v137
	v_fma_f32 v152, v152, s40, -v137
	v_mfma_f32_32x32x16_bf16 v[50:65], v[190:193], v[94:97], v[50:65]
	ds_read_b128 v[238:241], v136 offset:27680
	ds_read_b128 v[242:245], v136 offset:32288
	v_fma_f32 v153, v153, s40, -v137
	v_exp_f32_e32 v150, v150
	v_exp_f32_e32 v151, v151
	v_exp_f32_e32 v152, v152
	v_exp_f32_e32 v153, v153
	v_add_f32_e32 v134, v134, v146
	v_add_f32_e32 v177, v177, v147
	s_waitcnt lgkmcnt(4)
	v_mfma_f32_32x32x16_bf16 v[34:49], v[194:197], v[98:101], v[34:49]
	v_add_f32_e32 v134, v134, v148
	v_add_f32_e32 v177, v177, v149
	v_add_f32_e32 v134, v134, v150
	v_add_f32_e32 v177, v177, v151
	v_add_f32_e32 v134, v134, v152
	v_add_f32_e32 v177, v177, v153
	v_cvt_pk_bf16_f32 v146, v146, v147
	v_mfma_f32_32x32x16_bf16 v[50:65], v[202:205], v[98:101], v[50:65]
	ds_read_b128 v[186:189], v136 offset:27712
	ds_read_b128 v[190:193], v136 offset:32320
	v_cvt_pk_bf16_f32 v147, v148, v149
	v_cvt_pk_bf16_f32 v148, v150, v151
	v_cvt_pk_bf16_f32 v149, v152, v153
	v_fma_f32 v154, v154, s40, -v137
	v_fma_f32 v155, v155, s40, -v137
	v_fma_f32 v156, v156, s40, -v137
	v_fma_f32 v157, v157, s40, -v137
	s_waitcnt lgkmcnt(4)
	v_mfma_f32_32x32x16_bf16 v[18:33], v[210:213], v[138:141], v[18:33]
	v_exp_f32_e32 v154, v154
	v_exp_f32_e32 v155, v155
	v_exp_f32_e32 v156, v156
	v_exp_f32_e32 v157, v157
	v_fma_f32 v158, v158, s40, -v137
	v_fma_f32 v159, v159, s40, -v137
	v_fma_f32 v160, v160, s40, -v137
	v_mfma_f32_32x32x16_bf16 v[2:17], v[234:237], v[138:141], v[2:17]
	ds_read_b128 v[194:197], v136 offset:27744
	ds_read_b128 v[202:205], v136 offset:32352
	v_fma_f32 v161, v161, s40, -v137
	v_exp_f32_e32 v158, v158
	v_exp_f32_e32 v159, v159
	v_exp_f32_e32 v160, v160
	v_exp_f32_e32 v161, v161
	v_add_f32_e32 v134, v134, v154
	v_add_f32_e32 v177, v177, v155
	s_waitcnt lgkmcnt(4)
	v_mfma_f32_32x32x16_bf16 v[18:33], v[238:241], v[146:149], v[18:33]
	v_add_f32_e32 v134, v134, v156
	v_add_f32_e32 v177, v177, v157
	v_add_f32_e32 v134, v134, v158
	v_add_f32_e32 v177, v177, v159
	v_add_f32_e32 v134, v134, v160
	v_add_f32_e32 v177, v177, v161
	v_cvt_pk_bf16_f32 v154, v154, v155
	v_mfma_f32_32x32x16_bf16 v[2:17], v[242:245], v[146:149], v[2:17]
	v_cvt_pk_bf16_f32 v155, v156, v157
	v_cvt_pk_bf16_f32 v156, v158, v159
	v_cvt_pk_bf16_f32 v157, v160, v161
	v_fma_f32 v162, v162, s40, -v137
	v_fma_f32 v163, v163, s40, -v137
	v_fma_f32 v164, v164, s40, -v137
	v_fma_f32 v165, v165, s40, -v137
	v_exp_f32_e32 v162, v162
	v_exp_f32_e32 v163, v163
	v_exp_f32_e32 v164, v164
	v_exp_f32_e32 v165, v165
	s_waitcnt lgkmcnt(2)
	v_mfma_f32_32x32x16_bf16 v[18:33], v[186:189], v[154:157], v[18:33]
	v_fma_f32 v166, v166, s40, -v137
	v_fma_f32 v167, v167, s40, -v137
	v_fma_f32 v168, v168, s40, -v137
	v_fma_f32 v169, v169, s40, -v137
	v_exp_f32_e32 v166, v166
	v_exp_f32_e32 v167, v167
	v_exp_f32_e32 v168, v168
	v_exp_f32_e32 v169, v169
	v_add_f32_e32 v134, v134, v162
	v_add_f32_e32 v177, v177, v163
	v_add_f32_e32 v134, v134, v164
	v_add_f32_e32 v177, v177, v165
	v_add_f32_e32 v134, v134, v166
	v_add_f32_e32 v177, v177, v167
	v_mfma_f32_32x32x16_bf16 v[2:17], v[190:193], v[154:157], v[2:17]
	v_add_f32_e32 v134, v134, v168
	v_add_f32_e32 v177, v177, v169
	v_cvt_pk_bf16_f32 v162, v162, v163
	v_cvt_pk_bf16_f32 v163, v164, v165
	v_cvt_pk_bf16_f32 v164, v166, v167
	v_cvt_pk_bf16_f32 v165, v168, v169
	v_add_f32_e32 v134, v134, v177
	s_nop 0
	s_waitcnt lgkmcnt(0)
	v_mfma_f32_32x32x16_bf16 v[18:33], v[194:197], v[162:165], v[18:33]
	v_mfma_f32_32x32x16_bf16 v[2:17], v[202:205], v[162:165], v[2:17]
	s_branch .Lmla_coop3

; #define MFMA32(a, b, c) __builtin_amdgcn_mfma_f32_32x32x16_bf16((a), (b), (c), 0, 0, 0)
;     DI float* h() const { return (float*)(__attribute__((address_space(1))) float*)kp->out; }
; DI void pv_tile(lbf Vt, const f32x16& p0, const f32x16& p1, f32x16 (&O)[2], int r, int h) {
;     bf16x8 va0, va1, vb0, vb1;
;     pv_load(Vt, 0, r, h, va0, va1);
; #pragma unroll
;     for (int g = 0; g < 4; g += 2) {
;         pv_load(Vt, g + 1, r, h, vb0, vb1);
;         const bf16x8 pa = pack8(g >> 1 ? p1 : p0, 0);
;         __builtin_amdgcn_sched_barrier(0);
;         O[0] = MFMA32(va0, pa, O[0]); O[1] = MFMA32(va1, pa, O[1]);
;         __builtin_amdgcn_sched_barrier(0);
;         if (g + 2 < 4) pv_load(Vt, g + 2, r, h, va0, va1);
;         const bf16x8 pb = pack8(g >> 1 ? p1 : p0, 1);
;         __builtin_amdgcn_sched_barrier(0);
;         O[0] = MFMA32(vb0, pb, O[0]); O[1] = MFMA32(vb1, pb, O[1]);
;         __builtin_amdgcn_sched_barrier(0);
;     }
; }
; DI void online_raw(f32x16& s0, f32x16& s1, float c1, float& m, float& l, f32x16 (&O)[2]) {
;     ...
;     const float nmn = -m;
;     float ls = 0.f;
; #pragma unroll
;     for (int i = 0; i < 16; ++i) { s0[i] = __builtin_amdgcn_exp2f(fmaf(s0[i], c1, nmn)); s1[i] = __builtin_amdgcn_exp2f(fmaf(s1[i], c1, nmn)); ls += s0[i] + s1[i]; }
;     ls += __shfl_xor(ls, 32);
;     l += ls;
; }
.Lmla_rback_l3:
	v_fma_f32 v138, v138, s40, -v137
	v_fma_f32 v139, v139, s40, -v137
	v_fma_f32 v140, v140, s40, -v137
	v_fma_f32 v141, v141, s40, -v137
	v_exp_f32_e32 v138, v138
	v_exp_f32_e32 v139, v139
	v_exp_f32_e32 v140, v140
	v_exp_f32_e32 v141, v141
	v_fma_f32 v142, v142, s40, -v137
	v_fma_f32 v143, v143, s40, -v137
	v_fma_f32 v144, v144, s40, -v137
	v_fma_f32 v145, v145, s40, -v137
	v_exp_f32_e32 v142, v142
	v_exp_f32_e32 v143, v143
	v_exp_f32_e32 v144, v144
	v_exp_f32_e32 v145, v145
	v_add_f32_e32 v134, v134, v138
	v_add_f32_e32 v134, v134, v140
	v_add_f32_e32 v177, v139, v141
	v_add_f32_e32 v134, v134, v142
	v_add_f32_e32 v177, v177, v143
	v_add_f32_e32 v134, v134, v144
	v_add_f32_e32 v177, v177, v145
	v_cvt_pk_bf16_f32 v138, v138, v139
	v_cvt_pk_bf16_f32 v139, v140, v141
	v_cvt_pk_bf16_f32 v140, v142, v143
	v_cvt_pk_bf16_f32 v141, v144, v145
	v_fma_f32 v146, v146, s40, -v137
	v_fma_f32 v147, v147, s40, -v137
	v_fma_f32 v148, v148, s40, -v137
	v_fma_f32 v149, v149, s40, -v137
	v_exp_f32_e32 v146, v146
	v_exp_f32_e32 v147, v147
	v_exp_f32_e32 v148, v148
	v_exp_f32_e32 v149, v149
	s_waitcnt lgkmcnt(4)
	v_mfma_f32_32x32x16_bf16 v[18:33], v[186:189], v[138:141], v[18:33]
	v_fma_f32 v150, v150, s40, -v137
	v_fma_f32 v151, v151, s40, -v137
	v_fma_f32 v152, v152, s40, -v137
	v_fma_f32 v153, v153, s40, -v137
	v_exp_f32_e32 v150, v150
	v_exp_f32_e32 v151, v151
	v_exp_f32_e32 v152, v152
	v_exp_f32_e32 v153, v153
	v_add_f32_e32 v134, v134, v146
	v_add_f32_e32 v177, v177, v147
	v_add_f32_e32 v134, v134, v148
	v_add_f32_e32 v177, v177, v149
	v_add_f32_e32 v134, v134, v150
	v_add_f32_e32 v177, v177, v151
	v_mfma_f32_32x32x16_bf16 v[2:17], v[190:193], v[138:141], v[2:17]
	ds_read_b128 v[238:241], v136 offset:27744
	ds_read_b128 v[242:245], v136 offset:32352
	v_add_f32_e32 v134, v134, v152
	v_add_f32_e32 v177, v177, v153
	v_cvt_pk_bf16_f32 v146, v146, v147
	v_cvt_pk_bf16_f32 v147, v148, v149
	v_cvt_pk_bf16_f32 v148, v150, v151
	v_cvt_pk_bf16_f32 v149, v152, v153
	v_fma_f32 v154, v154, s40, -v137
	v_fma_f32 v155, v155, s40, -v137
	v_fma_f32 v156, v156, s40, -v137
	v_fma_f32 v157, v157, s40, -v137
	v_exp_f32_e32 v154, v154
	v_exp_f32_e32 v155, v155
	v_exp_f32_e32 v156, v156
	v_exp_f32_e32 v157, v157
	s_waitcnt lgkmcnt(4)
	v_mfma_f32_32x32x16_bf16 v[18:33], v[194:197], v[146:149], v[18:33]
	v_fma_f32 v158, v158, s40, -v137
	v_fma_f32 v159, v159, s40, -v137
	v_fma_f32 v160, v160, s40, -v137
	v_fma_f32 v161, v161, s40, -v137
	v_exp_f32_e32 v158, v158
	v_exp_f32_e32 v159, v159
	v_exp_f32_e32 v160, v160
	v_exp_f32_e32 v161, v161
	v_add_f32_e32 v134, v134, v154
	v_add_f32_e32 v177, v177, v155
	v_add_f32_e32 v134, v134, v156
	v_add_f32_e32 v177, v177, v157
	v_add_f32_e32 v134, v134, v158
	v_add_f32_e32 v177, v177, v159
	v_mfma_f32_32x32x16_bf16 v[2:17], v[202:205], v[146:149], v[2:17]
	v_add_f32_e32 v134, v134, v160
	v_add_f32_e32 v177, v177, v161
	v_cvt_pk_bf16_f32 v154, v154, v155
	v_cvt_pk_bf16_f32 v155, v156, v157
	v_cvt_pk_bf16_f32 v156, v158, v159
	v_cvt_pk_bf16_f32 v157, v160, v161
	v_fma_f32 v162, v162, s40, -v137
	v_fma_f32 v163, v163, s40, -v137
	v_fma_f32 v164, v164, s40, -v137
	v_fma_f32 v165, v165, s40, -v137
	v_exp_f32_e32 v162, v162
	v_exp_f32_e32 v163, v163
	v_exp_f32_e32 v164, v164
	v_exp_f32_e32 v165, v165
	s_waitcnt lgkmcnt(2)
	v_mfma_f32_32x32x16_bf16 v[18:33], v[210:213], v[154:157], v[18:33]
	v_fma_f32 v166, v166, s40, -v137
	v_fma_f32 v167, v167, s40, -v137
	v_fma_f32 v168, v168, s40, -v137
	v_fma_f32 v169, v169, s40, -v137
	v_exp_f32_e32 v166, v166
	v_exp_f32_e32 v167, v167
	v_exp_f32_e32 v168, v168
	v_exp_f32_e32 v169, v169
	v_add_f32_e32 v134, v134, v162
	v_add_f32_e32 v177, v177, v163
	v_add_f32_e32 v134, v134, v164
	v_add_f32_e32 v177, v177, v165
	v_add_f32_e32 v134, v134, v166
	v_add_f32_e32 v177, v177, v167
	v_mfma_f32_32x32x16_bf16 v[2:17], v[234:237], v[154:157], v[2:17]
	v_add_f32_e32 v134, v134, v168
	v_add_f32_e32 v177, v177, v169
	v_cvt_pk_bf16_f32 v162, v162, v163
	v_cvt_pk_bf16_f32 v163, v164, v165
	v_cvt_pk_bf16_f32 v164, v166, v167
	v_cvt_pk_bf16_f32 v165, v168, v169
	v_add_f32_e32 v134, v134, v177
	s_nop 0
	s_waitcnt lgkmcnt(0)
	v_mfma_f32_32x32x16_bf16 v[18:33], v[238:241], v[162:165], v[18:33]
	v_mfma_f32_32x32x16_bf16 v[2:17], v[242:245], v[162:165], v[2:17]

; DI float gelu_tanh(float x) { return 0.5f * x * (1.f + tanhf(0.7978845608028654f * (x + 0.044715f * x * x * x))); }
;     DI bf16_t* z() const { return (bf16_t*)(ws + WS_Z); }
;     DI float* ssqz() const { return (float*)(ws + WS_SSQZ); }
; DI float rstd_q(const float* ssqz, int row) {
;     const f32x4* p = (const f32x4*)(ssqz + (size_t)row * 24); float s = 0.f;
; #pragma unroll
;     for (int i = 0; i < 3; ++i) { f32x4 v = p[i]; s += (v[0] + v[1]) + (v[2] + v[3]); }
;     return rsqrtf(s * (1.f / 384.f) + EPS);
; }
;     __device__ __forceinline__ void operator()(const f32x4 (&acc)[2][2][4][2], const Unit& u, int wr, int wc, int fr, int fq) const {
;         const int row0 = u.pm * BM + wr * 64 + fr, col0 = u.pn * BM + wc * 32 + 8 * fq;
; #pragma unroll
;         for (int ai = 0; ai < 2; ++ai)
; #pragma unroll
;             for (int m = 0; m < 4; ++m) {
;                 const int row = row0 + ai * HALF + m * 16;
;                 float sc = 1.f;
;                 if (MODE == EM_SCALEH) sc = ::rstd_h(ssq_in, row + rowoff);
;                 if (MODE == EM_SCALEQ) sc = ::rstd_q(ssq_in, row);
;                 if (MODE == EM_SCALEKV) sc = ::rstd_kv(ssq_in, row);
;                 float ss[2] = {0.f, 0.f};
; #pragma unroll
;                 for (int bj = 0; bj < 2; ++bj) {
;                     const int col = col0 + bj * HALF;
;                     f32x4 v0 = acc[ai][bj][m][0] * sc, v1 = acc[ai][bj][m][1] * sc;
;                     if (MODE == EM_GELU) { if (col < nvalid) { const f32x4 b0 = *(const f32x4*)(bias + col), b1 = *(const f32x4*)(bias + col + 4);
; #pragma unroll
;                         for (int i = 0; i < 4; ++i) { v0[i] = ::gelu_tanh(v0[i] + b0[i]); v1[i] = ::gelu_tanh(v1[i] + b1[i]); } } }
;                     if (MODE == EM_RES) { const f32x4* hi = (const f32x4*)(Hin + (size_t)row * 1024 + col); f32x4* hp = (f32x4*)(H + (size_t)row * 1024 + col); v0 += hi[0]; v1 += hi[1]; hp[0] = v0; hp[1] = v1; }
;                     if (STATS) ss[bj] = ((v0[0] * v0[0] + v0[1] * v0[1]) + (v0[2] * v0[2] + v0[3] * v0[3])) + ((v1[0] * v1[0] + v1[1] * v1[1]) + (v1[2] * v1[2] + v1[3] * v1[3]));
;                     if (col < nvalid) { u32x4 w; w.x = cvt_pk_bf16(v0[0], v0[1]); w.y = cvt_pk_bf16(v0[2], v0[3]); w.z = cvt_pk_bf16(v1[0], v1[1]); w.w = cvt_pk_bf16(v1[2], v1[3]);
;                         *(u32x4*)(O + (size_t)row * ldc + col) = w; }
.LBB0_1530:
	v_and_b32_e32 v251, 48, v221
	v_xor_b32_e32 v213, 16, v221
	v_lshlrev_b32_e32 v213, 2, v213
	v_min_u32_e32 v212, 32, v251
	v_lshl_add_u32 v212, v144, 6, v212
	v_lshl_add_u32 v212, v144, 5, v212
	v_lshlrev_b32_e32 v211, 1, v146
	v_lshl_add_u32 v211, v144, 10, v211
	v_lshl_add_u32 v211, v144, 9, v211
	s_mul_i32 s32, s46, 0x60000
	s_add_u32 s24, s50, s32
	s_addc_u32 s25, s51, 0
	s_lshl_b32 s32, s8, 9
	s_add_u32 s24, s24, s32
	s_addc_u32 s25, s25, 0
	s_mul_i32 s32, s46, 0x6000
	s_add_u32 s60, s10, s32
	s_addc_u32 s61, s11, 0
	global_load_dwordx4 v[140:143], v212, s[60:61]
	s_add_u32 s60, s60, 0x600
	s_addc_u32 s61, s61, 0
	global_load_dwordx4 v[150:153], v212, s[60:61]
	s_add_u32 s60, s60, 0x600
	s_addc_u32 s61, s61, 0
	global_load_dwordx4 v[154:157], v212, s[60:61]
	s_add_u32 s60, s60, 0x600
	s_addc_u32 s61, s61, 0
	global_load_dwordx4 v[158:161], v212, s[60:61]
	s_add_u32 s60, s60, 0x1e00
	s_addc_u32 s61, s61, 0
	global_load_dwordx4 v[162:165], v212, s[60:61]
	s_add_u32 s60, s60, 0x600
	s_addc_u32 s61, s61, 0
	global_load_dwordx4 v[166:169], v212, s[60:61]
	s_add_u32 s60, s60, 0x600
	s_addc_u32 s61, s61, 0
	global_load_dwordx4 v[186:189], v212, s[60:61]
	s_add_u32 s60, s60, 0x600
	s_addc_u32 s61, s61, 0
	global_load_dwordx4 v[190:193], v212, s[60:61]
	s_waitcnt vmcnt(0)
	v_add_f32_e32 v194, v140, v141
	v_add_f32_e32 v202, v142, v143
	v_add_f32_e32 v195, v150, v151
	v_add_f32_e32 v203, v152, v153
	v_add_f32_e32 v196, v154, v155
	v_add_f32_e32 v204, v156, v157
	v_add_f32_e32 v197, v158, v159
	v_add_f32_e32 v205, v160, v161
	v_add_f32_e32 v198, v162, v163
	v_add_f32_e32 v206, v164, v165
	v_add_f32_e32 v199, v166, v167
	v_add_f32_e32 v207, v168, v169
	v_add_f32_e32 v200, v186, v187
	v_add_f32_e32 v208, v188, v189
	v_add_f32_e32 v201, v190, v191
	v_add_f32_e32 v210, v192, v193
	v_add_f32_e32 v194, v194, v202
	v_add_f32_e32 v195, v195, v203
	v_add_f32_e32 v196, v196, v204
	v_add_f32_e32 v197, v197, v205
	v_add_f32_e32 v198, v198, v206
	v_add_f32_e32 v199, v199, v207
	v_add_f32_e32 v200, v200, v208
	v_add_f32_e32 v201, v201, v210
	v_cmp_gt_u32_e32 vcc, 48, v251
	s_nop 1
	v_cndmask_b32_e32 v194, 0, v194, vcc
	v_cndmask_b32_e32 v195, 0, v195, vcc
	v_cndmask_b32_e32 v196, 0, v196, vcc
	v_cndmask_b32_e32 v197, 0, v197, vcc
	v_cndmask_b32_e32 v198, 0, v198, vcc
	v_cndmask_b32_e32 v199, 0, v199, vcc
	v_cndmask_b32_e32 v200, 0, v200, vcc
	v_cndmask_b32_e32 v201, 0, v201, vcc
	ds_bpermute_b32 v202, v213, v194
	ds_bpermute_b32 v203, v213, v195
	ds_bpermute_b32 v204, v213, v196
	ds_bpermute_b32 v205, v213, v197
	ds_bpermute_b32 v206, v213, v198
	ds_bpermute_b32 v207, v213, v199
	ds_bpermute_b32 v208, v213, v200
	ds_bpermute_b32 v210, v213, v201
	s_waitcnt lgkmcnt(0)
	v_add_f32_e32 v194, v194, v202
	v_add_f32_e32 v195, v195, v203
	v_add_f32_e32 v196, v196, v204
	v_add_f32_e32 v197, v197, v205
	v_add_f32_e32 v198, v198, v206
	v_add_f32_e32 v199, v199, v207
	v_add_f32_e32 v200, v200, v208
	v_add_f32_e32 v201, v201, v210
	v_mov_b32_e32 v202, v194
	v_mov_b32_e32 v203, v195
	v_mov_b32_e32 v204, v196
	v_mov_b32_e32 v205, v197
	v_mov_b32_e32 v206, v198
	v_mov_b32_e32 v207, v199
	v_mov_b32_e32 v208, v200
	v_mov_b32_e32 v210, v201
	s_nop 1
	v_permlane32_swap_b32_e32 v202, v194
	v_permlane32_swap_b32_e32 v203, v195
	v_permlane32_swap_b32_e32 v204, v196
	v_permlane32_swap_b32_e32 v205, v197
	v_permlane32_swap_b32_e32 v206, v198
	v_permlane32_swap_b32_e32 v207, v199
	v_permlane32_swap_b32_e32 v208, v200
	v_permlane32_swap_b32_e32 v210, v201
	v_add_f32_e32 v194, v194, v202
	v_add_f32_e32 v195, v195, v203
	v_add_f32_e32 v196, v196, v204
	v_add_f32_e32 v197, v197, v205
	v_add_f32_e32 v198, v198, v206
	v_add_f32_e32 v199, v199, v207
	v_add_f32_e32 v200, v200, v208
	v_add_f32_e32 v201, v201, v210
	s_mov_b32 s32, 0x800000
	v_fmamk_f32 v194, v194, 0x3b2aaaab, v215
	v_cmp_gt_f32_e32 vcc, s32, v194
	v_mul_f32_e32 v202, 0x4b800000, v194
	s_nop 0
	v_cndmask_b32_e32 v194, v194, v202, vcc
	v_rsq_f32_e32 v194, v194
	s_nop 0
	v_mul_f32_e32 v202, 0x45800000, v194
	v_cndmask_b32_e32 v194, v194, v202, vcc
	v_fmamk_f32 v195, v195, 0x3b2aaaab, v215
	v_cmp_gt_f32_e32 vcc, s32, v195
	v_mul_f32_e32 v203, 0x4b800000, v195
	s_nop 0
	v_cndmask_b32_e32 v195, v195, v203, vcc
	v_rsq_f32_e32 v195, v195
	s_nop 0
	v_mul_f32_e32 v203, 0x45800000, v195
	v_cndmask_b32_e32 v195, v195, v203, vcc
	v_fmamk_f32 v196, v196, 0x3b2aaaab, v215
	v_cmp_gt_f32_e32 vcc, s32, v196
	v_mul_f32_e32 v204, 0x4b800000, v196
	s_nop 0
	v_cndmask_b32_e32 v196, v196, v204, vcc
	v_rsq_f32_e32 v196, v196
	s_nop 0
	v_mul_f32_e32 v204, 0x45800000, v196
	v_cndmask_b32_e32 v196, v196, v204, vcc
	v_fmamk_f32 v197, v197, 0x3b2aaaab, v215
	v_cmp_gt_f32_e32 vcc, s32, v197
	v_mul_f32_e32 v205, 0x4b800000, v197
	s_nop 0
	v_cndmask_b32_e32 v197, v197, v205, vcc
	v_rsq_f32_e32 v197, v197
	s_nop 0
	v_mul_f32_e32 v205, 0x45800000, v197
	v_cndmask_b32_e32 v197, v197, v205, vcc
	v_fmamk_f32 v198, v198, 0x3b2aaaab, v215
	v_cmp_gt_f32_e32 vcc, s32, v198
	v_mul_f32_e32 v206, 0x4b800000, v198
	s_nop 0
	v_cndmask_b32_e32 v198, v198, v206, vcc
	v_rsq_f32_e32 v198, v198
	s_nop 0
	v_mul_f32_e32 v206, 0x45800000, v198
	v_cndmask_b32_e32 v198, v198, v206, vcc
	v_fmamk_f32 v199, v199, 0x3b2aaaab, v215
	v_cmp_gt_f32_e32 vcc, s32, v199
	v_mul_f32_e32 v207, 0x4b800000, v199
	s_nop 0
	v_cndmask_b32_e32 v199, v199, v207, vcc
	v_rsq_f32_e32 v199, v199
	s_nop 0
	v_mul_f32_e32 v207, 0x45800000, v199
	v_cndmask_b32_e32 v199, v199, v207, vcc
	v_fmamk_f32 v200, v200, 0x3b2aaaab, v215
	v_cmp_gt_f32_e32 vcc, s32, v200
	v_mul_f32_e32 v208, 0x4b800000, v200
	s_nop 0
	v_cndmask_b32_e32 v200, v200, v208, vcc
	v_rsq_f32_e32 v200, v200
	s_nop 0
; DI float gelu_tanh(float x) { return 0.5f * x * (1.f + tanhf(0.7978845608028654f * (x + 0.044715f * x * x * x))); }
; __device__ __forceinline__ unsigned cvt_pk_bf16(float lo, float hi) { unsigned r; asm volatile("v_cvt_pk_bf16_f32 %0, %1, %2" : "=v"(r) : "v"(lo), "v"(hi)); return r; }
;     DI bf16_t* z() const { return (bf16_t*)(ws + WS_Z); }
;     DI float* b1(int l, int v) const { return (float*)(ws + WS_B1) + (l * 2 + v) * 128; }
;     __device__ __forceinline__ void operator()(const f32x4 (&acc)[2][2][4][2], const Unit& u, int wr, int wc, int fr, int fq) const {
;     ...
;                     f32x4 v0 = acc[ai][bj][m][0] * sc, v1 = acc[ai][bj][m][1] * sc;
;                     if (MODE == EM_GELU) { if (col < nvalid) { const f32x4 b0 = *(const f32x4*)(bias + col), b1 = *(const f32x4*)(bias + col + 4);
; #pragma unroll
;                         for (int i = 0; i < 4; ++i) { v0[i] = ::gelu_tanh(v0[i] + b0[i]); v1[i] = ::gelu_tanh(v1[i] + b1[i]); } } }
;                     if (MODE == EM_RES) { const f32x4* hi = (const f32x4*)(Hin + (size_t)row * 1024 + col); f32x4* hp = (f32x4*)(H + (size_t)row * 1024 + col); v0 += hi[0]; v1 += hi[1]; hp[0] = v0; hp[1] = v1; }
;                     if (STATS) ss[bj] = ((v0[0] * v0[0] + v0[1] * v0[1]) + (v0[2] * v0[2] + v0[3] * v0[3])) + ((v1[0] * v1[0] + v1[1] * v1[1]) + (v1[2] * v1[2] + v1[3] * v1[3]));
;                     if (col < nvalid) { u32x4 w; w.x = cvt_pk_bf16(v0[0], v0[1]); w.y = cvt_pk_bf16(v0[2], v0[3]); w.z = cvt_pk_bf16(v1[0], v1[1]); w.w = cvt_pk_bf16(v1[2], v1[3]);
;                         *(u32x4*)(O + (size_t)row * ldc + col) = w; }
	v_mul_f32_e32 v208, 0x45800000, v200
	v_cndmask_b32_e32 v200, v200, v208, vcc
	v_fmamk_f32 v201, v201, 0x3b2aaaab, v215
	v_cmp_gt_f32_e32 vcc, s32, v201
	v_mul_f32_e32 v210, 0x4b800000, v201
	s_nop 0
	v_cndmask_b32_e32 v201, v201, v210, vcc
	v_rsq_f32_e32 v201, v201
	s_nop 0
	v_mul_f32_e32 v210, 0x45800000, v201
	v_cndmask_b32_e32 v201, v201, v210, vcc
	v_mul_f32_e32 v126, v126, v194
	v_mul_f32_e32 v127, v127, v194
	v_mul_f32_e32 v128, v128, v194
	v_mul_f32_e32 v129, v129, v194
	v_mul_f32_e32 v122, v122, v194
	v_mul_f32_e32 v123, v123, v194
	v_mul_f32_e32 v124, v124, v194
	v_mul_f32_e32 v125, v125, v194
	v_mul_f32_e32 v118, v118, v194
	v_mul_f32_e32 v119, v119, v194
	v_mul_f32_e32 v120, v120, v194
	v_mul_f32_e32 v121, v121, v194
	v_mul_f32_e32 v114, v114, v194
	v_mul_f32_e32 v115, v115, v194
	v_mul_f32_e32 v116, v116, v194
	v_mul_f32_e32 v117, v117, v194
	v_cvt_pk_bf16_f32 v234, v126, v127
	v_cvt_pk_bf16_f32 v235, v128, v129
	v_cvt_pk_bf16_f32 v236, v122, v123
	v_cvt_pk_bf16_f32 v237, v124, v125
	v_cvt_pk_bf16_f32 v238, v118, v119
	v_cvt_pk_bf16_f32 v239, v120, v121
	v_cvt_pk_bf16_f32 v240, v114, v115
	v_cvt_pk_bf16_f32 v241, v116, v117
	global_store_dwordx4 v211, v[234:237], s[24:25]
	global_store_dwordx4 v211, v[238:241], s[24:25] offset:256
	s_add_u32 s24, s24, 0x6000
	s_addc_u32 s25, s25, 0
	v_mul_f32_e32 v110, v110, v195
	v_mul_f32_e32 v111, v111, v195
	v_mul_f32_e32 v112, v112, v195
	v_mul_f32_e32 v113, v113, v195
	v_mul_f32_e32 v106, v106, v195
	v_mul_f32_e32 v107, v107, v195
	v_mul_f32_e32 v108, v108, v195
	v_mul_f32_e32 v109, v109, v195
	v_mul_f32_e32 v102, v102, v195
	v_mul_f32_e32 v103, v103, v195
	v_mul_f32_e32 v104, v104, v195
	v_mul_f32_e32 v105, v105, v195
	v_mul_f32_e32 v98, v98, v195
	v_mul_f32_e32 v99, v99, v195
	v_mul_f32_e32 v100, v100, v195
	v_mul_f32_e32 v101, v101, v195
	v_cvt_pk_bf16_f32 v234, v110, v111
	v_cvt_pk_bf16_f32 v235, v112, v113
	v_cvt_pk_bf16_f32 v236, v106, v107
	v_cvt_pk_bf16_f32 v237, v108, v109
	v_cvt_pk_bf16_f32 v238, v102, v103
	v_cvt_pk_bf16_f32 v239, v104, v105
	v_cvt_pk_bf16_f32 v240, v98, v99
	v_cvt_pk_bf16_f32 v241, v100, v101
	global_store_dwordx4 v211, v[234:237], s[24:25]
	global_store_dwordx4 v211, v[238:241], s[24:25] offset:256
	s_add_u32 s24, s24, 0x6000
	s_addc_u32 s25, s25, 0
	v_mul_f32_e32 v94, v94, v196
	v_mul_f32_e32 v95, v95, v196
	v_mul_f32_e32 v96, v96, v196
	v_mul_f32_e32 v97, v97, v196
	v_mul_f32_e32 v90, v90, v196
	v_mul_f32_e32 v91, v91, v196
	v_mul_f32_e32 v92, v92, v196
	v_mul_f32_e32 v93, v93, v196
	v_mul_f32_e32 v86, v86, v196
	v_mul_f32_e32 v87, v87, v196
	v_mul_f32_e32 v88, v88, v196
	v_mul_f32_e32 v89, v89, v196
	v_mul_f32_e32 v82, v82, v196
	v_mul_f32_e32 v83, v83, v196
	v_mul_f32_e32 v84, v84, v196
	v_mul_f32_e32 v85, v85, v196
	v_cvt_pk_bf16_f32 v234, v94, v95
	v_cvt_pk_bf16_f32 v235, v96, v97
	v_cvt_pk_bf16_f32 v236, v90, v91
	v_cvt_pk_bf16_f32 v237, v92, v93
	v_cvt_pk_bf16_f32 v238, v86, v87
	v_cvt_pk_bf16_f32 v239, v88, v89
	v_cvt_pk_bf16_f32 v240, v82, v83
	v_cvt_pk_bf16_f32 v241, v84, v85
	global_store_dwordx4 v211, v[234:237], s[24:25]
	global_store_dwordx4 v211, v[238:241], s[24:25] offset:256
	s_add_u32 s24, s24, 0x6000
	s_addc_u32 s25, s25, 0
	v_mul_f32_e32 v78, v78, v197
	v_mul_f32_e32 v79, v79, v197
	v_mul_f32_e32 v80, v80, v197
	v_mul_f32_e32 v81, v81, v197
	v_mul_f32_e32 v74, v74, v197
	v_mul_f32_e32 v75, v75, v197
	v_mul_f32_e32 v76, v76, v197
	v_mul_f32_e32 v77, v77, v197
	v_mul_f32_e32 v70, v70, v197
	v_mul_f32_e32 v71, v71, v197
	v_mul_f32_e32 v72, v72, v197
	v_mul_f32_e32 v73, v73, v197
	v_mul_f32_e32 v66, v66, v197
	v_mul_f32_e32 v67, v67, v197
	v_mul_f32_e32 v68, v68, v197
	v_mul_f32_e32 v69, v69, v197
	v_cvt_pk_bf16_f32 v234, v78, v79
	v_cvt_pk_bf16_f32 v235, v80, v81
	v_cvt_pk_bf16_f32 v236, v74, v75
	v_cvt_pk_bf16_f32 v237, v76, v77
	v_cvt_pk_bf16_f32 v238, v70, v71
	v_cvt_pk_bf16_f32 v239, v72, v73
	v_cvt_pk_bf16_f32 v240, v66, v67
	v_cvt_pk_bf16_f32 v241, v68, v69
; DI float gelu_tanh(float x) { return 0.5f * x * (1.f + tanhf(0.7978845608028654f * (x + 0.044715f * x * x * x))); }
; __device__ __forceinline__ unsigned cvt_pk_bf16(float lo, float hi) { unsigned r; asm volatile("v_cvt_pk_bf16_f32 %0, %1, %2" : "=v"(r) : "v"(lo), "v"(hi)); return r; }
;     DI bf16_t* z() const { return (bf16_t*)(ws + WS_Z); }
;     DI float* b1(int l, int v) const { return (float*)(ws + WS_B1) + (l * 2 + v) * 128; }
;     __device__ __forceinline__ void operator()(const f32x4 (&acc)[2][2][4][2], const Unit& u, int wr, int wc, int fr, int fq) const {
;     ...
;                     f32x4 v0 = acc[ai][bj][m][0] * sc, v1 = acc[ai][bj][m][1] * sc;
;                     if (MODE == EM_GELU) { if (col < nvalid) { const f32x4 b0 = *(const f32x4*)(bias + col), b1 = *(const f32x4*)(bias + col + 4);
; #pragma unroll
;                         for (int i = 0; i < 4; ++i) { v0[i] = ::gelu_tanh(v0[i] + b0[i]); v1[i] = ::gelu_tanh(v1[i] + b1[i]); } } }
;                     if (MODE == EM_RES) { const f32x4* hi = (const f32x4*)(Hin + (size_t)row * 1024 + col); f32x4* hp = (f32x4*)(H + (size_t)row * 1024 + col); v0 += hi[0]; v1 += hi[1]; hp[0] = v0; hp[1] = v1; }
;                     if (STATS) ss[bj] = ((v0[0] * v0[0] + v0[1] * v0[1]) + (v0[2] * v0[2] + v0[3] * v0[3])) + ((v1[0] * v1[0] + v1[1] * v1[1]) + (v1[2] * v1[2] + v1[3] * v1[3]));
;                     if (col < nvalid) { u32x4 w; w.x = cvt_pk_bf16(v0[0], v0[1]); w.y = cvt_pk_bf16(v0[2], v0[3]); w.z = cvt_pk_bf16(v1[0], v1[1]); w.w = cvt_pk_bf16(v1[2], v1[3]);
;                         *(u32x4*)(O + (size_t)row * ldc + col) = w; }
	global_store_dwordx4 v211, v[234:237], s[24:25]
	global_store_dwordx4 v211, v[238:241], s[24:25] offset:256
	s_add_u32 s24, s24, 0x1e000
	s_addc_u32 s25, s25, 0
	v_mul_f32_e32 v62, v62, v198
	v_mul_f32_e32 v63, v63, v198
	v_mul_f32_e32 v64, v64, v198
	v_mul_f32_e32 v65, v65, v198
	v_mul_f32_e32 v58, v58, v198
	v_mul_f32_e32 v59, v59, v198
	v_mul_f32_e32 v60, v60, v198
	v_mul_f32_e32 v61, v61, v198
	v_mul_f32_e32 v54, v54, v198
	v_mul_f32_e32 v55, v55, v198
	v_mul_f32_e32 v56, v56, v198
	v_mul_f32_e32 v57, v57, v198
	v_mul_f32_e32 v50, v50, v198
	v_mul_f32_e32 v51, v51, v198
	v_mul_f32_e32 v52, v52, v198
	v_mul_f32_e32 v53, v53, v198
	v_cvt_pk_bf16_f32 v234, v62, v63
	v_cvt_pk_bf16_f32 v235, v64, v65
	v_cvt_pk_bf16_f32 v236, v58, v59
	v_cvt_pk_bf16_f32 v237, v60, v61
	v_cvt_pk_bf16_f32 v238, v54, v55
	v_cvt_pk_bf16_f32 v239, v56, v57
	v_cvt_pk_bf16_f32 v240, v50, v51
	v_cvt_pk_bf16_f32 v241, v52, v53
	global_store_dwordx4 v211, v[234:237], s[24:25]
	global_store_dwordx4 v211, v[238:241], s[24:25] offset:256
	s_add_u32 s24, s24, 0x6000
	s_addc_u32 s25, s25, 0
	v_mul_f32_e32 v46, v46, v199
	v_mul_f32_e32 v47, v47, v199
	v_mul_f32_e32 v48, v48, v199
	v_mul_f32_e32 v49, v49, v199
	v_mul_f32_e32 v42, v42, v199
	v_mul_f32_e32 v43, v43, v199
	v_mul_f32_e32 v44, v44, v199
	v_mul_f32_e32 v45, v45, v199
	v_mul_f32_e32 v38, v38, v199
	v_mul_f32_e32 v39, v39, v199
	v_mul_f32_e32 v40, v40, v199
	v_mul_f32_e32 v41, v41, v199
	v_mul_f32_e32 v34, v34, v199
	v_mul_f32_e32 v35, v35, v199
	v_mul_f32_e32 v36, v36, v199
	v_mul_f32_e32 v37, v37, v199
	v_cvt_pk_bf16_f32 v234, v46, v47
	v_cvt_pk_bf16_f32 v235, v48, v49
	v_cvt_pk_bf16_f32 v236, v42, v43
	v_cvt_pk_bf16_f32 v237, v44, v45
	v_cvt_pk_bf16_f32 v238, v38, v39
	v_cvt_pk_bf16_f32 v239, v40, v41
	v_cvt_pk_bf16_f32 v240, v34, v35
	v_cvt_pk_bf16_f32 v241, v36, v37
	global_store_dwordx4 v211, v[234:237], s[24:25]
	global_store_dwordx4 v211, v[238:241], s[24:25] offset:256
	s_add_u32 s24, s24, 0x6000
	s_addc_u32 s25, s25, 0
	v_mul_f32_e32 v30, v30, v200
	v_mul_f32_e32 v31, v31, v200
	v_mul_f32_e32 v32, v32, v200
	v_mul_f32_e32 v33, v33, v200
	v_mul_f32_e32 v26, v26, v200
	v_mul_f32_e32 v27, v27, v200
	v_mul_f32_e32 v28, v28, v200
	v_mul_f32_e32 v29, v29, v200
	v_mul_f32_e32 v22, v22, v200
	v_mul_f32_e32 v23, v23, v200
	v_mul_f32_e32 v24, v24, v200
	v_mul_f32_e32 v25, v25, v200
	v_mul_f32_e32 v18, v18, v200
	v_mul_f32_e32 v19, v19, v200
	v_mul_f32_e32 v20, v20, v200
	v_mul_f32_e32 v21, v21, v200
	v_cvt_pk_bf16_f32 v234, v30, v31
	v_cvt_pk_bf16_f32 v235, v32, v33
	v_cvt_pk_bf16_f32 v236, v26, v27
	v_cvt_pk_bf16_f32 v237, v28, v29
	v_cvt_pk_bf16_f32 v238, v22, v23
	v_cvt_pk_bf16_f32 v239, v24, v25
	v_cvt_pk_bf16_f32 v240, v18, v19
	v_cvt_pk_bf16_f32 v241, v20, v21
	global_store_dwordx4 v211, v[234:237], s[24:25]
	global_store_dwordx4 v211, v[238:241], s[24:25] offset:256
	s_add_u32 s24, s24, 0x6000
	s_addc_u32 s25, s25, 0
	v_mul_f32_e32 v14, v14, v201
	v_mul_f32_e32 v15, v15, v201
	v_mul_f32_e32 v16, v16, v201
	v_mul_f32_e32 v17, v17, v201
	v_mul_f32_e32 v10, v10, v201
	v_mul_f32_e32 v11, v11, v201
	v_mul_f32_e32 v12, v12, v201
	v_mul_f32_e32 v13, v13, v201
	v_mul_f32_e32 v6, v6, v201
	v_mul_f32_e32 v7, v7, v201
	v_mul_f32_e32 v8, v8, v201
	v_mul_f32_e32 v9, v9, v201
	v_mul_f32_e32 v2, v2, v201
	v_mul_f32_e32 v3, v3, v201
	v_mul_f32_e32 v4, v4, v201
	v_mul_f32_e32 v5, v5, v201
	v_cvt_pk_bf16_f32 v234, v14, v15
	v_cvt_pk_bf16_f32 v235, v16, v17
	v_cvt_pk_bf16_f32 v236, v10, v11
	v_cvt_pk_bf16_f32 v237, v12, v13
	v_cvt_pk_bf16_f32 v238, v6, v7
	v_cvt_pk_bf16_f32 v239, v8, v9
	v_cvt_pk_bf16_f32 v240, v2, v3
	v_cvt_pk_bf16_f32 v241, v4, v5
	global_store_dwordx4 v211, v[234:237], s[24:25]
	global_store_dwordx4 v211, v[238:241], s[24:25] offset:256
	v_readlane_b32 s76, v254, 38
	v_readlane_b32 s77, v254, 39
	v_readlane_b32 s78, v254, 40
	v_readlane_b32 s79, v254, 41
	s_and_b64 vcc, exec, s[42:43]
	s_mov_b64 s[16:17], -1
	s_cbranch_vccnz .LBB0_1521

; DI float gelu_tanh(float x) { return 0.5f * x * (1.f + tanhf(0.7978845608028654f * (x + 0.044715f * x * x * x))); }
;     DI bf16_t* z() const { return (bf16_t*)(ws + WS_Z); }
;     DI float* ssqz() const { return (float*)(ws + WS_SSQZ); }
; DI float rstd_kv(const float* ssqz, int row) {
;     const f32x4* p = (const f32x4*)(ssqz + (size_t)row * 24 + 16); float s = 0.f;
; #pragma unroll
;     for (int i = 0; i < 2; ++i) { f32x4 v = p[i]; s += (v[0] + v[1]) + (v[2] + v[3]); }
;     return rsqrtf(s * (1.f / 256.f) + EPS);
; }
;     __device__ __forceinline__ void operator()(const f32x4 (&acc)[2][2][4][2], const Unit& u, int wr, int wc, int fr, int fq) const {
;         const int row0 = u.pm * BM + wr * 64 + fr, col0 = u.pn * BM + wc * 32 + 8 * fq;
; #pragma unroll
;         for (int ai = 0; ai < 2; ++ai)
; #pragma unroll
;             for (int m = 0; m < 4; ++m) {
;                 const int row = row0 + ai * HALF + m * 16;
;                 float sc = 1.f;
;                 if (MODE == EM_SCALEH) sc = ::rstd_h(ssq_in, row + rowoff);
;                 if (MODE == EM_SCALEQ) sc = ::rstd_q(ssq_in, row);
;                 if (MODE == EM_SCALEKV) sc = ::rstd_kv(ssq_in, row);
;                 float ss[2] = {0.f, 0.f};
; #pragma unroll
;                 for (int bj = 0; bj < 2; ++bj) {
;                     const int col = col0 + bj * HALF;
;                     f32x4 v0 = acc[ai][bj][m][0] * sc, v1 = acc[ai][bj][m][1] * sc;
;                     if (MODE == EM_GELU) { if (col < nvalid) { const f32x4 b0 = *(const f32x4*)(bias + col), b1 = *(const f32x4*)(bias + col + 4);
; #pragma unroll
;                         for (int i = 0; i < 4; ++i) { v0[i] = ::gelu_tanh(v0[i] + b0[i]); v1[i] = ::gelu_tanh(v1[i] + b1[i]); } } }
;                     if (MODE == EM_RES) { const f32x4* hi = (const f32x4*)(Hin + (size_t)row * 1024 + col); f32x4* hp = (f32x4*)(H + (size_t)row * 1024 + col); v0 += hi[0]; v1 += hi[1]; hp[0] = v0; hp[1] = v1; }
;                     if (STATS) ss[bj] = ((v0[0] * v0[0] + v0[1] * v0[1]) + (v0[2] * v0[2] + v0[3] * v0[3])) + ((v1[0] * v1[0] + v1[1] * v1[1]) + (v1[2] * v1[2] + v1[3] * v1[3]));
;                     if (col < nvalid) { u32x4 w; w.x = cvt_pk_bf16(v0[0], v0[1]); w.y = cvt_pk_bf16(v0[2], v0[3]); w.z = cvt_pk_bf16(v1[0], v1[1]); w.w = cvt_pk_bf16(v1[2], v1[3]);
;                         *(u32x4*)(O + (size_t)row * ldc + col) = w; }
.LBB0_1588:
	v_and_b32_e32 v251, 48, v221
	v_xor_b32_e32 v213, 16, v221
	v_lshlrev_b32_e32 v213, 2, v213
	v_min_u32_e32 v212, 16, v251
	v_lshl_add_u32 v212, v144, 6, v212
	v_lshl_add_u32 v212, v144, 5, v212
	v_add_u32_e32 v212, 64, v212
	v_lshlrev_b32_e32 v211, 1, v146
	v_lshl_add_u32 v211, v144, 11, v211
	s_mul_i32 s32, s44, 0x80000
	s_add_u32 s24, s50, s32
	s_addc_u32 s25, s51, 0
	s_lshl_b32 s32, s46, 9
	s_add_u32 s24, s24, s32
	s_addc_u32 s25, s25, 0
	s_mul_i32 s32, s44, 0x6000
	s_add_u32 s52, s10, s32
	s_addc_u32 s53, s11, 0
	global_load_dwordx4 v[140:143], v212, s[52:53]
	s_add_u32 s52, s52, 0x600
	s_addc_u32 s53, s53, 0
	global_load_dwordx4 v[150:153], v212, s[52:53]
	s_add_u32 s52, s52, 0x600
	s_addc_u32 s53, s53, 0
	global_load_dwordx4 v[154:157], v212, s[52:53]
	s_add_u32 s52, s52, 0x600
	s_addc_u32 s53, s53, 0
	global_load_dwordx4 v[158:161], v212, s[52:53]
	s_add_u32 s52, s52, 0x1e00
	s_addc_u32 s53, s53, 0
	global_load_dwordx4 v[162:165], v212, s[52:53]
	s_add_u32 s52, s52, 0x600
	s_addc_u32 s53, s53, 0
	global_load_dwordx4 v[166:169], v212, s[52:53]
	s_add_u32 s52, s52, 0x600
	s_addc_u32 s53, s53, 0
	global_load_dwordx4 v[186:189], v212, s[52:53]
	s_add_u32 s52, s52, 0x600
	s_addc_u32 s53, s53, 0
	global_load_dwordx4 v[190:193], v212, s[52:53]
	s_waitcnt vmcnt(0)
	v_add_f32_e32 v194, v140, v141
	v_add_f32_e32 v202, v142, v143
	v_add_f32_e32 v195, v150, v151
	v_add_f32_e32 v203, v152, v153
	v_add_f32_e32 v196, v154, v155
	v_add_f32_e32 v204, v156, v157
	v_add_f32_e32 v197, v158, v159
	v_add_f32_e32 v205, v160, v161
	v_add_f32_e32 v198, v162, v163
	v_add_f32_e32 v206, v164, v165
	v_add_f32_e32 v199, v166, v167
	v_add_f32_e32 v207, v168, v169
	v_add_f32_e32 v200, v186, v187
	v_add_f32_e32 v208, v188, v189
	v_add_f32_e32 v201, v190, v191
	v_add_f32_e32 v210, v192, v193
	v_add_f32_e32 v194, v194, v202
	v_add_f32_e32 v195, v195, v203
	v_add_f32_e32 v196, v196, v204
	v_add_f32_e32 v197, v197, v205
	v_add_f32_e32 v198, v198, v206
	v_add_f32_e32 v199, v199, v207
	v_add_f32_e32 v200, v200, v208
	v_add_f32_e32 v201, v201, v210
	v_cmp_gt_u32_e32 vcc, 32, v251
	s_nop 1
	v_cndmask_b32_e32 v194, 0, v194, vcc
	v_cndmask_b32_e32 v195, 0, v195, vcc
	v_cndmask_b32_e32 v196, 0, v196, vcc
	v_cndmask_b32_e32 v197, 0, v197, vcc
	v_cndmask_b32_e32 v198, 0, v198, vcc
	v_cndmask_b32_e32 v199, 0, v199, vcc
	v_cndmask_b32_e32 v200, 0, v200, vcc
	v_cndmask_b32_e32 v201, 0, v201, vcc
	ds_bpermute_b32 v202, v213, v194
	ds_bpermute_b32 v203, v213, v195
	ds_bpermute_b32 v204, v213, v196
	ds_bpermute_b32 v205, v213, v197
	ds_bpermute_b32 v206, v213, v198
	ds_bpermute_b32 v207, v213, v199
	ds_bpermute_b32 v208, v213, v200
	ds_bpermute_b32 v210, v213, v201
	s_waitcnt lgkmcnt(0)
	v_add_f32_e32 v194, v194, v202
	v_add_f32_e32 v195, v195, v203
	v_add_f32_e32 v196, v196, v204
	v_add_f32_e32 v197, v197, v205
	v_add_f32_e32 v198, v198, v206
	v_add_f32_e32 v199, v199, v207
	v_add_f32_e32 v200, v200, v208
	v_add_f32_e32 v201, v201, v210
	v_mov_b32_e32 v202, v194
	v_mov_b32_e32 v203, v195
	v_mov_b32_e32 v204, v196
	v_mov_b32_e32 v205, v197
	v_mov_b32_e32 v206, v198
	v_mov_b32_e32 v207, v199
	v_mov_b32_e32 v208, v200
	v_mov_b32_e32 v210, v201
	s_nop 1
	v_permlane32_swap_b32_e32 v202, v194
	v_permlane32_swap_b32_e32 v203, v195
	v_permlane32_swap_b32_e32 v204, v196
	v_permlane32_swap_b32_e32 v205, v197
	v_permlane32_swap_b32_e32 v206, v198
	v_permlane32_swap_b32_e32 v207, v199
	v_permlane32_swap_b32_e32 v208, v200
	v_permlane32_swap_b32_e32 v210, v201
	v_add_f32_e32 v194, v194, v202
	v_add_f32_e32 v195, v195, v203
	v_add_f32_e32 v196, v196, v204
	v_add_f32_e32 v197, v197, v205
	v_add_f32_e32 v198, v198, v206
	v_add_f32_e32 v199, v199, v207
	v_add_f32_e32 v200, v200, v208
	v_add_f32_e32 v201, v201, v210
	s_mov_b32 s32, 0x800000
	v_fmamk_f32 v194, v194, 0x3b800000, v215
	v_cmp_gt_f32_e32 vcc, s32, v194
	v_mul_f32_e32 v202, 0x4b800000, v194
	s_nop 0
	v_cndmask_b32_e32 v194, v194, v202, vcc
	v_rsq_f32_e32 v194, v194
	s_nop 0
	v_mul_f32_e32 v202, 0x45800000, v194
	v_cndmask_b32_e32 v194, v194, v202, vcc
	v_fmamk_f32 v195, v195, 0x3b800000, v215
	v_cmp_gt_f32_e32 vcc, s32, v195
	v_mul_f32_e32 v203, 0x4b800000, v195
	s_nop 0
	v_cndmask_b32_e32 v195, v195, v203, vcc
	v_rsq_f32_e32 v195, v195
	s_nop 0
	v_mul_f32_e32 v203, 0x45800000, v195
	v_cndmask_b32_e32 v195, v195, v203, vcc
	v_fmamk_f32 v196, v196, 0x3b800000, v215
	v_cmp_gt_f32_e32 vcc, s32, v196
	v_mul_f32_e32 v204, 0x4b800000, v196
	s_nop 0
	v_cndmask_b32_e32 v196, v196, v204, vcc
	v_rsq_f32_e32 v196, v196
	s_nop 0
	v_mul_f32_e32 v204, 0x45800000, v196
	v_cndmask_b32_e32 v196, v196, v204, vcc
	v_fmamk_f32 v197, v197, 0x3b800000, v215
	v_cmp_gt_f32_e32 vcc, s32, v197
	v_mul_f32_e32 v205, 0x4b800000, v197
	s_nop 0
	v_cndmask_b32_e32 v197, v197, v205, vcc
	v_rsq_f32_e32 v197, v197
	s_nop 0
	v_mul_f32_e32 v205, 0x45800000, v197
	v_cndmask_b32_e32 v197, v197, v205, vcc
	v_fmamk_f32 v198, v198, 0x3b800000, v215
	v_cmp_gt_f32_e32 vcc, s32, v198
	v_mul_f32_e32 v206, 0x4b800000, v198
	s_nop 0
	v_cndmask_b32_e32 v198, v198, v206, vcc
	v_rsq_f32_e32 v198, v198
	s_nop 0
	v_mul_f32_e32 v206, 0x45800000, v198
	v_cndmask_b32_e32 v198, v198, v206, vcc
	v_fmamk_f32 v199, v199, 0x3b800000, v215
	v_cmp_gt_f32_e32 vcc, s32, v199
	v_mul_f32_e32 v207, 0x4b800000, v199
	s_nop 0
	v_cndmask_b32_e32 v199, v199, v207, vcc
	v_rsq_f32_e32 v199, v199
	s_nop 0
	v_mul_f32_e32 v207, 0x45800000, v199
	v_cndmask_b32_e32 v199, v199, v207, vcc
	v_fmamk_f32 v200, v200, 0x3b800000, v215
	v_cmp_gt_f32_e32 vcc, s32, v200
	v_mul_f32_e32 v208, 0x4b800000, v200
	s_nop 0
	v_cndmask_b32_e32 v200, v200, v208, vcc
	v_rsq_f32_e32 v200, v200
	s_nop 0
; DI float gelu_tanh(float x) { return 0.5f * x * (1.f + tanhf(0.7978845608028654f * (x + 0.044715f * x * x * x))); }
; __device__ __forceinline__ unsigned cvt_pk_bf16(float lo, float hi) { unsigned r; asm volatile("v_cvt_pk_bf16_f32 %0, %1, %2" : "=v"(r) : "v"(lo), "v"(hi)); return r; }
;     DI bf16_t* z() const { return (bf16_t*)(ws + WS_Z); }
;     DI float* b1(int l, int v) const { return (float*)(ws + WS_B1) + (l * 2 + v) * 128; }
;     __device__ __forceinline__ void operator()(const f32x4 (&acc)[2][2][4][2], const Unit& u, int wr, int wc, int fr, int fq) const {
;     ...
;                     f32x4 v0 = acc[ai][bj][m][0] * sc, v1 = acc[ai][bj][m][1] * sc;
;                     if (MODE == EM_GELU) { if (col < nvalid) { const f32x4 b0 = *(const f32x4*)(bias + col), b1 = *(const f32x4*)(bias + col + 4);
; #pragma unroll
;                         for (int i = 0; i < 4; ++i) { v0[i] = ::gelu_tanh(v0[i] + b0[i]); v1[i] = ::gelu_tanh(v1[i] + b1[i]); } } }
;                     if (MODE == EM_RES) { const f32x4* hi = (const f32x4*)(Hin + (size_t)row * 1024 + col); f32x4* hp = (f32x4*)(H + (size_t)row * 1024 + col); v0 += hi[0]; v1 += hi[1]; hp[0] = v0; hp[1] = v1; }
;                     if (STATS) ss[bj] = ((v0[0] * v0[0] + v0[1] * v0[1]) + (v0[2] * v0[2] + v0[3] * v0[3])) + ((v1[0] * v1[0] + v1[1] * v1[1]) + (v1[2] * v1[2] + v1[3] * v1[3]));
;                     if (col < nvalid) { u32x4 w; w.x = cvt_pk_bf16(v0[0], v0[1]); w.y = cvt_pk_bf16(v0[2], v0[3]); w.z = cvt_pk_bf16(v1[0], v1[1]); w.w = cvt_pk_bf16(v1[2], v1[3]);
;                         *(u32x4*)(O + (size_t)row * ldc + col) = w; }
	v_mul_f32_e32 v208, 0x45800000, v200
	v_cndmask_b32_e32 v200, v200, v208, vcc
	v_fmamk_f32 v201, v201, 0x3b800000, v215
	v_cmp_gt_f32_e32 vcc, s32, v201
	v_mul_f32_e32 v210, 0x4b800000, v201
	s_nop 0
	v_cndmask_b32_e32 v201, v201, v210, vcc
	v_rsq_f32_e32 v201, v201
	s_nop 0
	v_mul_f32_e32 v210, 0x45800000, v201
	v_cndmask_b32_e32 v201, v201, v210, vcc
	v_mul_f32_e32 v126, v126, v194
	v_mul_f32_e32 v127, v127, v194
	v_mul_f32_e32 v128, v128, v194
	v_mul_f32_e32 v129, v129, v194
	v_mul_f32_e32 v122, v122, v194
	v_mul_f32_e32 v123, v123, v194
	v_mul_f32_e32 v124, v124, v194
	v_mul_f32_e32 v125, v125, v194
	v_mul_f32_e32 v118, v118, v194
	v_mul_f32_e32 v119, v119, v194
	v_mul_f32_e32 v120, v120, v194
	v_mul_f32_e32 v121, v121, v194
	v_mul_f32_e32 v114, v114, v194
	v_mul_f32_e32 v115, v115, v194
	v_mul_f32_e32 v116, v116, v194
	v_mul_f32_e32 v117, v117, v194
	v_cvt_pk_bf16_f32 v234, v126, v127
	v_cvt_pk_bf16_f32 v235, v128, v129
	v_cvt_pk_bf16_f32 v236, v122, v123
	v_cvt_pk_bf16_f32 v237, v124, v125
	v_cvt_pk_bf16_f32 v238, v118, v119
	v_cvt_pk_bf16_f32 v239, v120, v121
	v_cvt_pk_bf16_f32 v240, v114, v115
	v_cvt_pk_bf16_f32 v241, v116, v117
	global_store_dwordx4 v211, v[234:237], s[24:25]
	global_store_dwordx4 v211, v[238:241], s[24:25] offset:256
	s_add_u32 s24, s24, 0x8000
	s_addc_u32 s25, s25, 0
	v_mul_f32_e32 v110, v110, v195
	v_mul_f32_e32 v111, v111, v195
	v_mul_f32_e32 v112, v112, v195
	v_mul_f32_e32 v113, v113, v195
	v_mul_f32_e32 v106, v106, v195
	v_mul_f32_e32 v107, v107, v195
	v_mul_f32_e32 v108, v108, v195
	v_mul_f32_e32 v109, v109, v195
	v_mul_f32_e32 v102, v102, v195
	v_mul_f32_e32 v103, v103, v195
	v_mul_f32_e32 v104, v104, v195
	v_mul_f32_e32 v105, v105, v195
	v_mul_f32_e32 v98, v98, v195
	v_mul_f32_e32 v99, v99, v195
	v_mul_f32_e32 v100, v100, v195
	v_mul_f32_e32 v101, v101, v195
	v_cvt_pk_bf16_f32 v234, v110, v111
	v_cvt_pk_bf16_f32 v235, v112, v113
	v_cvt_pk_bf16_f32 v236, v106, v107
	v_cvt_pk_bf16_f32 v237, v108, v109
	v_cvt_pk_bf16_f32 v238, v102, v103
	v_cvt_pk_bf16_f32 v239, v104, v105
	v_cvt_pk_bf16_f32 v240, v98, v99
	v_cvt_pk_bf16_f32 v241, v100, v101
	global_store_dwordx4 v211, v[234:237], s[24:25]
	global_store_dwordx4 v211, v[238:241], s[24:25] offset:256
	s_add_u32 s24, s24, 0x8000
	s_addc_u32 s25, s25, 0
	v_mul_f32_e32 v94, v94, v196
	v_mul_f32_e32 v95, v95, v196
	v_mul_f32_e32 v96, v96, v196
	v_mul_f32_e32 v97, v97, v196
	v_mul_f32_e32 v90, v90, v196
	v_mul_f32_e32 v91, v91, v196
	v_mul_f32_e32 v92, v92, v196
	v_mul_f32_e32 v93, v93, v196
	v_mul_f32_e32 v86, v86, v196
	v_mul_f32_e32 v87, v87, v196
	v_mul_f32_e32 v88, v88, v196
	v_mul_f32_e32 v89, v89, v196
	v_mul_f32_e32 v82, v82, v196
	v_mul_f32_e32 v83, v83, v196
	v_mul_f32_e32 v84, v84, v196
	v_mul_f32_e32 v85, v85, v196
	v_cvt_pk_bf16_f32 v234, v94, v95
	v_cvt_pk_bf16_f32 v235, v96, v97
	v_cvt_pk_bf16_f32 v236, v90, v91
	v_cvt_pk_bf16_f32 v237, v92, v93
	v_cvt_pk_bf16_f32 v238, v86, v87
	v_cvt_pk_bf16_f32 v239, v88, v89
	v_cvt_pk_bf16_f32 v240, v82, v83
	v_cvt_pk_bf16_f32 v241, v84, v85
	global_store_dwordx4 v211, v[234:237], s[24:25]
	global_store_dwordx4 v211, v[238:241], s[24:25] offset:256
	s_add_u32 s24, s24, 0x8000
	s_addc_u32 s25, s25, 0
	v_mul_f32_e32 v78, v78, v197
	v_mul_f32_e32 v79, v79, v197
	v_mul_f32_e32 v80, v80, v197
	v_mul_f32_e32 v81, v81, v197
	v_mul_f32_e32 v74, v74, v197
	v_mul_f32_e32 v75, v75, v197
	v_mul_f32_e32 v76, v76, v197
	v_mul_f32_e32 v77, v77, v197
	v_mul_f32_e32 v70, v70, v197
	v_mul_f32_e32 v71, v71, v197
	v_mul_f32_e32 v72, v72, v197
	v_mul_f32_e32 v73, v73, v197
	v_mul_f32_e32 v66, v66, v197
	v_mul_f32_e32 v67, v67, v197
	v_mul_f32_e32 v68, v68, v197
	v_mul_f32_e32 v69, v69, v197
	v_cvt_pk_bf16_f32 v234, v78, v79
	v_cvt_pk_bf16_f32 v235, v80, v81
	v_cvt_pk_bf16_f32 v236, v74, v75
	v_cvt_pk_bf16_f32 v237, v76, v77
	v_cvt_pk_bf16_f32 v238, v70, v71
	v_cvt_pk_bf16_f32 v239, v72, v73
	v_cvt_pk_bf16_f32 v240, v66, v67
	v_cvt_pk_bf16_f32 v241, v68, v69
; DI float gelu_tanh(float x) { return 0.5f * x * (1.f + tanhf(0.7978845608028654f * (x + 0.044715f * x * x * x))); }
; __device__ __forceinline__ unsigned cvt_pk_bf16(float lo, float hi) { unsigned r; asm volatile("v_cvt_pk_bf16_f32 %0, %1, %2" : "=v"(r) : "v"(lo), "v"(hi)); return r; }
;     DI bf16_t* z() const { return (bf16_t*)(ws + WS_Z); }
;     DI float* b1(int l, int v) const { return (float*)(ws + WS_B1) + (l * 2 + v) * 128; }
;     __device__ __forceinline__ void operator()(const f32x4 (&acc)[2][2][4][2], const Unit& u, int wr, int wc, int fr, int fq) const {
;     ...
;                     f32x4 v0 = acc[ai][bj][m][0] * sc, v1 = acc[ai][bj][m][1] * sc;
;                     if (MODE == EM_GELU) { if (col < nvalid) { const f32x4 b0 = *(const f32x4*)(bias + col), b1 = *(const f32x4*)(bias + col + 4);
; #pragma unroll
;                         for (int i = 0; i < 4; ++i) { v0[i] = ::gelu_tanh(v0[i] + b0[i]); v1[i] = ::gelu_tanh(v1[i] + b1[i]); } } }
;                     if (MODE == EM_RES) { const f32x4* hi = (const f32x4*)(Hin + (size_t)row * 1024 + col); f32x4* hp = (f32x4*)(H + (size_t)row * 1024 + col); v0 += hi[0]; v1 += hi[1]; hp[0] = v0; hp[1] = v1; }
;                     if (STATS) ss[bj] = ((v0[0] * v0[0] + v0[1] * v0[1]) + (v0[2] * v0[2] + v0[3] * v0[3])) + ((v1[0] * v1[0] + v1[1] * v1[1]) + (v1[2] * v1[2] + v1[3] * v1[3]));
;                     if (col < nvalid) { u32x4 w; w.x = cvt_pk_bf16(v0[0], v0[1]); w.y = cvt_pk_bf16(v0[2], v0[3]); w.z = cvt_pk_bf16(v1[0], v1[1]); w.w = cvt_pk_bf16(v1[2], v1[3]);
;                         *(u32x4*)(O + (size_t)row * ldc + col) = w; }
	global_store_dwordx4 v211, v[234:237], s[24:25]
	global_store_dwordx4 v211, v[238:241], s[24:25] offset:256
	s_add_u32 s24, s24, 0x28000
	s_addc_u32 s25, s25, 0
	v_mul_f32_e32 v62, v62, v198
	v_mul_f32_e32 v63, v63, v198
	v_mul_f32_e32 v64, v64, v198
	v_mul_f32_e32 v65, v65, v198
	v_mul_f32_e32 v58, v58, v198
	v_mul_f32_e32 v59, v59, v198
	v_mul_f32_e32 v60, v60, v198
	v_mul_f32_e32 v61, v61, v198
	v_mul_f32_e32 v54, v54, v198
	v_mul_f32_e32 v55, v55, v198
	v_mul_f32_e32 v56, v56, v198
	v_mul_f32_e32 v57, v57, v198
	v_mul_f32_e32 v50, v50, v198
	v_mul_f32_e32 v51, v51, v198
	v_mul_f32_e32 v52, v52, v198
	v_mul_f32_e32 v53, v53, v198
	v_cvt_pk_bf16_f32 v234, v62, v63
	v_cvt_pk_bf16_f32 v235, v64, v65
	v_cvt_pk_bf16_f32 v236, v58, v59
	v_cvt_pk_bf16_f32 v237, v60, v61
	v_cvt_pk_bf16_f32 v238, v54, v55
	v_cvt_pk_bf16_f32 v239, v56, v57
	v_cvt_pk_bf16_f32 v240, v50, v51
	v_cvt_pk_bf16_f32 v241, v52, v53
	global_store_dwordx4 v211, v[234:237], s[24:25]
	global_store_dwordx4 v211, v[238:241], s[24:25] offset:256
	s_add_u32 s24, s24, 0x8000
	s_addc_u32 s25, s25, 0
	v_mul_f32_e32 v46, v46, v199
	v_mul_f32_e32 v47, v47, v199
	v_mul_f32_e32 v48, v48, v199
	v_mul_f32_e32 v49, v49, v199
	v_mul_f32_e32 v42, v42, v199
	v_mul_f32_e32 v43, v43, v199
	v_mul_f32_e32 v44, v44, v199
	v_mul_f32_e32 v45, v45, v199
	v_mul_f32_e32 v38, v38, v199
	v_mul_f32_e32 v39, v39, v199
	v_mul_f32_e32 v40, v40, v199
	v_mul_f32_e32 v41, v41, v199
	v_mul_f32_e32 v34, v34, v199
	v_mul_f32_e32 v35, v35, v199
	v_mul_f32_e32 v36, v36, v199
	v_mul_f32_e32 v37, v37, v199
	v_cvt_pk_bf16_f32 v234, v46, v47
	v_cvt_pk_bf16_f32 v235, v48, v49
	v_cvt_pk_bf16_f32 v236, v42, v43
	v_cvt_pk_bf16_f32 v237, v44, v45
	v_cvt_pk_bf16_f32 v238, v38, v39
	v_cvt_pk_bf16_f32 v239, v40, v41
	v_cvt_pk_bf16_f32 v240, v34, v35
	v_cvt_pk_bf16_f32 v241, v36, v37
	global_store_dwordx4 v211, v[234:237], s[24:25]
	global_store_dwordx4 v211, v[238:241], s[24:25] offset:256
	s_add_u32 s24, s24, 0x8000
	s_addc_u32 s25, s25, 0
	v_mul_f32_e32 v30, v30, v200
	v_mul_f32_e32 v31, v31, v200
	v_mul_f32_e32 v32, v32, v200
	v_mul_f32_e32 v33, v33, v200
	v_mul_f32_e32 v26, v26, v200
	v_mul_f32_e32 v27, v27, v200
	v_mul_f32_e32 v28, v28, v200
	v_mul_f32_e32 v29, v29, v200
	v_mul_f32_e32 v22, v22, v200
	v_mul_f32_e32 v23, v23, v200
	v_mul_f32_e32 v24, v24, v200
	v_mul_f32_e32 v25, v25, v200
	v_mul_f32_e32 v18, v18, v200
	v_mul_f32_e32 v19, v19, v200
	v_mul_f32_e32 v20, v20, v200
	v_mul_f32_e32 v21, v21, v200
	v_cvt_pk_bf16_f32 v234, v30, v31
	v_cvt_pk_bf16_f32 v235, v32, v33
	v_cvt_pk_bf16_f32 v236, v26, v27
	v_cvt_pk_bf16_f32 v237, v28, v29
	v_cvt_pk_bf16_f32 v238, v22, v23
	v_cvt_pk_bf16_f32 v239, v24, v25
	v_cvt_pk_bf16_f32 v240, v18, v19
	v_cvt_pk_bf16_f32 v241, v20, v21
	global_store_dwordx4 v211, v[234:237], s[24:25]
	global_store_dwordx4 v211, v[238:241], s[24:25] offset:256
	s_add_u32 s24, s24, 0x8000
	s_addc_u32 s25, s25, 0
	v_mul_f32_e32 v14, v14, v201
	v_mul_f32_e32 v15, v15, v201
	v_mul_f32_e32 v16, v16, v201
	v_mul_f32_e32 v17, v17, v201
	v_mul_f32_e32 v10, v10, v201
	v_mul_f32_e32 v11, v11, v201
	v_mul_f32_e32 v12, v12, v201
	v_mul_f32_e32 v13, v13, v201
	v_mul_f32_e32 v6, v6, v201
	v_mul_f32_e32 v7, v7, v201
	v_mul_f32_e32 v8, v8, v201
	v_mul_f32_e32 v9, v9, v201
	v_mul_f32_e32 v2, v2, v201
	v_mul_f32_e32 v3, v3, v201
	v_mul_f32_e32 v4, v4, v201
	v_mul_f32_e32 v5, v5, v201
	v_cvt_pk_bf16_f32 v234, v14, v15
	v_cvt_pk_bf16_f32 v235, v16, v17
	v_cvt_pk_bf16_f32 v236, v10, v11
	v_cvt_pk_bf16_f32 v237, v12, v13
	v_cvt_pk_bf16_f32 v238, v6, v7
	v_cvt_pk_bf16_f32 v239, v8, v9
	v_cvt_pk_bf16_f32 v240, v2, v3
	v_cvt_pk_bf16_f32 v241, v4, v5
	global_store_dwordx4 v211, v[234:237], s[24:25]
	global_store_dwordx4 v211, v[238:241], s[24:25] offset:256
	v_readlane_b32 s76, v254, 38
	v_readlane_b32 s77, v254, 39
	v_readlane_b32 s78, v254, 40
	v_readlane_b32 s79, v254, 41
	v_readlane_b32 s73, v254, 32
	s_andn2_b64 vcc, exec, s[42:43]
	s_mov_b64 s[16:17], -1
	s_cbranch_vccnz .LBB0_1577

; __device__ __forceinline__ unsigned cvt_pk_bf16(float lo, float hi) { unsigned r; asm volatile("v_cvt_pk_bf16_f32 %0, %1, %2" : "=v"(r) : "v"(lo), "v"(hi)); return r; }
;     DI bf16_t* z() const { return (bf16_t*)(ws + WS_Z); }
;     __device__ __forceinline__ void operator()(const f32x4 (&acc)[2][2][4][2], const Unit& u, int wr, int wc, int fr, int fq) const {
;     ...
;                     if (MODE == EM_RES) { const f32x4* hi = (const f32x4*)(Hin + (size_t)row * 1024 + col); f32x4* hp = (f32x4*)(H + (size_t)row * 1024 + col); v0 += hi[0]; v1 += hi[1]; hp[0] = v0; hp[1] = v1; }
;                     if (STATS) ss[bj] = ((v0[0] * v0[0] + v0[1] * v0[1]) + (v0[2] * v0[2] + v0[3] * v0[3])) + ((v1[0] * v1[0] + v1[1] * v1[1]) + (v1[2] * v1[2] + v1[3] * v1[3]));
;                     if (col < nvalid) { u32x4 w; w.x = cvt_pk_bf16(v0[0], v0[1]); w.y = cvt_pk_bf16(v0[2], v0[3]); w.z = cvt_pk_bf16(v1[0], v1[1]); w.w = cvt_pk_bf16(v1[2], v1[3]);
;                         *(u32x4*)(O + (size_t)row * ldc + col) = w; }
;                 }
;                 if (STATS == 1) { float t = ss[0] + ss[1]; t += __shfl_xor(t, 16); t += __shfl_xor(t, 32); if (fq == 0) ssq_out[(size_t)row * 16 + u.pn * 4 + wc] = t; }
.LBB0_1662:
	v_lshlrev_b32_e32 v168, 12, v148
	v_lshl_add_u32 v168, v150, 2, v168
	v_lshlrev_b32_e32 v169, 11, v148
	v_lshl_add_u32 v169, v150, 1, v169
	v_lshlrev_b32_e32 v170, 6, v148
	v_xor_b32_e32 v176, 16, v221
	v_lshlrev_b32_e32 v176, 2, v176
	s_lshl_b32 s32, s91, 20
	s_add_u32 s24, s8, s32
	s_addc_u32 s25, s9, 0
	s_lshl_b32 s32, s88, 10
	s_add_u32 s24, s24, s32
	s_addc_u32 s25, s25, 0
	s_lshl_b32 s32, s91, 20
	s_add_u32 s48, s8, s32
	s_addc_u32 s49, s9, 0
	s_lshl_b32 s32, s88, 10
	s_add_u32 s48, s48, s32
	s_addc_u32 s49, s49, 0
	s_lshl_b32 s32, s91, 19
	s_add_u32 s60, s50, s32
	s_addc_u32 s61, s51, 0
	s_lshl_b32 s32, s88, 9
	s_add_u32 s60, s60, s32
	s_addc_u32 s61, s61, 0
	s_lshl_b32 s32, s91, 14
	s_add_u32 s96, s52, s32
	s_addc_u32 s97, s53, 0
	s_lshl_b32 s32, s88, 2
	s_add_i32 s32, s32, s69
	s_lshl_b32 s32, s32, 2
	s_add_u32 s96, s96, s32
	s_addc_u32 s97, s97, 0
	global_load_dwordx4 v[140:143], v168, s[24:25]
	global_load_dwordx4 v[144:147], v168, s[24:25] offset:16
	global_load_dwordx4 v[156:159], v168, s[24:25] offset:512
	global_load_dwordx4 v[160:163], v168, s[24:25] offset:528
	s_add_u32 s24, s24, 0x10000
	s_addc_u32 s25, s25, 0
	global_load_dwordx4 v[164:167], v168, s[24:25]
	global_load_dwordx4 v[186:189], v168, s[24:25] offset:16
	global_load_dwordx4 v[190:193], v168, s[24:25] offset:512
	global_load_dwordx4 v[194:197], v168, s[24:25] offset:528
	s_add_u32 s24, s24, 0x10000
	s_addc_u32 s25, s25, 0
	global_load_dwordx4 v[198:201], v168, s[24:25]
	global_load_dwordx4 v[202:205], v168, s[24:25] offset:16
	global_load_dwordx4 v[210:213], v168, s[24:25] offset:512
	global_load_dwordx4 v[234:237], v168, s[24:25] offset:528
	s_add_u32 s24, s24, 0x10000
	s_addc_u32 s25, s25, 0
	global_load_dwordx4 v[238:241], v168, s[24:25]
	global_load_dwordx4 v[242:245], v168, s[24:25] offset:16
	global_load_dwordx4 v[246:249], v168, s[24:25] offset:512
	global_load_dwordx4 v[152:155], v168, s[24:25] offset:528
	s_waitcnt vmcnt(12)
	v_pk_add_f32 v[126:127], v[126:127], v[140:141]
	v_pk_add_f32 v[128:129], v[128:129], v[142:143]
	v_pk_add_f32 v[122:123], v[122:123], v[144:145]
	v_pk_add_f32 v[124:125], v[124:125], v[146:147]
	v_pk_add_f32 v[118:119], v[118:119], v[156:157]
	v_pk_add_f32 v[120:121], v[120:121], v[158:159]
	v_pk_add_f32 v[114:115], v[114:115], v[160:161]
	v_pk_add_f32 v[116:117], v[116:117], v[162:163]
	global_store_dwordx4 v168, v[126:129], s[48:49]
	global_store_dwordx4 v168, v[122:125], s[48:49] offset:16
	global_store_dwordx4 v168, v[118:121], s[48:49] offset:512
	global_store_dwordx4 v168, v[114:117], s[48:49] offset:528
	v_cvt_pk_bf16_f32 v140, v126, v127
	v_cvt_pk_bf16_f32 v141, v128, v129
	v_cvt_pk_bf16_f32 v142, v122, v123
	v_cvt_pk_bf16_f32 v143, v124, v125
	v_cvt_pk_bf16_f32 v156, v118, v119
	v_cvt_pk_bf16_f32 v157, v120, v121
	v_cvt_pk_bf16_f32 v158, v114, v115
	v_cvt_pk_bf16_f32 v159, v116, v117
	global_store_dwordx4 v169, v[140:143], s[60:61]
	global_store_dwordx4 v169, v[156:159], s[60:61] offset:256
	s_add_u32 s24, s24, 0x50000
	s_addc_u32 s25, s25, 0
	global_load_dwordx4 v[140:143], v168, s[24:25]
	global_load_dwordx4 v[144:147], v168, s[24:25] offset:16
	global_load_dwordx4 v[156:159], v168, s[24:25] offset:512
	global_load_dwordx4 v[160:163], v168, s[24:25] offset:528
	v_mul_f32_e32 v177, v126, v126
	v_mul_f32_e32 v184, v122, v122
	v_fmac_f32_e32 v177, v127, v127
	v_fmac_f32_e32 v177, v128, v128
	v_fmac_f32_e32 v177, v129, v129
	v_fmac_f32_e32 v184, v123, v123
	v_fmac_f32_e32 v184, v124, v124
	v_fmac_f32_e32 v184, v125, v125
	v_fmac_f32_e32 v177, v118, v118
	v_fmac_f32_e32 v177, v119, v119
	v_fmac_f32_e32 v177, v120, v120
	v_fmac_f32_e32 v177, v121, v121
	v_fmac_f32_e32 v184, v114, v114
	v_fmac_f32_e32 v184, v115, v115
	v_fmac_f32_e32 v184, v116, v116
	v_fmac_f32_e32 v184, v117, v117
	v_add_f32_e32 v177, v177, v184
	ds_bpermute_b32 v184, v176, v177
	s_waitcnt lgkmcnt(0)
	v_add_f32_e32 v177, v177, v184
	v_mov_b32_e32 v184, v177
	s_nop 1
	v_permlane32_swap_b32_e32 v184, v177
	v_add_f32_e32 v206, v177, v184
	s_and_saveexec_b64 s[16:17], s[42:43]
	global_store_dword v170, v206, s[96:97]
	s_or_b64 exec, exec, s[16:17]
	s_add_u32 s48, s48, 0x10000
	s_addc_u32 s49, s49, 0
	s_add_u32 s60, s60, 0x8000
	s_addc_u32 s61, s61, 0
	s_add_u32 s96, s96, 0x400
	s_addc_u32 s97, s97, 0
	s_waitcnt vmcnt(19)
	v_pk_add_f32 v[110:111], v[110:111], v[164:165]
	v_pk_add_f32 v[112:113], v[112:113], v[166:167]
	v_pk_add_f32 v[106:107], v[106:107], v[186:187]
	v_pk_add_f32 v[108:109], v[108:109], v[188:189]
	v_pk_add_f32 v[102:103], v[102:103], v[190:191]
	v_pk_add_f32 v[104:105], v[104:105], v[192:193]
	v_pk_add_f32 v[98:99], v[98:99], v[194:195]
	v_pk_add_f32 v[100:101], v[100:101], v[196:197]
	global_store_dwordx4 v168, v[110:113], s[48:49]
	global_store_dwordx4 v168, v[106:109], s[48:49] offset:16
	global_store_dwordx4 v168, v[102:105], s[48:49] offset:512
	global_store_dwordx4 v168, v[98:101], s[48:49] offset:528
	v_cvt_pk_bf16_f32 v164, v110, v111
	v_cvt_pk_bf16_f32 v165, v112, v113
	v_cvt_pk_bf16_f32 v166, v106, v107
	v_cvt_pk_bf16_f32 v167, v108, v109
	v_cvt_pk_bf16_f32 v190, v102, v103
	v_cvt_pk_bf16_f32 v191, v104, v105
	v_cvt_pk_bf16_f32 v192, v98, v99
	v_cvt_pk_bf16_f32 v193, v100, v101
	global_store_dwordx4 v169, v[164:167], s[60:61]
	global_store_dwordx4 v169, v[190:193], s[60:61] offset:256
	s_add_u32 s24, s24, 0x10000
	s_addc_u32 s25, s25, 0
	global_load_dwordx4 v[164:167], v168, s[24:25]
	global_load_dwordx4 v[186:189], v168, s[24:25] offset:16
	global_load_dwordx4 v[190:193], v168, s[24:25] offset:512
	global_load_dwordx4 v[194:197], v168, s[24:25] offset:528
	v_mul_f32_e32 v177, v110, v110
	v_mul_f32_e32 v184, v106, v106
	v_fmac_f32_e32 v177, v111, v111
	v_fmac_f32_e32 v177, v112, v112
	v_fmac_f32_e32 v177, v113, v113
	v_fmac_f32_e32 v184, v107, v107
	v_fmac_f32_e32 v184, v108, v108
	v_fmac_f32_e32 v184, v109, v109
	v_fmac_f32_e32 v177, v102, v102
	v_fmac_f32_e32 v177, v103, v103
	v_fmac_f32_e32 v177, v104, v104
	v_fmac_f32_e32 v177, v105, v105
	v_fmac_f32_e32 v184, v98, v98
	v_fmac_f32_e32 v184, v99, v99
	v_fmac_f32_e32 v184, v100, v100
	v_fmac_f32_e32 v184, v101, v101
	v_add_f32_e32 v177, v177, v184
	ds_bpermute_b32 v184, v176, v177
	s_waitcnt lgkmcnt(0)
; __device__ __forceinline__ unsigned cvt_pk_bf16(float lo, float hi) { unsigned r; asm volatile("v_cvt_pk_bf16_f32 %0, %1, %2" : "=v"(r) : "v"(lo), "v"(hi)); return r; }
;     DI bf16_t* z() const { return (bf16_t*)(ws + WS_Z); }
;     __device__ __forceinline__ void operator()(const f32x4 (&acc)[2][2][4][2], const Unit& u, int wr, int wc, int fr, int fq) const {
;     ...
;                     if (MODE == EM_RES) { const f32x4* hi = (const f32x4*)(Hin + (size_t)row * 1024 + col); f32x4* hp = (f32x4*)(H + (size_t)row * 1024 + col); v0 += hi[0]; v1 += hi[1]; hp[0] = v0; hp[1] = v1; }
;                     if (STATS) ss[bj] = ((v0[0] * v0[0] + v0[1] * v0[1]) + (v0[2] * v0[2] + v0[3] * v0[3])) + ((v1[0] * v1[0] + v1[1] * v1[1]) + (v1[2] * v1[2] + v1[3] * v1[3]));
;                     if (col < nvalid) { u32x4 w; w.x = cvt_pk_bf16(v0[0], v0[1]); w.y = cvt_pk_bf16(v0[2], v0[3]); w.z = cvt_pk_bf16(v1[0], v1[1]); w.w = cvt_pk_bf16(v1[2], v1[3]);
;                         *(u32x4*)(O + (size_t)row * ldc + col) = w; }
;                 }
;                 if (STATS == 1) { float t = ss[0] + ss[1]; t += __shfl_xor(t, 16); t += __shfl_xor(t, 32); if (fq == 0) ssq_out[(size_t)row * 16 + u.pn * 4 + wc] = t; }
	v_add_f32_e32 v177, v177, v184
	v_mov_b32_e32 v184, v177
	s_nop 1
	v_permlane32_swap_b32_e32 v184, v177
	v_add_f32_e32 v206, v177, v184
	s_and_saveexec_b64 s[16:17], s[42:43]
	global_store_dword v170, v206, s[96:97]
	s_or_b64 exec, exec, s[16:17]
	s_add_u32 s48, s48, 0x10000
	s_addc_u32 s49, s49, 0
	s_add_u32 s60, s60, 0x8000
	s_addc_u32 s61, s61, 0
	s_add_u32 s96, s96, 0x400
	s_addc_u32 s97, s97, 0
	s_waitcnt vmcnt(26)
	v_pk_add_f32 v[94:95], v[94:95], v[198:199]
	v_pk_add_f32 v[96:97], v[96:97], v[200:201]
	v_pk_add_f32 v[90:91], v[90:91], v[202:203]
	v_pk_add_f32 v[92:93], v[92:93], v[204:205]
	v_pk_add_f32 v[86:87], v[86:87], v[210:211]
	v_pk_add_f32 v[88:89], v[88:89], v[212:213]
	v_pk_add_f32 v[82:83], v[82:83], v[234:235]
	v_pk_add_f32 v[84:85], v[84:85], v[236:237]
	global_store_dwordx4 v168, v[94:97], s[48:49]
	global_store_dwordx4 v168, v[90:93], s[48:49] offset:16
	global_store_dwordx4 v168, v[86:89], s[48:49] offset:512
	global_store_dwordx4 v168, v[82:85], s[48:49] offset:528
	v_cvt_pk_bf16_f32 v198, v94, v95
	v_cvt_pk_bf16_f32 v199, v96, v97
	v_cvt_pk_bf16_f32 v200, v90, v91
	v_cvt_pk_bf16_f32 v201, v92, v93
	v_cvt_pk_bf16_f32 v210, v86, v87
	v_cvt_pk_bf16_f32 v211, v88, v89
	v_cvt_pk_bf16_f32 v212, v82, v83
	v_cvt_pk_bf16_f32 v213, v84, v85
	global_store_dwordx4 v169, v[198:201], s[60:61]
	global_store_dwordx4 v169, v[210:213], s[60:61] offset:256
	s_add_u32 s24, s24, 0x10000
	s_addc_u32 s25, s25, 0
	global_load_dwordx4 v[198:201], v168, s[24:25]
	global_load_dwordx4 v[202:205], v168, s[24:25] offset:16
	global_load_dwordx4 v[210:213], v168, s[24:25] offset:512
	global_load_dwordx4 v[234:237], v168, s[24:25] offset:528
	v_mul_f32_e32 v177, v94, v94
	v_mul_f32_e32 v184, v90, v90
	v_fmac_f32_e32 v177, v95, v95
	v_fmac_f32_e32 v177, v96, v96
	v_fmac_f32_e32 v177, v97, v97
	v_fmac_f32_e32 v184, v91, v91
	v_fmac_f32_e32 v184, v92, v92
	v_fmac_f32_e32 v184, v93, v93
	v_fmac_f32_e32 v177, v86, v86
	v_fmac_f32_e32 v177, v87, v87
	v_fmac_f32_e32 v177, v88, v88
	v_fmac_f32_e32 v177, v89, v89
	v_fmac_f32_e32 v184, v82, v82
	v_fmac_f32_e32 v184, v83, v83
	v_fmac_f32_e32 v184, v84, v84
	v_fmac_f32_e32 v184, v85, v85
	v_add_f32_e32 v177, v177, v184
	ds_bpermute_b32 v184, v176, v177
	s_waitcnt lgkmcnt(0)
	v_add_f32_e32 v177, v177, v184
	v_mov_b32_e32 v184, v177
	s_nop 1
	v_permlane32_swap_b32_e32 v184, v177
	v_add_f32_e32 v206, v177, v184
	s_and_saveexec_b64 s[16:17], s[42:43]
	global_store_dword v170, v206, s[96:97]
	s_or_b64 exec, exec, s[16:17]
	s_add_u32 s48, s48, 0x10000
	s_addc_u32 s49, s49, 0
	s_add_u32 s60, s60, 0x8000
	s_addc_u32 s61, s61, 0
	s_add_u32 s96, s96, 0x400
	s_addc_u32 s97, s97, 0
	s_waitcnt vmcnt(33)
	v_pk_add_f32 v[78:79], v[78:79], v[238:239]
	v_pk_add_f32 v[80:81], v[80:81], v[240:241]
	v_pk_add_f32 v[74:75], v[74:75], v[242:243]
	v_pk_add_f32 v[76:77], v[76:77], v[244:245]
	v_pk_add_f32 v[70:71], v[70:71], v[246:247]
	v_pk_add_f32 v[72:73], v[72:73], v[248:249]
	v_pk_add_f32 v[66:67], v[66:67], v[152:153]
	v_pk_add_f32 v[68:69], v[68:69], v[154:155]
	global_store_dwordx4 v168, v[78:81], s[48:49]
	global_store_dwordx4 v168, v[74:77], s[48:49] offset:16
	global_store_dwordx4 v168, v[70:73], s[48:49] offset:512
	global_store_dwordx4 v168, v[66:69], s[48:49] offset:528
	v_cvt_pk_bf16_f32 v238, v78, v79
	v_cvt_pk_bf16_f32 v239, v80, v81
	v_cvt_pk_bf16_f32 v240, v74, v75
	v_cvt_pk_bf16_f32 v241, v76, v77
	v_cvt_pk_bf16_f32 v246, v70, v71
	v_cvt_pk_bf16_f32 v247, v72, v73
	v_cvt_pk_bf16_f32 v248, v66, v67
	v_cvt_pk_bf16_f32 v249, v68, v69
	global_store_dwordx4 v169, v[238:241], s[60:61]
	global_store_dwordx4 v169, v[246:249], s[60:61] offset:256
	s_add_u32 s24, s24, 0x10000
	s_addc_u32 s25, s25, 0
	global_load_dwordx4 v[238:241], v168, s[24:25]
	global_load_dwordx4 v[242:245], v168, s[24:25] offset:16
	global_load_dwordx4 v[246:249], v168, s[24:25] offset:512
	global_load_dwordx4 v[152:155], v168, s[24:25] offset:528
	v_mul_f32_e32 v177, v78, v78
	v_mul_f32_e32 v184, v74, v74
	v_fmac_f32_e32 v177, v79, v79
	v_fmac_f32_e32 v177, v80, v80
	v_fmac_f32_e32 v177, v81, v81
	v_fmac_f32_e32 v184, v75, v75
	v_fmac_f32_e32 v184, v76, v76
	v_fmac_f32_e32 v184, v77, v77
	v_fmac_f32_e32 v177, v70, v70
	v_fmac_f32_e32 v177, v71, v71
	v_fmac_f32_e32 v177, v72, v72
	v_fmac_f32_e32 v177, v73, v73
	v_fmac_f32_e32 v184, v66, v66
	v_fmac_f32_e32 v184, v67, v67
	v_fmac_f32_e32 v184, v68, v68
	v_fmac_f32_e32 v184, v69, v69
	v_add_f32_e32 v177, v177, v184
	ds_bpermute_b32 v184, v176, v177
	s_waitcnt lgkmcnt(0)
	v_add_f32_e32 v177, v177, v184
	v_mov_b32_e32 v184, v177
	s_nop 1
	v_permlane32_swap_b32_e32 v184, v177
	v_add_f32_e32 v206, v177, v184
	s_and_saveexec_b64 s[16:17], s[42:43]
	global_store_dword v170, v206, s[96:97]
	s_or_b64 exec, exec, s[16:17]
	s_add_u32 s48, s48, 0x50000
	s_addc_u32 s49, s49, 0
	s_add_u32 s60, s60, 0x28000
	s_addc_u32 s61, s61, 0
	s_add_u32 s96, s96, 0x1400
	s_addc_u32 s97, s97, 0
	s_waitcnt vmcnt(34)
; __device__ __forceinline__ unsigned cvt_pk_bf16(float lo, float hi) { unsigned r; asm volatile("v_cvt_pk_bf16_f32 %0, %1, %2" : "=v"(r) : "v"(lo), "v"(hi)); return r; }
;     DI bf16_t* z() const { return (bf16_t*)(ws + WS_Z); }
;     __device__ __forceinline__ void operator()(const f32x4 (&acc)[2][2][4][2], const Unit& u, int wr, int wc, int fr, int fq) const {
;     ...
;                     if (MODE == EM_RES) { const f32x4* hi = (const f32x4*)(Hin + (size_t)row * 1024 + col); f32x4* hp = (f32x4*)(H + (size_t)row * 1024 + col); v0 += hi[0]; v1 += hi[1]; hp[0] = v0; hp[1] = v1; }
;                     if (STATS) ss[bj] = ((v0[0] * v0[0] + v0[1] * v0[1]) + (v0[2] * v0[2] + v0[3] * v0[3])) + ((v1[0] * v1[0] + v1[1] * v1[1]) + (v1[2] * v1[2] + v1[3] * v1[3]));
;                     if (col < nvalid) { u32x4 w; w.x = cvt_pk_bf16(v0[0], v0[1]); w.y = cvt_pk_bf16(v0[2], v0[3]); w.z = cvt_pk_bf16(v1[0], v1[1]); w.w = cvt_pk_bf16(v1[2], v1[3]);
;                         *(u32x4*)(O + (size_t)row * ldc + col) = w; }
;                 }
;                 if (STATS == 1) { float t = ss[0] + ss[1]; t += __shfl_xor(t, 16); t += __shfl_xor(t, 32); if (fq == 0) ssq_out[(size_t)row * 16 + u.pn * 4 + wc] = t; }
	v_pk_add_f32 v[62:63], v[62:63], v[140:141]
	v_pk_add_f32 v[64:65], v[64:65], v[142:143]
	v_pk_add_f32 v[58:59], v[58:59], v[144:145]
	v_pk_add_f32 v[60:61], v[60:61], v[146:147]
	v_pk_add_f32 v[54:55], v[54:55], v[156:157]
	v_pk_add_f32 v[56:57], v[56:57], v[158:159]
	v_pk_add_f32 v[50:51], v[50:51], v[160:161]
	v_pk_add_f32 v[52:53], v[52:53], v[162:163]
	global_store_dwordx4 v168, v[62:65], s[48:49]
	global_store_dwordx4 v168, v[58:61], s[48:49] offset:16
	global_store_dwordx4 v168, v[54:57], s[48:49] offset:512
	global_store_dwordx4 v168, v[50:53], s[48:49] offset:528
	v_cvt_pk_bf16_f32 v140, v62, v63
	v_cvt_pk_bf16_f32 v141, v64, v65
	v_cvt_pk_bf16_f32 v142, v58, v59
	v_cvt_pk_bf16_f32 v143, v60, v61
	v_cvt_pk_bf16_f32 v156, v54, v55
	v_cvt_pk_bf16_f32 v157, v56, v57
	v_cvt_pk_bf16_f32 v158, v50, v51
	v_cvt_pk_bf16_f32 v159, v52, v53
	global_store_dwordx4 v169, v[140:143], s[60:61]
	global_store_dwordx4 v169, v[156:159], s[60:61] offset:256
	v_mul_f32_e32 v177, v62, v62
	v_mul_f32_e32 v184, v58, v58
	v_fmac_f32_e32 v177, v63, v63
	v_fmac_f32_e32 v177, v64, v64
	v_fmac_f32_e32 v177, v65, v65
	v_fmac_f32_e32 v184, v59, v59
	v_fmac_f32_e32 v184, v60, v60
	v_fmac_f32_e32 v184, v61, v61
	v_fmac_f32_e32 v177, v54, v54
	v_fmac_f32_e32 v177, v55, v55
	v_fmac_f32_e32 v177, v56, v56
	v_fmac_f32_e32 v177, v57, v57
	v_fmac_f32_e32 v184, v50, v50
	v_fmac_f32_e32 v184, v51, v51
	v_fmac_f32_e32 v184, v52, v52
	v_fmac_f32_e32 v184, v53, v53
	v_add_f32_e32 v177, v177, v184
	ds_bpermute_b32 v184, v176, v177
	s_waitcnt lgkmcnt(0)
	v_add_f32_e32 v177, v177, v184
	v_mov_b32_e32 v184, v177
	s_nop 1
	v_permlane32_swap_b32_e32 v184, v177
	v_add_f32_e32 v206, v177, v184
	s_and_saveexec_b64 s[16:17], s[42:43]
	global_store_dword v170, v206, s[96:97]
	s_or_b64 exec, exec, s[16:17]
	s_add_u32 s48, s48, 0x10000
	s_addc_u32 s49, s49, 0
	s_add_u32 s60, s60, 0x8000
	s_addc_u32 s61, s61, 0
	s_add_u32 s96, s96, 0x400
	s_addc_u32 s97, s97, 0
	s_waitcnt vmcnt(30)
	v_pk_add_f32 v[46:47], v[46:47], v[164:165]
	v_pk_add_f32 v[48:49], v[48:49], v[166:167]
	v_pk_add_f32 v[42:43], v[42:43], v[186:187]
	v_pk_add_f32 v[44:45], v[44:45], v[188:189]
	v_pk_add_f32 v[38:39], v[38:39], v[190:191]
	v_pk_add_f32 v[40:41], v[40:41], v[192:193]
	v_pk_add_f32 v[34:35], v[34:35], v[194:195]
	v_pk_add_f32 v[36:37], v[36:37], v[196:197]
	global_store_dwordx4 v168, v[46:49], s[48:49]
	global_store_dwordx4 v168, v[42:45], s[48:49] offset:16
	global_store_dwordx4 v168, v[38:41], s[48:49] offset:512
	global_store_dwordx4 v168, v[34:37], s[48:49] offset:528
	v_cvt_pk_bf16_f32 v164, v46, v47
	v_cvt_pk_bf16_f32 v165, v48, v49
	v_cvt_pk_bf16_f32 v166, v42, v43
	v_cvt_pk_bf16_f32 v167, v44, v45
	v_cvt_pk_bf16_f32 v190, v38, v39
	v_cvt_pk_bf16_f32 v191, v40, v41
	v_cvt_pk_bf16_f32 v192, v34, v35
	v_cvt_pk_bf16_f32 v193, v36, v37
	global_store_dwordx4 v169, v[164:167], s[60:61]
	global_store_dwordx4 v169, v[190:193], s[60:61] offset:256
	v_mul_f32_e32 v177, v46, v46
	v_mul_f32_e32 v184, v42, v42
	v_fmac_f32_e32 v177, v47, v47
	v_fmac_f32_e32 v177, v48, v48
	v_fmac_f32_e32 v177, v49, v49
	v_fmac_f32_e32 v184, v43, v43
	v_fmac_f32_e32 v184, v44, v44
	v_fmac_f32_e32 v184, v45, v45
	v_fmac_f32_e32 v177, v38, v38
	v_fmac_f32_e32 v177, v39, v39
	v_fmac_f32_e32 v177, v40, v40
	v_fmac_f32_e32 v177, v41, v41
	v_fmac_f32_e32 v184, v34, v34
	v_fmac_f32_e32 v184, v35, v35
	v_fmac_f32_e32 v184, v36, v36
	v_fmac_f32_e32 v184, v37, v37
	v_add_f32_e32 v177, v177, v184
	ds_bpermute_b32 v184, v176, v177
	s_waitcnt lgkmcnt(0)
	v_add_f32_e32 v177, v177, v184
	v_mov_b32_e32 v184, v177
	s_nop 1
	v_permlane32_swap_b32_e32 v184, v177
	v_add_f32_e32 v206, v177, v184
	s_and_saveexec_b64 s[16:17], s[42:43]
	global_store_dword v170, v206, s[96:97]
	s_or_b64 exec, exec, s[16:17]
	s_add_u32 s48, s48, 0x10000
	s_addc_u32 s49, s49, 0
	s_add_u32 s60, s60, 0x8000
	s_addc_u32 s61, s61, 0
	s_add_u32 s96, s96, 0x400
	s_addc_u32 s97, s97, 0
	s_waitcnt vmcnt(26)
; __device__ __forceinline__ unsigned cvt_pk_bf16(float lo, float hi) { unsigned r; asm volatile("v_cvt_pk_bf16_f32 %0, %1, %2" : "=v"(r) : "v"(lo), "v"(hi)); return r; }
;     DI bf16_t* z() const { return (bf16_t*)(ws + WS_Z); }
;     __device__ __forceinline__ void operator()(const f32x4 (&acc)[2][2][4][2], const Unit& u, int wr, int wc, int fr, int fq) const {
;     ...
;                     if (MODE == EM_RES) { const f32x4* hi = (const f32x4*)(Hin + (size_t)row * 1024 + col); f32x4* hp = (f32x4*)(H + (size_t)row * 1024 + col); v0 += hi[0]; v1 += hi[1]; hp[0] = v0; hp[1] = v1; }
;                     if (STATS) ss[bj] = ((v0[0] * v0[0] + v0[1] * v0[1]) + (v0[2] * v0[2] + v0[3] * v0[3])) + ((v1[0] * v1[0] + v1[1] * v1[1]) + (v1[2] * v1[2] + v1[3] * v1[3]));
;                     if (col < nvalid) { u32x4 w; w.x = cvt_pk_bf16(v0[0], v0[1]); w.y = cvt_pk_bf16(v0[2], v0[3]); w.z = cvt_pk_bf16(v1[0], v1[1]); w.w = cvt_pk_bf16(v1[2], v1[3]);
;                         *(u32x4*)(O + (size_t)row * ldc + col) = w; }
;                 }
;                 if (STATS == 1) { float t = ss[0] + ss[1]; t += __shfl_xor(t, 16); t += __shfl_xor(t, 32); if (fq == 0) ssq_out[(size_t)row * 16 + u.pn * 4 + wc] = t; }
	v_pk_add_f32 v[30:31], v[30:31], v[198:199]
	v_pk_add_f32 v[32:33], v[32:33], v[200:201]
	v_pk_add_f32 v[26:27], v[26:27], v[202:203]
	v_pk_add_f32 v[28:29], v[28:29], v[204:205]
	v_pk_add_f32 v[22:23], v[22:23], v[210:211]
	v_pk_add_f32 v[24:25], v[24:25], v[212:213]
	v_pk_add_f32 v[18:19], v[18:19], v[234:235]
	v_pk_add_f32 v[20:21], v[20:21], v[236:237]
	global_store_dwordx4 v168, v[30:33], s[48:49]
	global_store_dwordx4 v168, v[26:29], s[48:49] offset:16
	global_store_dwordx4 v168, v[22:25], s[48:49] offset:512
	global_store_dwordx4 v168, v[18:21], s[48:49] offset:528
	v_cvt_pk_bf16_f32 v198, v30, v31
	v_cvt_pk_bf16_f32 v199, v32, v33
	v_cvt_pk_bf16_f32 v200, v26, v27
	v_cvt_pk_bf16_f32 v201, v28, v29
	v_cvt_pk_bf16_f32 v210, v22, v23
	v_cvt_pk_bf16_f32 v211, v24, v25
	v_cvt_pk_bf16_f32 v212, v18, v19
	v_cvt_pk_bf16_f32 v213, v20, v21
	global_store_dwordx4 v169, v[198:201], s[60:61]
	global_store_dwordx4 v169, v[210:213], s[60:61] offset:256
	v_mul_f32_e32 v177, v30, v30
	v_mul_f32_e32 v184, v26, v26
	v_fmac_f32_e32 v177, v31, v31
	v_fmac_f32_e32 v177, v32, v32
	v_fmac_f32_e32 v177, v33, v33
	v_fmac_f32_e32 v184, v27, v27
	v_fmac_f32_e32 v184, v28, v28
	v_fmac_f32_e32 v184, v29, v29
	v_fmac_f32_e32 v177, v22, v22
	v_fmac_f32_e32 v177, v23, v23
	v_fmac_f32_e32 v177, v24, v24
	v_fmac_f32_e32 v177, v25, v25
	v_fmac_f32_e32 v184, v18, v18
	v_fmac_f32_e32 v184, v19, v19
	v_fmac_f32_e32 v184, v20, v20
	v_fmac_f32_e32 v184, v21, v21
	v_add_f32_e32 v177, v177, v184
	ds_bpermute_b32 v184, v176, v177
	s_waitcnt lgkmcnt(0)
	v_add_f32_e32 v177, v177, v184
	v_mov_b32_e32 v184, v177
	s_nop 1
	v_permlane32_swap_b32_e32 v184, v177
	v_add_f32_e32 v206, v177, v184
	s_and_saveexec_b64 s[16:17], s[42:43]
	global_store_dword v170, v206, s[96:97]
	s_or_b64 exec, exec, s[16:17]
	s_add_u32 s48, s48, 0x10000
	s_addc_u32 s49, s49, 0
	s_add_u32 s60, s60, 0x8000
	s_addc_u32 s61, s61, 0
	s_add_u32 s96, s96, 0x400
	s_addc_u32 s97, s97, 0
	s_waitcnt vmcnt(22)
	v_pk_add_f32 v[14:15], v[14:15], v[238:239]
	v_pk_add_f32 v[16:17], v[16:17], v[240:241]
	v_pk_add_f32 v[10:11], v[10:11], v[242:243]
	v_pk_add_f32 v[12:13], v[12:13], v[244:245]
	v_pk_add_f32 v[6:7], v[6:7], v[246:247]
	v_pk_add_f32 v[8:9], v[8:9], v[248:249]
	v_pk_add_f32 v[2:3], v[2:3], v[152:153]
	v_pk_add_f32 v[4:5], v[4:5], v[154:155]
	global_store_dwordx4 v168, v[14:17], s[48:49]
	global_store_dwordx4 v168, v[10:13], s[48:49] offset:16
	global_store_dwordx4 v168, v[6:9], s[48:49] offset:512
	global_store_dwordx4 v168, v[2:5], s[48:49] offset:528
	v_cvt_pk_bf16_f32 v238, v14, v15
	v_cvt_pk_bf16_f32 v239, v16, v17
	v_cvt_pk_bf16_f32 v240, v10, v11
	v_cvt_pk_bf16_f32 v241, v12, v13
	v_cvt_pk_bf16_f32 v246, v6, v7
	v_cvt_pk_bf16_f32 v247, v8, v9
	v_cvt_pk_bf16_f32 v248, v2, v3
	v_cvt_pk_bf16_f32 v249, v4, v5
	global_store_dwordx4 v169, v[238:241], s[60:61]
	global_store_dwordx4 v169, v[246:249], s[60:61] offset:256
	v_mul_f32_e32 v177, v14, v14
	v_mul_f32_e32 v184, v10, v10
	v_fmac_f32_e32 v177, v15, v15
	v_fmac_f32_e32 v177, v16, v16
	v_fmac_f32_e32 v177, v17, v17
	v_fmac_f32_e32 v184, v11, v11
	v_fmac_f32_e32 v184, v12, v12
	v_fmac_f32_e32 v184, v13, v13
	v_fmac_f32_e32 v177, v6, v6
	v_fmac_f32_e32 v177, v7, v7
	v_fmac_f32_e32 v177, v8, v8
	v_fmac_f32_e32 v177, v9, v9
	v_fmac_f32_e32 v184, v2, v2
	v_fmac_f32_e32 v184, v3, v3
	v_fmac_f32_e32 v184, v4, v4
	v_fmac_f32_e32 v184, v5, v5
	v_add_f32_e32 v177, v177, v184
	ds_bpermute_b32 v184, v176, v177
	s_waitcnt lgkmcnt(0)
	v_add_f32_e32 v177, v177, v184
	v_mov_b32_e32 v184, v177
	s_nop 1
	v_permlane32_swap_b32_e32 v184, v177
	v_add_f32_e32 v206, v177, v184
	s_and_saveexec_b64 s[16:17], s[42:43]
	global_store_dword v170, v206, s[96:97]
	s_or_b64 exec, exec, s[16:17]
	v_readlane_b32 s92, v254, 29
	v_readlane_b32 s93, v254, 30
	v_readlane_b32 s76, v254, 38
	v_readlane_b32 s77, v254, 39
	v_readlane_b32 s78, v254, 40
	v_readlane_b32 s79, v254, 41
	s_and_b64 vcc, exec, s[44:45]
	s_mov_b64 s[16:17], -1
	s_cbranch_vccnz .LBB0_1647
	s_andn2_b64 vcc, exec, s[10:11]
	s_cbranch_vccnz .LBB0_1646
	s_barrier
	s_branch .LBB0_1646

;     __device__ __forceinline__ void operator()(const f32x4 (&acc)[2][2][4][2], const Unit& u, int wr, int wc, int fr, int fq) const {
;         const int row0 = u.pm * BM + wr * 64 + fr, col0 = u.pn * BM + wc * 32 + 8 * fq;
; #pragma unroll
;         for (int ai = 0; ai < 2; ++ai)
; #pragma unroll
;             for (int m = 0; m < 4; ++m) {
;                 const int row = row0 + ai * HALF + m * 16;
;                 float sc = 1.f;
;                 if (MODE == EM_SCALEH) sc = ::rstd_h(ssq_in, row + rowoff);
;                 if (MODE == EM_SCALEQ) sc = ::rstd_q(ssq_in, row);
;                 if (MODE == EM_SCALEKV) sc = ::rstd_kv(ssq_in, row);
;                 float ss[2] = {0.f, 0.f};
; #pragma unroll
;                 for (int bj = 0; bj < 2; ++bj) {
;                     const int col = col0 + bj * HALF;
;                     f32x4 v0 = acc[ai][bj][m][0] * sc, v1 = acc[ai][bj][m][1] * sc;
;                     if (MODE == EM_GELU) { if (col < nvalid) { const f32x4 b0 = *(const f32x4*)(bias + col), b1 = *(const f32x4*)(bias + col + 4);
; #pragma unroll
;                         for (int i = 0; i < 4; ++i) { v0[i] = ::gelu_tanh(v0[i] + b0[i]); v1[i] = ::gelu_tanh(v1[i] + b1[i]); } } }
;                     if (MODE == EM_RES) { const f32x4* hi = (const f32x4*)(Hin + (size_t)row * 1024 + col); f32x4* hp = (f32x4*)(H + (size_t)row * 1024 + col); v0 += hi[0]; v1 += hi[1]; hp[0] = v0; hp[1] = v1; }
;                     if (STATS) ss[bj] = ((v0[0] * v0[0] + v0[1] * v0[1]) + (v0[2] * v0[2] + v0[3] * v0[3])) + ((v1[0] * v1[0] + v1[1] * v1[1]) + (v1[2] * v1[2] + v1[3] * v1[3]));
;                     if (col < nvalid) { u32x4 w; w.x = cvt_pk_bf16(v0[0], v0[1]); w.y = cvt_pk_bf16(v0[2], v0[3]); w.z = cvt_pk_bf16(v1[0], v1[1]); w.w = cvt_pk_bf16(v1[2], v1[3]);
;                         *(u32x4*)(O + (size_t)row * ldc + col) = w; }
;                 }
;                 if (STATS == 1) { float t = ss[0] + ss[1]; t += __shfl_xor(t, 16); t += __shfl_xor(t, 32); if (fq == 0) ssq_out[(size_t)row * 16 + u.pn * 4 + wc] = t; }
;                 if (STATS == 2) { if (u.pn <= 2) { float t0 = ss[0], t1 = ss[1]; t0 += __shfl_xor(t0, 16); t0 += __shfl_xor(t0, 32); t1 += __shfl_xor(t1, 16); t1 += __shfl_xor(t1, 32);
;                     if (fq == 0) { ssq_out[(size_t)row * 24 + u.pn * 8 + wc] = t0; ssq_out[(size_t)row * 24 + u.pn * 8 + 4 + wc] = t1; } } }
.LBB0_1801:
	v_and_b32_e32 v251, 48, v221
	v_xor_b32_e32 v213, 16, v221
	v_lshlrev_b32_e32 v213, 2, v213
	v_min_u32_e32 v212, 48, v251
	v_lshl_add_u32 v212, v146, 6, v212
	v_lshlrev_b32_e32 v211, 1, v148
	v_lshl_add_u32 v211, v146, 12, v211
	s_mul_i32 s32, s46, 0x100000
	s_add_u32 s68, s52, s32
	s_addc_u32 s69, s53, 0
	s_lshl_b32 s32, s8, 9
	s_add_u32 s68, s68, s32
	s_addc_u32 s69, s69, 0
	s_mul_i32 s32, s46, 0x4000
	s_add_u32 s48, s54, s32
	s_addc_u32 s49, s55, 0
	v_lshlrev_b32_e32 v250, 6, v146
	v_lshl_add_u32 v250, v146, 5, v250
	s_mul_i32 s32, s46, 0x6000
	s_add_u32 s50, s56, s32
	s_addc_u32 s51, s57, 0
	s_lshl_b32 s32, s8, 3
	s_add_i32 s32, s32, s11
	s_lshl_b32 s32, s32, 2
	s_add_u32 s50, s50, s32
	s_addc_u32 s51, s51, 0
	global_load_dwordx4 v[140:143], v212, s[48:49]
	s_add_u32 s48, s48, 0x400
	s_addc_u32 s49, s49, 0
	global_load_dwordx4 v[150:153], v212, s[48:49]
	s_add_u32 s48, s48, 0x400
	s_addc_u32 s49, s49, 0
	global_load_dwordx4 v[154:157], v212, s[48:49]
	s_add_u32 s48, s48, 0x400
	s_addc_u32 s49, s49, 0
	global_load_dwordx4 v[158:161], v212, s[48:49]
	s_add_u32 s48, s48, 0x1400
	s_addc_u32 s49, s49, 0
	global_load_dwordx4 v[162:165], v212, s[48:49]
	s_add_u32 s48, s48, 0x400
	s_addc_u32 s49, s49, 0
	global_load_dwordx4 v[166:169], v212, s[48:49]
	s_add_u32 s48, s48, 0x400
	s_addc_u32 s49, s49, 0
	global_load_dwordx4 v[186:189], v212, s[48:49]
	s_add_u32 s48, s48, 0x400
	s_addc_u32 s49, s49, 0
	global_load_dwordx4 v[190:193], v212, s[48:49]
	s_waitcnt vmcnt(0)
	v_add_f32_e32 v194, v140, v141
	v_add_f32_e32 v202, v142, v143
	v_add_f32_e32 v195, v150, v151
	v_add_f32_e32 v203, v152, v153
	v_add_f32_e32 v196, v154, v155
	v_add_f32_e32 v204, v156, v157
	v_add_f32_e32 v197, v158, v159
	v_add_f32_e32 v205, v160, v161
	v_add_f32_e32 v198, v162, v163
	v_add_f32_e32 v206, v164, v165
	v_add_f32_e32 v199, v166, v167
	v_add_f32_e32 v207, v168, v169
	v_add_f32_e32 v200, v186, v187
	v_add_f32_e32 v208, v188, v189
	v_add_f32_e32 v201, v190, v191
	v_add_f32_e32 v210, v192, v193
	v_add_f32_e32 v194, v194, v202
	v_add_f32_e32 v195, v195, v203
	v_add_f32_e32 v196, v196, v204
	v_add_f32_e32 v197, v197, v205
	v_add_f32_e32 v198, v198, v206
	v_add_f32_e32 v199, v199, v207
	v_add_f32_e32 v200, v200, v208
	v_add_f32_e32 v201, v201, v210
	ds_bpermute_b32 v202, v213, v194
	ds_bpermute_b32 v203, v213, v195
	ds_bpermute_b32 v204, v213, v196
	ds_bpermute_b32 v205, v213, v197
	ds_bpermute_b32 v206, v213, v198
	ds_bpermute_b32 v207, v213, v199
	ds_bpermute_b32 v208, v213, v200
	ds_bpermute_b32 v210, v213, v201
	s_waitcnt lgkmcnt(0)
	v_add_f32_e32 v194, v194, v202
	v_add_f32_e32 v195, v195, v203
	v_add_f32_e32 v196, v196, v204
	v_add_f32_e32 v197, v197, v205
	v_add_f32_e32 v198, v198, v206
	v_add_f32_e32 v199, v199, v207
	v_add_f32_e32 v200, v200, v208
	v_add_f32_e32 v201, v201, v210
	v_mov_b32_e32 v202, v194
	v_mov_b32_e32 v203, v195
	v_mov_b32_e32 v204, v196
	v_mov_b32_e32 v205, v197
	v_mov_b32_e32 v206, v198
	v_mov_b32_e32 v207, v199
	v_mov_b32_e32 v208, v200
	v_mov_b32_e32 v210, v201
	s_nop 1
	v_permlane32_swap_b32_e32 v202, v194
	v_permlane32_swap_b32_e32 v203, v195
	v_permlane32_swap_b32_e32 v204, v196
	v_permlane32_swap_b32_e32 v205, v197
	v_permlane32_swap_b32_e32 v206, v198
	v_permlane32_swap_b32_e32 v207, v199
	v_permlane32_swap_b32_e32 v208, v200
	v_permlane32_swap_b32_e32 v210, v201
	v_add_f32_e32 v194, v194, v202
	v_add_f32_e32 v195, v195, v203
	v_add_f32_e32 v196, v196, v204
	v_add_f32_e32 v197, v197, v205
	v_add_f32_e32 v198, v198, v206
	v_add_f32_e32 v199, v199, v207
	v_add_f32_e32 v200, v200, v208
	v_add_f32_e32 v201, v201, v210
	s_mov_b32 s32, 0x800000
	v_fmamk_f32 v194, v194, 0x3a800000, v215
	v_cmp_gt_f32_e32 vcc, s32, v194
	v_mul_f32_e32 v202, 0x4b800000, v194
	s_nop 0
	v_cndmask_b32_e32 v194, v194, v202, vcc
	v_rsq_f32_e32 v194, v194
	s_nop 0
	v_mul_f32_e32 v202, 0x45800000, v194
	v_cndmask_b32_e32 v194, v194, v202, vcc
	v_fmamk_f32 v195, v195, 0x3a800000, v215
	v_cmp_gt_f32_e32 vcc, s32, v195
	v_mul_f32_e32 v203, 0x4b800000, v195
	s_nop 0
	v_cndmask_b32_e32 v195, v195, v203, vcc
	v_rsq_f32_e32 v195, v195
	s_nop 0
	v_mul_f32_e32 v203, 0x45800000, v195
	v_cndmask_b32_e32 v195, v195, v203, vcc
	v_fmamk_f32 v196, v196, 0x3a800000, v215
	v_cmp_gt_f32_e32 vcc, s32, v196
	v_mul_f32_e32 v204, 0x4b800000, v196
	s_nop 0
	v_cndmask_b32_e32 v196, v196, v204, vcc
	v_rsq_f32_e32 v196, v196
	s_nop 0
	v_mul_f32_e32 v204, 0x45800000, v196
	v_cndmask_b32_e32 v196, v196, v204, vcc
	v_fmamk_f32 v197, v197, 0x3a800000, v215
	v_cmp_gt_f32_e32 vcc, s32, v197
	v_mul_f32_e32 v205, 0x4b800000, v197
	s_nop 0
	v_cndmask_b32_e32 v197, v197, v205, vcc
	v_rsq_f32_e32 v197, v197
	s_nop 0
	v_mul_f32_e32 v205, 0x45800000, v197
	v_cndmask_b32_e32 v197, v197, v205, vcc
	v_fmamk_f32 v198, v198, 0x3a800000, v215
	v_cmp_gt_f32_e32 vcc, s32, v198
	v_mul_f32_e32 v206, 0x4b800000, v198
	s_nop 0
	v_cndmask_b32_e32 v198, v198, v206, vcc
	v_rsq_f32_e32 v198, v198
	s_nop 0
	v_mul_f32_e32 v206, 0x45800000, v198
	v_cndmask_b32_e32 v198, v198, v206, vcc
	v_fmamk_f32 v199, v199, 0x3a800000, v215
	v_cmp_gt_f32_e32 vcc, s32, v199
	v_mul_f32_e32 v207, 0x4b800000, v199
	s_nop 0
	v_cndmask_b32_e32 v199, v199, v207, vcc
	v_rsq_f32_e32 v199, v199
	s_nop 0
	v_mul_f32_e32 v207, 0x45800000, v199
	v_cndmask_b32_e32 v199, v199, v207, vcc
	v_fmamk_f32 v200, v200, 0x3a800000, v215
	v_cmp_gt_f32_e32 vcc, s32, v200
	v_mul_f32_e32 v208, 0x4b800000, v200
	s_nop 0
	v_cndmask_b32_e32 v200, v200, v208, vcc
	v_rsq_f32_e32 v200, v200
	s_nop 0
	v_mul_f32_e32 v208, 0x45800000, v200
	v_cndmask_b32_e32 v200, v200, v208, vcc
	v_fmamk_f32 v201, v201, 0x3a800000, v215
	v_cmp_gt_f32_e32 vcc, s32, v201
	v_mul_f32_e32 v210, 0x4b800000, v201
	s_nop 0
	v_cndmask_b32_e32 v201, v201, v210, vcc
	v_rsq_f32_e32 v201, v201
	s_nop 0
	v_mul_f32_e32 v210, 0x45800000, v201
	v_cndmask_b32_e32 v201, v201, v210, vcc
	s_cmp_lt_i32 s8, 3
	s_cselect_b32 s23, 1, 0
	v_mul_f32_e32 v126, v126, v194
	v_mul_f32_e32 v127, v127, v194
	v_mul_f32_e32 v128, v128, v194
	v_mul_f32_e32 v129, v129, v194
	v_mul_f32_e32 v122, v122, v194
	v_mul_f32_e32 v123, v123, v194
	v_mul_f32_e32 v124, v124, v194
	v_mul_f32_e32 v125, v125, v194
	v_mul_f32_e32 v118, v118, v194
	v_mul_f32_e32 v119, v119, v194
	v_mul_f32_e32 v120, v120, v194
	v_mul_f32_e32 v121, v121, v194
	v_mul_f32_e32 v114, v114, v194
	v_mul_f32_e32 v115, v115, v194
	v_mul_f32_e32 v116, v116, v194
	v_mul_f32_e32 v117, v117, v194
	v_cvt_pk_bf16_f32 v234, v126, v127
	v_cvt_pk_bf16_f32 v235, v128, v129
	v_cvt_pk_bf16_f32 v236, v122, v123
	v_cvt_pk_bf16_f32 v237, v124, v125
	v_cvt_pk_bf16_f32 v238, v118, v119
	v_cvt_pk_bf16_f32 v239, v120, v121
	v_cvt_pk_bf16_f32 v240, v114, v115
	v_cvt_pk_bf16_f32 v241, v116, v117
	global_store_dwordx4 v211, v[234:237], s[68:69]
	global_store_dwordx4 v211, v[238:241], s[68:69] offset:256
	s_cmp_eq_u32 s23, 0
	s_cbranch_scc1 .Lzep_ns0
; DI float gelu_tanh(float x) { return 0.5f * x * (1.f + tanhf(0.7978845608028654f * (x + 0.044715f * x * x * x))); }
; __device__ __forceinline__ unsigned cvt_pk_bf16(float lo, float hi) { unsigned r; asm volatile("v_cvt_pk_bf16_f32 %0, %1, %2" : "=v"(r) : "v"(lo), "v"(hi)); return r; }
;     DI bf16_t* z() const { return (bf16_t*)(ws + WS_Z); }
;     DI float* b1(int l, int v) const { return (float*)(ws + WS_B1) + (l * 2 + v) * 128; }
;     __device__ __forceinline__ void operator()(const f32x4 (&acc)[2][2][4][2], const Unit& u, int wr, int wc, int fr, int fq) const {
;     ...
;                     f32x4 v0 = acc[ai][bj][m][0] * sc, v1 = acc[ai][bj][m][1] * sc;
;                     if (MODE == EM_GELU) { if (col < nvalid) { const f32x4 b0 = *(const f32x4*)(bias + col), b1 = *(const f32x4*)(bias + col + 4);
; #pragma unroll
;                         for (int i = 0; i < 4; ++i) { v0[i] = ::gelu_tanh(v0[i] + b0[i]); v1[i] = ::gelu_tanh(v1[i] + b1[i]); } } }
;                     if (MODE == EM_RES) { const f32x4* hi = (const f32x4*)(Hin + (size_t)row * 1024 + col); f32x4* hp = (f32x4*)(H + (size_t)row * 1024 + col); v0 += hi[0]; v1 += hi[1]; hp[0] = v0; hp[1] = v1; }
;                     if (STATS) ss[bj] = ((v0[0] * v0[0] + v0[1] * v0[1]) + (v0[2] * v0[2] + v0[3] * v0[3])) + ((v1[0] * v1[0] + v1[1] * v1[1]) + (v1[2] * v1[2] + v1[3] * v1[3]));
;                     if (col < nvalid) { u32x4 w; w.x = cvt_pk_bf16(v0[0], v0[1]); w.y = cvt_pk_bf16(v0[2], v0[3]); w.z = cvt_pk_bf16(v1[0], v1[1]); w.w = cvt_pk_bf16(v1[2], v1[3]);
;                         *(u32x4*)(O + (size_t)row * ldc + col) = w; }
;                 }
;                 if (STATS == 1) { float t = ss[0] + ss[1]; t += __shfl_xor(t, 16); t += __shfl_xor(t, 32); if (fq == 0) ssq_out[(size_t)row * 16 + u.pn * 4 + wc] = t; }
;                 if (STATS == 2) { if (u.pn <= 2) { float t0 = ss[0], t1 = ss[1]; t0 += __shfl_xor(t0, 16); t0 += __shfl_xor(t0, 32); t1 += __shfl_xor(t1, 16); t1 += __shfl_xor(t1, 32);
;                     if (fq == 0) { ssq_out[(size_t)row * 24 + u.pn * 8 + wc] = t0; ssq_out[(size_t)row * 24 + u.pn * 8 + 4 + wc] = t1; } } }
	v_mul_f32_e32 v242, v126, v126
	v_mul_f32_e32 v243, v118, v118
	v_fmac_f32_e32 v242, v127, v127
	v_fmac_f32_e32 v242, v128, v128
	v_fmac_f32_e32 v242, v129, v129
	v_fmac_f32_e32 v242, v122, v122
	v_fmac_f32_e32 v242, v123, v123
	v_fmac_f32_e32 v242, v124, v124
	v_fmac_f32_e32 v242, v125, v125
	v_fmac_f32_e32 v243, v119, v119
	v_fmac_f32_e32 v243, v120, v120
	v_fmac_f32_e32 v243, v121, v121
	v_fmac_f32_e32 v243, v114, v114
	v_fmac_f32_e32 v243, v115, v115
	v_fmac_f32_e32 v243, v116, v116
	v_fmac_f32_e32 v243, v117, v117
	ds_bpermute_b32 v244, v213, v242
	ds_bpermute_b32 v245, v213, v243
	s_waitcnt lgkmcnt(0)
	v_add_f32_e32 v242, v242, v244
	v_add_f32_e32 v243, v243, v245
	v_mov_b32_e32 v244, v242
	v_mov_b32_e32 v245, v243
	s_nop 1
	v_permlane32_swap_b32_e32 v244, v242
	v_permlane32_swap_b32_e32 v245, v243
	v_add_f32_e32 v246, v242, v244
	v_add_f32_e32 v247, v243, v245
	s_and_saveexec_b64 s[16:17], s[42:43]
	global_store_dword v250, v246, s[50:51]
	global_store_dword v250, v247, s[50:51] offset:16
	s_or_b64 exec, exec, s[16:17]
.Lzep_ns0:
	s_add_u32 s68, s68, 0x10000
	s_addc_u32 s69, s69, 0
	s_add_u32 s50, s50, 0x600
	s_addc_u32 s51, s51, 0
	v_mul_f32_e32 v110, v110, v195
	v_mul_f32_e32 v111, v111, v195
	v_mul_f32_e32 v112, v112, v195
	v_mul_f32_e32 v113, v113, v195
	v_mul_f32_e32 v106, v106, v195
	v_mul_f32_e32 v107, v107, v195
	v_mul_f32_e32 v108, v108, v195
	v_mul_f32_e32 v109, v109, v195
	v_mul_f32_e32 v102, v102, v195
	v_mul_f32_e32 v103, v103, v195
	v_mul_f32_e32 v104, v104, v195
	v_mul_f32_e32 v105, v105, v195
	v_mul_f32_e32 v98, v98, v195
	v_mul_f32_e32 v99, v99, v195
	v_mul_f32_e32 v100, v100, v195
	v_mul_f32_e32 v101, v101, v195
	v_cvt_pk_bf16_f32 v234, v110, v111
	v_cvt_pk_bf16_f32 v235, v112, v113
	v_cvt_pk_bf16_f32 v236, v106, v107
	v_cvt_pk_bf16_f32 v237, v108, v109
	v_cvt_pk_bf16_f32 v238, v102, v103
	v_cvt_pk_bf16_f32 v239, v104, v105
	v_cvt_pk_bf16_f32 v240, v98, v99
	v_cvt_pk_bf16_f32 v241, v100, v101
	global_store_dwordx4 v211, v[234:237], s[68:69]
	global_store_dwordx4 v211, v[238:241], s[68:69] offset:256
	s_cmp_eq_u32 s23, 0
	s_cbranch_scc1 .Lzep_ns1
	v_mul_f32_e32 v242, v110, v110
	v_mul_f32_e32 v243, v102, v102
	v_fmac_f32_e32 v242, v111, v111
	v_fmac_f32_e32 v242, v112, v112
	v_fmac_f32_e32 v242, v113, v113
	v_fmac_f32_e32 v242, v106, v106
	v_fmac_f32_e32 v242, v107, v107
	v_fmac_f32_e32 v242, v108, v108
	v_fmac_f32_e32 v242, v109, v109
	v_fmac_f32_e32 v243, v103, v103
	v_fmac_f32_e32 v243, v104, v104
	v_fmac_f32_e32 v243, v105, v105
	v_fmac_f32_e32 v243, v98, v98
	v_fmac_f32_e32 v243, v99, v99
	v_fmac_f32_e32 v243, v100, v100
	v_fmac_f32_e32 v243, v101, v101
	ds_bpermute_b32 v244, v213, v242
	ds_bpermute_b32 v245, v213, v243
	s_waitcnt lgkmcnt(0)
	v_add_f32_e32 v242, v242, v244
	v_add_f32_e32 v243, v243, v245
	v_mov_b32_e32 v244, v242
	v_mov_b32_e32 v245, v243
	s_nop 1
	v_permlane32_swap_b32_e32 v244, v242
	v_permlane32_swap_b32_e32 v245, v243
	v_add_f32_e32 v246, v242, v244
	v_add_f32_e32 v247, v243, v245
	s_and_saveexec_b64 s[16:17], s[42:43]
	global_store_dword v250, v246, s[50:51]
	global_store_dword v250, v247, s[50:51] offset:16
	s_or_b64 exec, exec, s[16:17]
.Lzep_ns1:
	s_add_u32 s68, s68, 0x10000
	s_addc_u32 s69, s69, 0
	s_add_u32 s50, s50, 0x600
	s_addc_u32 s51, s51, 0
	v_mul_f32_e32 v94, v94, v196
	v_mul_f32_e32 v95, v95, v196
	v_mul_f32_e32 v96, v96, v196
	v_mul_f32_e32 v97, v97, v196
	v_mul_f32_e32 v90, v90, v196
	v_mul_f32_e32 v91, v91, v196
	v_mul_f32_e32 v92, v92, v196
	v_mul_f32_e32 v93, v93, v196
	v_mul_f32_e32 v86, v86, v196
	v_mul_f32_e32 v87, v87, v196
	v_mul_f32_e32 v88, v88, v196
	v_mul_f32_e32 v89, v89, v196
	v_mul_f32_e32 v82, v82, v196
	v_mul_f32_e32 v83, v83, v196
	v_mul_f32_e32 v84, v84, v196
	v_mul_f32_e32 v85, v85, v196
	v_cvt_pk_bf16_f32 v234, v94, v95
	v_cvt_pk_bf16_f32 v235, v96, v97
	v_cvt_pk_bf16_f32 v236, v90, v91
	v_cvt_pk_bf16_f32 v237, v92, v93
	v_cvt_pk_bf16_f32 v238, v86, v87
	v_cvt_pk_bf16_f32 v239, v88, v89
	v_cvt_pk_bf16_f32 v240, v82, v83
	v_cvt_pk_bf16_f32 v241, v84, v85
	global_store_dwordx4 v211, v[234:237], s[68:69]
	global_store_dwordx4 v211, v[238:241], s[68:69] offset:256
	s_cmp_eq_u32 s23, 0
	s_cbranch_scc1 .Lzep_ns2
	v_mul_f32_e32 v242, v94, v94
	v_mul_f32_e32 v243, v86, v86
	v_fmac_f32_e32 v242, v95, v95
	v_fmac_f32_e32 v242, v96, v96
	v_fmac_f32_e32 v242, v97, v97
	v_fmac_f32_e32 v242, v90, v90
	v_fmac_f32_e32 v242, v91, v91
	v_fmac_f32_e32 v242, v92, v92
	v_fmac_f32_e32 v242, v93, v93
	v_fmac_f32_e32 v243, v87, v87
	v_fmac_f32_e32 v243, v88, v88
	v_fmac_f32_e32 v243, v89, v89
	v_fmac_f32_e32 v243, v82, v82
	v_fmac_f32_e32 v243, v83, v83
	v_fmac_f32_e32 v243, v84, v84
	v_fmac_f32_e32 v243, v85, v85
	ds_bpermute_b32 v244, v213, v242
	ds_bpermute_b32 v245, v213, v243
	s_waitcnt lgkmcnt(0)
	v_add_f32_e32 v242, v242, v244
	v_add_f32_e32 v243, v243, v245
	v_mov_b32_e32 v244, v242
	v_mov_b32_e32 v245, v243
	s_nop 1
	v_permlane32_swap_b32_e32 v244, v242
	v_permlane32_swap_b32_e32 v245, v243
	v_add_f32_e32 v246, v242, v244
	v_add_f32_e32 v247, v243, v245
	s_and_saveexec_b64 s[16:17], s[42:43]
	global_store_dword v250, v246, s[50:51]
	global_store_dword v250, v247, s[50:51] offset:16
	s_or_b64 exec, exec, s[16:17]
; DI float gelu_tanh(float x) { return 0.5f * x * (1.f + tanhf(0.7978845608028654f * (x + 0.044715f * x * x * x))); }
; __device__ __forceinline__ unsigned cvt_pk_bf16(float lo, float hi) { unsigned r; asm volatile("v_cvt_pk_bf16_f32 %0, %1, %2" : "=v"(r) : "v"(lo), "v"(hi)); return r; }
;     DI bf16_t* z() const { return (bf16_t*)(ws + WS_Z); }
;     DI float* b1(int l, int v) const { return (float*)(ws + WS_B1) + (l * 2 + v) * 128; }
;     __device__ __forceinline__ void operator()(const f32x4 (&acc)[2][2][4][2], const Unit& u, int wr, int wc, int fr, int fq) const {
;     ...
;                     f32x4 v0 = acc[ai][bj][m][0] * sc, v1 = acc[ai][bj][m][1] * sc;
;                     if (MODE == EM_GELU) { if (col < nvalid) { const f32x4 b0 = *(const f32x4*)(bias + col), b1 = *(const f32x4*)(bias + col + 4);
; #pragma unroll
;                         for (int i = 0; i < 4; ++i) { v0[i] = ::gelu_tanh(v0[i] + b0[i]); v1[i] = ::gelu_tanh(v1[i] + b1[i]); } } }
;                     if (MODE == EM_RES) { const f32x4* hi = (const f32x4*)(Hin + (size_t)row * 1024 + col); f32x4* hp = (f32x4*)(H + (size_t)row * 1024 + col); v0 += hi[0]; v1 += hi[1]; hp[0] = v0; hp[1] = v1; }
;                     if (STATS) ss[bj] = ((v0[0] * v0[0] + v0[1] * v0[1]) + (v0[2] * v0[2] + v0[3] * v0[3])) + ((v1[0] * v1[0] + v1[1] * v1[1]) + (v1[2] * v1[2] + v1[3] * v1[3]));
;                     if (col < nvalid) { u32x4 w; w.x = cvt_pk_bf16(v0[0], v0[1]); w.y = cvt_pk_bf16(v0[2], v0[3]); w.z = cvt_pk_bf16(v1[0], v1[1]); w.w = cvt_pk_bf16(v1[2], v1[3]);
;                         *(u32x4*)(O + (size_t)row * ldc + col) = w; }
;                 }
;                 if (STATS == 1) { float t = ss[0] + ss[1]; t += __shfl_xor(t, 16); t += __shfl_xor(t, 32); if (fq == 0) ssq_out[(size_t)row * 16 + u.pn * 4 + wc] = t; }
;                 if (STATS == 2) { if (u.pn <= 2) { float t0 = ss[0], t1 = ss[1]; t0 += __shfl_xor(t0, 16); t0 += __shfl_xor(t0, 32); t1 += __shfl_xor(t1, 16); t1 += __shfl_xor(t1, 32);
;                     if (fq == 0) { ssq_out[(size_t)row * 24 + u.pn * 8 + wc] = t0; ssq_out[(size_t)row * 24 + u.pn * 8 + 4 + wc] = t1; } } }
.Lzep_ns2:
	s_add_u32 s68, s68, 0x10000
	s_addc_u32 s69, s69, 0
	s_add_u32 s50, s50, 0x600
	s_addc_u32 s51, s51, 0
	v_mul_f32_e32 v78, v78, v197
	v_mul_f32_e32 v79, v79, v197
	v_mul_f32_e32 v80, v80, v197
	v_mul_f32_e32 v81, v81, v197
	v_mul_f32_e32 v74, v74, v197
	v_mul_f32_e32 v75, v75, v197
	v_mul_f32_e32 v76, v76, v197
	v_mul_f32_e32 v77, v77, v197
	v_mul_f32_e32 v70, v70, v197
	v_mul_f32_e32 v71, v71, v197
	v_mul_f32_e32 v72, v72, v197
	v_mul_f32_e32 v73, v73, v197
	v_mul_f32_e32 v66, v66, v197
	v_mul_f32_e32 v67, v67, v197
	v_mul_f32_e32 v68, v68, v197
	v_mul_f32_e32 v69, v69, v197
	v_cvt_pk_bf16_f32 v234, v78, v79
	v_cvt_pk_bf16_f32 v235, v80, v81
	v_cvt_pk_bf16_f32 v236, v74, v75
	v_cvt_pk_bf16_f32 v237, v76, v77
	v_cvt_pk_bf16_f32 v238, v70, v71
	v_cvt_pk_bf16_f32 v239, v72, v73
	v_cvt_pk_bf16_f32 v240, v66, v67
	v_cvt_pk_bf16_f32 v241, v68, v69
	global_store_dwordx4 v211, v[234:237], s[68:69]
	global_store_dwordx4 v211, v[238:241], s[68:69] offset:256
	s_cmp_eq_u32 s23, 0
	s_cbranch_scc1 .Lzep_ns3
	v_mul_f32_e32 v242, v78, v78
	v_mul_f32_e32 v243, v70, v70
	v_fmac_f32_e32 v242, v79, v79
	v_fmac_f32_e32 v242, v80, v80
	v_fmac_f32_e32 v242, v81, v81
	v_fmac_f32_e32 v242, v74, v74
	v_fmac_f32_e32 v242, v75, v75
	v_fmac_f32_e32 v242, v76, v76
	v_fmac_f32_e32 v242, v77, v77
	v_fmac_f32_e32 v243, v71, v71
	v_fmac_f32_e32 v243, v72, v72
	v_fmac_f32_e32 v243, v73, v73
	v_fmac_f32_e32 v243, v66, v66
	v_fmac_f32_e32 v243, v67, v67
	v_fmac_f32_e32 v243, v68, v68
	v_fmac_f32_e32 v243, v69, v69
	ds_bpermute_b32 v244, v213, v242
	ds_bpermute_b32 v245, v213, v243
	s_waitcnt lgkmcnt(0)
	v_add_f32_e32 v242, v242, v244
	v_add_f32_e32 v243, v243, v245
	v_mov_b32_e32 v244, v242
	v_mov_b32_e32 v245, v243
	s_nop 1
	v_permlane32_swap_b32_e32 v244, v242
	v_permlane32_swap_b32_e32 v245, v243
	v_add_f32_e32 v246, v242, v244
	v_add_f32_e32 v247, v243, v245
	s_and_saveexec_b64 s[16:17], s[42:43]
	global_store_dword v250, v246, s[50:51]
	global_store_dword v250, v247, s[50:51] offset:16
	s_or_b64 exec, exec, s[16:17]
.Lzep_ns3:
	s_add_u32 s68, s68, 0x50000
	s_addc_u32 s69, s69, 0
	s_add_u32 s50, s50, 0x1e00
	s_addc_u32 s51, s51, 0
	v_mul_f32_e32 v62, v62, v198
	v_mul_f32_e32 v63, v63, v198
	v_mul_f32_e32 v64, v64, v198
	v_mul_f32_e32 v65, v65, v198
	v_mul_f32_e32 v58, v58, v198
	v_mul_f32_e32 v59, v59, v198
	v_mul_f32_e32 v60, v60, v198
	v_mul_f32_e32 v61, v61, v198
	v_mul_f32_e32 v54, v54, v198
	v_mul_f32_e32 v55, v55, v198
	v_mul_f32_e32 v56, v56, v198
	v_mul_f32_e32 v57, v57, v198
	v_mul_f32_e32 v50, v50, v198
	v_mul_f32_e32 v51, v51, v198
	v_mul_f32_e32 v52, v52, v198
	v_mul_f32_e32 v53, v53, v198
	v_cvt_pk_bf16_f32 v234, v62, v63
	v_cvt_pk_bf16_f32 v235, v64, v65
	v_cvt_pk_bf16_f32 v236, v58, v59
	v_cvt_pk_bf16_f32 v237, v60, v61
	v_cvt_pk_bf16_f32 v238, v54, v55
	v_cvt_pk_bf16_f32 v239, v56, v57
	v_cvt_pk_bf16_f32 v240, v50, v51
	v_cvt_pk_bf16_f32 v241, v52, v53
	global_store_dwordx4 v211, v[234:237], s[68:69]
	global_store_dwordx4 v211, v[238:241], s[68:69] offset:256
	s_cmp_eq_u32 s23, 0
	s_cbranch_scc1 .Lzep_ns4
	v_mul_f32_e32 v242, v62, v62
	v_mul_f32_e32 v243, v54, v54
	v_fmac_f32_e32 v242, v63, v63
	v_fmac_f32_e32 v242, v64, v64
	v_fmac_f32_e32 v242, v65, v65
	v_fmac_f32_e32 v242, v58, v58
	v_fmac_f32_e32 v242, v59, v59
	v_fmac_f32_e32 v242, v60, v60
	v_fmac_f32_e32 v242, v61, v61
	v_fmac_f32_e32 v243, v55, v55
	v_fmac_f32_e32 v243, v56, v56
	v_fmac_f32_e32 v243, v57, v57
	v_fmac_f32_e32 v243, v50, v50
	v_fmac_f32_e32 v243, v51, v51
	v_fmac_f32_e32 v243, v52, v52
	v_fmac_f32_e32 v243, v53, v53
	ds_bpermute_b32 v244, v213, v242
	ds_bpermute_b32 v245, v213, v243
	s_waitcnt lgkmcnt(0)
	v_add_f32_e32 v242, v242, v244
	v_add_f32_e32 v243, v243, v245
	v_mov_b32_e32 v244, v242
	v_mov_b32_e32 v245, v243
	s_nop 1
	v_permlane32_swap_b32_e32 v244, v242
	v_permlane32_swap_b32_e32 v245, v243
	v_add_f32_e32 v246, v242, v244
	v_add_f32_e32 v247, v243, v245
	s_and_saveexec_b64 s[16:17], s[42:43]
	global_store_dword v250, v246, s[50:51]
	global_store_dword v250, v247, s[50:51] offset:16
	s_or_b64 exec, exec, s[16:17]
.Lzep_ns4:
	s_add_u32 s68, s68, 0x10000
	s_addc_u32 s69, s69, 0
	s_add_u32 s50, s50, 0x600
	s_addc_u32 s51, s51, 0
	v_mul_f32_e32 v46, v46, v199
	v_mul_f32_e32 v47, v47, v199
	v_mul_f32_e32 v48, v48, v199
	v_mul_f32_e32 v49, v49, v199
	v_mul_f32_e32 v42, v42, v199
	v_mul_f32_e32 v43, v43, v199
	v_mul_f32_e32 v44, v44, v199
	v_mul_f32_e32 v45, v45, v199
	v_mul_f32_e32 v38, v38, v199
	v_mul_f32_e32 v39, v39, v199
	v_mul_f32_e32 v40, v40, v199
	v_mul_f32_e32 v41, v41, v199
	v_mul_f32_e32 v34, v34, v199
	v_mul_f32_e32 v35, v35, v199
	v_mul_f32_e32 v36, v36, v199
	v_mul_f32_e32 v37, v37, v199
	v_cvt_pk_bf16_f32 v234, v46, v47
	v_cvt_pk_bf16_f32 v235, v48, v49
	v_cvt_pk_bf16_f32 v236, v42, v43
	v_cvt_pk_bf16_f32 v237, v44, v45
	v_cvt_pk_bf16_f32 v238, v38, v39
	v_cvt_pk_bf16_f32 v239, v40, v41
	v_cvt_pk_bf16_f32 v240, v34, v35
	v_cvt_pk_bf16_f32 v241, v36, v37
	global_store_dwordx4 v211, v[234:237], s[68:69]
	global_store_dwordx4 v211, v[238:241], s[68:69] offset:256
	s_cmp_eq_u32 s23, 0
	s_cbranch_scc1 .Lzep_ns5
	v_mul_f32_e32 v242, v46, v46
	v_mul_f32_e32 v243, v38, v38
	v_fmac_f32_e32 v242, v47, v47
	v_fmac_f32_e32 v242, v48, v48
	v_fmac_f32_e32 v242, v49, v49
	v_fmac_f32_e32 v242, v42, v42
	v_fmac_f32_e32 v242, v43, v43
	v_fmac_f32_e32 v242, v44, v44
	v_fmac_f32_e32 v242, v45, v45
	v_fmac_f32_e32 v243, v39, v39
	v_fmac_f32_e32 v243, v40, v40
	v_fmac_f32_e32 v243, v41, v41
	v_fmac_f32_e32 v243, v34, v34
	v_fmac_f32_e32 v243, v35, v35
	v_fmac_f32_e32 v243, v36, v36
	v_fmac_f32_e32 v243, v37, v37
	ds_bpermute_b32 v244, v213, v242
	ds_bpermute_b32 v245, v213, v243
	s_waitcnt lgkmcnt(0)
	v_add_f32_e32 v242, v242, v244
	v_add_f32_e32 v243, v243, v245
	v_mov_b32_e32 v244, v242
	v_mov_b32_e32 v245, v243
	s_nop 1
	v_permlane32_swap_b32_e32 v244, v242
	v_permlane32_swap_b32_e32 v245, v243
	v_add_f32_e32 v246, v242, v244
	v_add_f32_e32 v247, v243, v245
	s_and_saveexec_b64 s[16:17], s[42:43]
	global_store_dword v250, v246, s[50:51]
	global_store_dword v250, v247, s[50:51] offset:16
	s_or_b64 exec, exec, s[16:17]
; DI float gelu_tanh(float x) { return 0.5f * x * (1.f + tanhf(0.7978845608028654f * (x + 0.044715f * x * x * x))); }
; __device__ __forceinline__ unsigned cvt_pk_bf16(float lo, float hi) { unsigned r; asm volatile("v_cvt_pk_bf16_f32 %0, %1, %2" : "=v"(r) : "v"(lo), "v"(hi)); return r; }
;     DI bf16_t* z() const { return (bf16_t*)(ws + WS_Z); }
;     DI float* b1(int l, int v) const { return (float*)(ws + WS_B1) + (l * 2 + v) * 128; }
;     __device__ __forceinline__ void operator()(const f32x4 (&acc)[2][2][4][2], const Unit& u, int wr, int wc, int fr, int fq) const {
;     ...
;                     f32x4 v0 = acc[ai][bj][m][0] * sc, v1 = acc[ai][bj][m][1] * sc;
;                     if (MODE == EM_GELU) { if (col < nvalid) { const f32x4 b0 = *(const f32x4*)(bias + col), b1 = *(const f32x4*)(bias + col + 4);
; #pragma unroll
;                         for (int i = 0; i < 4; ++i) { v0[i] = ::gelu_tanh(v0[i] + b0[i]); v1[i] = ::gelu_tanh(v1[i] + b1[i]); } } }
;                     if (MODE == EM_RES) { const f32x4* hi = (const f32x4*)(Hin + (size_t)row * 1024 + col); f32x4* hp = (f32x4*)(H + (size_t)row * 1024 + col); v0 += hi[0]; v1 += hi[1]; hp[0] = v0; hp[1] = v1; }
;                     if (STATS) ss[bj] = ((v0[0] * v0[0] + v0[1] * v0[1]) + (v0[2] * v0[2] + v0[3] * v0[3])) + ((v1[0] * v1[0] + v1[1] * v1[1]) + (v1[2] * v1[2] + v1[3] * v1[3]));
;                     if (col < nvalid) { u32x4 w; w.x = cvt_pk_bf16(v0[0], v0[1]); w.y = cvt_pk_bf16(v0[2], v0[3]); w.z = cvt_pk_bf16(v1[0], v1[1]); w.w = cvt_pk_bf16(v1[2], v1[3]);
;                         *(u32x4*)(O + (size_t)row * ldc + col) = w; }
;                 }
;                 if (STATS == 1) { float t = ss[0] + ss[1]; t += __shfl_xor(t, 16); t += __shfl_xor(t, 32); if (fq == 0) ssq_out[(size_t)row * 16 + u.pn * 4 + wc] = t; }
;                 if (STATS == 2) { if (u.pn <= 2) { float t0 = ss[0], t1 = ss[1]; t0 += __shfl_xor(t0, 16); t0 += __shfl_xor(t0, 32); t1 += __shfl_xor(t1, 16); t1 += __shfl_xor(t1, 32);
;                     if (fq == 0) { ssq_out[(size_t)row * 24 + u.pn * 8 + wc] = t0; ssq_out[(size_t)row * 24 + u.pn * 8 + 4 + wc] = t1; } } }
.Lzep_ns5:
	s_add_u32 s68, s68, 0x10000
	s_addc_u32 s69, s69, 0
	s_add_u32 s50, s50, 0x600
	s_addc_u32 s51, s51, 0
	v_mul_f32_e32 v30, v30, v200
	v_mul_f32_e32 v31, v31, v200
	v_mul_f32_e32 v32, v32, v200
	v_mul_f32_e32 v33, v33, v200
	v_mul_f32_e32 v26, v26, v200
	v_mul_f32_e32 v27, v27, v200
	v_mul_f32_e32 v28, v28, v200
	v_mul_f32_e32 v29, v29, v200
	v_mul_f32_e32 v22, v22, v200
	v_mul_f32_e32 v23, v23, v200
	v_mul_f32_e32 v24, v24, v200
	v_mul_f32_e32 v25, v25, v200
	v_mul_f32_e32 v18, v18, v200
	v_mul_f32_e32 v19, v19, v200
	v_mul_f32_e32 v20, v20, v200
	v_mul_f32_e32 v21, v21, v200
	v_cvt_pk_bf16_f32 v234, v30, v31
	v_cvt_pk_bf16_f32 v235, v32, v33
	v_cvt_pk_bf16_f32 v236, v26, v27
	v_cvt_pk_bf16_f32 v237, v28, v29
	v_cvt_pk_bf16_f32 v238, v22, v23
	v_cvt_pk_bf16_f32 v239, v24, v25
	v_cvt_pk_bf16_f32 v240, v18, v19
	v_cvt_pk_bf16_f32 v241, v20, v21
	global_store_dwordx4 v211, v[234:237], s[68:69]
	global_store_dwordx4 v211, v[238:241], s[68:69] offset:256
	s_cmp_eq_u32 s23, 0
	s_cbranch_scc1 .Lzep_ns6
	v_mul_f32_e32 v242, v30, v30
	v_mul_f32_e32 v243, v22, v22
	v_fmac_f32_e32 v242, v31, v31
	v_fmac_f32_e32 v242, v32, v32
	v_fmac_f32_e32 v242, v33, v33
	v_fmac_f32_e32 v242, v26, v26
	v_fmac_f32_e32 v242, v27, v27
	v_fmac_f32_e32 v242, v28, v28
	v_fmac_f32_e32 v242, v29, v29
	v_fmac_f32_e32 v243, v23, v23
	v_fmac_f32_e32 v243, v24, v24
	v_fmac_f32_e32 v243, v25, v25
	v_fmac_f32_e32 v243, v18, v18
	v_fmac_f32_e32 v243, v19, v19
	v_fmac_f32_e32 v243, v20, v20
	v_fmac_f32_e32 v243, v21, v21
	ds_bpermute_b32 v244, v213, v242
	ds_bpermute_b32 v245, v213, v243
	s_waitcnt lgkmcnt(0)
	v_add_f32_e32 v242, v242, v244
	v_add_f32_e32 v243, v243, v245
	v_mov_b32_e32 v244, v242
	v_mov_b32_e32 v245, v243
	s_nop 1
	v_permlane32_swap_b32_e32 v244, v242
	v_permlane32_swap_b32_e32 v245, v243
	v_add_f32_e32 v246, v242, v244
	v_add_f32_e32 v247, v243, v245
	s_and_saveexec_b64 s[16:17], s[42:43]
	global_store_dword v250, v246, s[50:51]
	global_store_dword v250, v247, s[50:51] offset:16
	s_or_b64 exec, exec, s[16:17]
.Lzep_ns6:
	s_add_u32 s68, s68, 0x10000
	s_addc_u32 s69, s69, 0
	s_add_u32 s50, s50, 0x600
	s_addc_u32 s51, s51, 0
	v_mul_f32_e32 v14, v14, v201
	v_mul_f32_e32 v15, v15, v201
	v_mul_f32_e32 v16, v16, v201
	v_mul_f32_e32 v17, v17, v201
	v_mul_f32_e32 v10, v10, v201
	v_mul_f32_e32 v11, v11, v201
	v_mul_f32_e32 v12, v12, v201
	v_mul_f32_e32 v13, v13, v201
	v_mul_f32_e32 v6, v6, v201
	v_mul_f32_e32 v7, v7, v201
	v_mul_f32_e32 v8, v8, v201
	v_mul_f32_e32 v9, v9, v201
	v_mul_f32_e32 v2, v2, v201
	v_mul_f32_e32 v3, v3, v201
	v_mul_f32_e32 v4, v4, v201
	v_mul_f32_e32 v5, v5, v201
	v_cvt_pk_bf16_f32 v234, v14, v15
	v_cvt_pk_bf16_f32 v235, v16, v17
	v_cvt_pk_bf16_f32 v236, v10, v11
	v_cvt_pk_bf16_f32 v237, v12, v13
	v_cvt_pk_bf16_f32 v238, v6, v7
	v_cvt_pk_bf16_f32 v239, v8, v9
	v_cvt_pk_bf16_f32 v240, v2, v3
	v_cvt_pk_bf16_f32 v241, v4, v5
	global_store_dwordx4 v211, v[234:237], s[68:69]
	global_store_dwordx4 v211, v[238:241], s[68:69] offset:256
	s_cmp_eq_u32 s23, 0
	s_cbranch_scc1 .Lzep_ns7
	v_mul_f32_e32 v242, v14, v14
	v_mul_f32_e32 v243, v6, v6
	v_fmac_f32_e32 v242, v15, v15
	v_fmac_f32_e32 v242, v16, v16
	v_fmac_f32_e32 v242, v17, v17
	v_fmac_f32_e32 v242, v10, v10
	v_fmac_f32_e32 v242, v11, v11
	v_fmac_f32_e32 v242, v12, v12
	v_fmac_f32_e32 v242, v13, v13
	v_fmac_f32_e32 v243, v7, v7
	v_fmac_f32_e32 v243, v8, v8
	v_fmac_f32_e32 v243, v9, v9
	v_fmac_f32_e32 v243, v2, v2
	v_fmac_f32_e32 v243, v3, v3
	v_fmac_f32_e32 v243, v4, v4
	v_fmac_f32_e32 v243, v5, v5
	ds_bpermute_b32 v244, v213, v242
	ds_bpermute_b32 v245, v213, v243
	s_waitcnt lgkmcnt(0)
	v_add_f32_e32 v242, v242, v244
	v_add_f32_e32 v243, v243, v245
	v_mov_b32_e32 v244, v242
	v_mov_b32_e32 v245, v243
	s_nop 1
	v_permlane32_swap_b32_e32 v244, v242
	v_permlane32_swap_b32_e32 v245, v243
	v_add_f32_e32 v246, v242, v244
	v_add_f32_e32 v247, v243, v245
	s_and_saveexec_b64 s[16:17], s[42:43]
	global_store_dword v250, v246, s[50:51]
	global_store_dword v250, v247, s[50:51] offset:16
	s_or_b64 exec, exec, s[16:17]
.Lzep_ns7:
	v_readlane_b32 s76, v254, 38
	v_readlane_b32 s77, v254, 39
	v_readlane_b32 s78, v254, 40
	v_readlane_b32 s79, v254, 41
	s_andn2_b64 vcc, exec, s[44:45]
	s_mov_b64 s[8:9], -1
	s_cbranch_vccnz .LBB0_1790
